# epilogue de-serialisation: memory-attention gate loads (32) issued up front with one wait; P3 LoRA epilogues issue all 4 bias loads together (no store drain mid-epilogue)
# speedup vs baseline: 1.0113x; 1.0006x over previous
;     __device__ __forceinline__ void operator()(const f32x4 (&acc)[2][2][4][2], const Unit& u, int wr, int wc, int fr, int fq) const {
;         const int row0 = u.pm * BM + wr * 64 + fr, col0 = u.pn * BM + wc * 32 + 4 * fq;
; #pragma unroll
;         for (int bj = 0; bj < 2; ++bj)
; #pragma unroll
;             for (int n = 0; n < 2; ++n) { const f32x4 bv = *(const f32x4*)(bias + col0 + bj * HALF + n * 16);
; #pragma unroll
;                 for (int ai = 0; ai < 2; ++ai)
; #pragma unroll
;                     for (int m = 0; m < 4; ++m) { f32x4 v = acc[ai][bj][m][n] + bv, o;
; #pragma unroll
;                         for (int e = 0; e < 4; ++e) { const float z = v[e];
;                             const float sg = __builtin_amdgcn_rcpf(1.0f + __builtin_amdgcn_exp2f(-1.4426950408889634f * z));
;                             if (MODE == 0) o[e] = __builtin_amdgcn_exp2f(-0.8750387749f * sg);
;                             else o[e] = sg; }
;                         __builtin_nontemporal_store(o, (f32x4*)(O + (size_t)(row0 + ai * HALF + m * 16) * 1536 + col0 + bj * HALF + n * 16)); } }
.LBB0_378:
	s_load_dwordx16 s[40:55], s[62:63], 0x0
	v_lshl_or_b32 v100, s0, 8, v147
	v_ashrrev_i32_e32 v101, 31, v100
	v_lshlrev_b64 v[142:143], 2, v[100:101]
	v_lshl_add_u32 v153, s1, 8, v146
	s_waitcnt lgkmcnt(0)
	v_lshl_add_u64 v[140:141], s[50:51], 0, v[142:143]
	global_load_dwordx4 v[100:103], v[140:141], off
	global_load_dwordx4 v[212:215], v[140:141], off offset:64
	global_load_dwordx4 v[216:219], v[140:141], off offset:512
	global_load_dwordx4 v[220:223], v[140:141], off offset:576
	v_mov_b64_e32 v[144:145], s[8:9]
	v_mad_i64_i32 v[136:137], s[0:1], v153, s81, v[144:145]
	v_or_b32_e32 v138, 16, v153
	v_mad_i64_i32 v[138:139], s[0:1], v138, s81, v[144:145]
	v_lshl_add_u64 v[136:137], v[136:137], 0, v[142:143]
	v_lshl_add_u64 v[138:139], v[138:139], 0, v[142:143]
	v_or_b32_e32 v154, 32, v153
	s_andn2_b64 vcc, exec, s[22:23]
	s_mov_b64 s[22:23], -1
	s_waitcnt vmcnt(0)
	v_add_f32_e32 v120, v120, v100
	v_add_f32_e32 v121, v121, v101
	v_add_f32_e32 v122, v122, v102
	v_add_f32_e32 v123, v123, v103
	v_add_f32_e32 v124, v124, v100
	v_add_f32_e32 v125, v125, v101
	v_add_f32_e32 v126, v126, v102
	v_add_f32_e32 v127, v127, v103
	v_mul_f32_e32 v120, 0xbfb8aa3b, v120
	v_mul_f32_e32 v121, 0xbfb8aa3b, v121
	v_mul_f32_e32 v122, 0xbfb8aa3b, v122
	v_mul_f32_e32 v123, 0xbfb8aa3b, v123
	v_mul_f32_e32 v124, 0xbfb8aa3b, v124
	v_mul_f32_e32 v125, 0xbfb8aa3b, v125
	v_mul_f32_e32 v126, 0xbfb8aa3b, v126
	v_mul_f32_e32 v127, 0xbfb8aa3b, v127
	v_exp_f32_e32 v120, v120
	v_exp_f32_e32 v121, v121
	v_exp_f32_e32 v122, v122
	v_exp_f32_e32 v123, v123
	v_exp_f32_e32 v124, v124
	v_exp_f32_e32 v125, v125
	v_exp_f32_e32 v126, v126
	v_exp_f32_e32 v127, v127
	v_add_f32_e32 v112, v112, v100
	v_mul_f32_e32 v112, 0xbfb8aa3b, v112
	v_add_f32_e32 v120, 1.0, v120
	v_add_f32_e32 v121, 1.0, v121
	v_add_f32_e32 v122, 1.0, v122
	v_add_f32_e32 v123, 1.0, v123
	v_exp_f32_e32 v112, v112
	v_add_f32_e32 v124, 1.0, v124
	v_add_f32_e32 v125, 1.0, v125
	v_add_f32_e32 v126, 1.0, v126
	v_add_f32_e32 v127, 1.0, v127
	v_rcp_f32_e32 v120, v120
	v_rcp_f32_e32 v121, v121
	v_rcp_f32_e32 v122, v122
	v_rcp_f32_e32 v123, v123
	v_rcp_f32_e32 v124, v124
	v_rcp_f32_e32 v125, v125
	v_rcp_f32_e32 v126, v126
	v_rcp_f32_e32 v127, v127
	v_add_f32_e32 v112, 1.0, v112
	v_add_f32_e32 v113, v113, v101
	v_mul_f32_e32 v120, 0xbf60028b, v120
	v_mul_f32_e32 v121, 0xbf60028b, v121
	v_mul_f32_e32 v122, 0xbf60028b, v122
	v_mul_f32_e32 v123, 0xbf60028b, v123
	v_rcp_f32_e32 v112, v112
	v_mul_f32_e32 v113, 0xbfb8aa3b, v113
	v_mul_f32_e32 v124, 0xbf60028b, v124
	v_mul_f32_e32 v125, 0xbf60028b, v125
	v_mul_f32_e32 v126, 0xbf60028b, v126
	v_mul_f32_e32 v127, 0xbf60028b, v127
	v_exp_f32_e32 v120, v120
	v_exp_f32_e32 v121, v121
	v_exp_f32_e32 v122, v122
	v_exp_f32_e32 v123, v123
	v_exp_f32_e32 v113, v113
	v_exp_f32_e32 v124, v124
	v_exp_f32_e32 v125, v125
	v_exp_f32_e32 v126, v126
	v_exp_f32_e32 v127, v127
	v_mul_f32_e32 v112, 0xbf60028b, v112
	flat_store_dwordx4 v[136:137], v[120:123] nt
	flat_store_dwordx4 v[138:139], v[124:127] nt
	s_nop 0
	v_exp_f32_e32 v122, v112
	v_add_f32_e32 v112, 1.0, v113
	v_add_f32_e32 v113, v114, v102
	v_mul_f32_e32 v113, 0xbfb8aa3b, v113
	v_exp_f32_e32 v113, v113
	v_add_f32_e32 v114, v115, v103
	v_mul_f32_e32 v114, 0xbfb8aa3b, v114
	v_exp_f32_e32 v114, v114
	v_rcp_f32_e32 v112, v112
	v_add_f32_e32 v113, 1.0, v113
	v_rcp_f32_e32 v113, v113
	v_add_f32_e32 v114, 1.0, v114
	v_mul_f32_e32 v112, 0xbf60028b, v112
	v_rcp_f32_e32 v114, v114
	v_exp_f32_e32 v123, v112
	v_mul_f32_e32 v112, 0xbf60028b, v113
	v_add_f32_e32 v113, v116, v100
	v_mul_f32_e32 v113, 0xbfb8aa3b, v113
	v_exp_f32_e32 v116, v113
	v_exp_f32_e32 v124, v112
	v_mul_f32_e32 v112, 0xbf60028b, v114
	v_exp_f32_e32 v125, v112
	v_or_b32_e32 v112, 48, v153
	v_mad_i64_i32 v[112:113], s[0:1], v112, s81, v[144:145]
	v_lshl_add_u64 v[114:115], v[112:113], 0, v[142:143]
	v_add_f32_e32 v112, 1.0, v116
	v_add_f32_e32 v113, v117, v101
	v_rcp_f32_e32 v112, v112
	v_mul_f32_e32 v113, 0xbfb8aa3b, v113
	v_exp_f32_e32 v113, v113
	v_add_f32_e32 v117, v119, v103
	v_mul_f32_e32 v112, 0xbf60028b, v112
	v_exp_f32_e32 v116, v112
	v_add_f32_e32 v112, 1.0, v113
	v_add_f32_e32 v113, v118, v102
	v_mul_f32_e32 v113, 0xbfb8aa3b, v113
	v_exp_f32_e32 v113, v113
	v_mul_f32_e32 v117, 0xbfb8aa3b, v117
	v_exp_f32_e32 v117, v117
	v_add_f32_e32 v108, v108, v100
	v_rcp_f32_e32 v112, v112
	v_add_f32_e32 v113, 1.0, v113
	v_mul_f32_e32 v108, 0xbfb8aa3b, v108
	v_rcp_f32_e32 v113, v113
	v_add_f32_e32 v117, 1.0, v117
	v_exp_f32_e32 v108, v108
	v_rcp_f32_e32 v119, v117
	v_mul_f32_e32 v112, 0xbf60028b, v112
	v_exp_f32_e32 v117, v112
	v_mul_f32_e32 v112, 0xbf60028b, v113
	v_add_f32_e32 v108, 1.0, v108
	v_add_f32_e32 v109, v109, v101
	v_exp_f32_e32 v118, v112
	v_mul_f32_e32 v112, 0xbf60028b, v119
	v_rcp_f32_e32 v108, v108
	v_mul_f32_e32 v109, 0xbfb8aa3b, v109
	v_exp_f32_e32 v119, v112
	v_exp_f32_e32 v109, v109
	flat_store_dwordx4 v[114:115], v[122:125] nt
	v_mul_f32_e32 v108, 0xbf60028b, v108
	v_add_f32_e32 v104, v104, v100
	v_add_u32_e32 v122, 0x80, v153
	v_mad_i64_i32 v[112:113], s[0:1], v122, s81, v[144:145]
	v_lshl_add_u64 v[112:113], v[112:113], 0, v[142:143]
	flat_store_dwordx4 v[112:113], v[116:119] nt
	v_mul_f32_e32 v104, 0xbfb8aa3b, v104
	v_exp_f32_e32 v104, v104
	v_exp_f32_e32 v116, v108
	v_add_f32_e32 v108, 1.0, v109
	v_add_f32_e32 v109, v110, v102
	v_mul_f32_e32 v109, 0xbfb8aa3b, v109
	v_add_f32_e32 v110, v111, v103
	v_exp_f32_e32 v109, v109
	v_mul_f32_e32 v110, 0xbfb8aa3b, v110
	v_exp_f32_e32 v110, v110
	v_rcp_f32_e32 v108, v108
	v_add_f32_e32 v109, 1.0, v109
	v_rcp_f32_e32 v109, v109
	v_add_f32_e32 v110, 1.0, v110
	v_rcp_f32_e32 v110, v110
	v_mul_f32_e32 v108, 0xbf60028b, v108
;     __device__ __forceinline__ void operator()(const f32x4 (&acc)[2][2][4][2], const Unit& u, int wr, int wc, int fr, int fq) const {
;     ...
;             for (int n = 0; n < 2; ++n) { const f32x4 bv = *(const f32x4*)(bias + col0 + bj * HALF + n * 16);
; #pragma unroll
;                 for (int ai = 0; ai < 2; ++ai)
; #pragma unroll
;                     for (int m = 0; m < 4; ++m) { f32x4 v = acc[ai][bj][m][n] + bv, o;
; #pragma unroll
;                         for (int e = 0; e < 4; ++e) { const float z = v[e];
;                             const float sg = __builtin_amdgcn_rcpf(1.0f + __builtin_amdgcn_exp2f(-1.4426950408889634f * z));
;                             if (MODE == 0) o[e] = __builtin_amdgcn_exp2f(-0.8750387749f * sg);
;                             else o[e] = sg; }
;                         __builtin_nontemporal_store(o, (f32x4*)(O + (size_t)(row0 + ai * HALF + m * 16) * 1536 + col0 + bj * HALF + n * 16)); } }
	v_exp_f32_e32 v117, v108
	v_mul_f32_e32 v108, 0xbf60028b, v109
	v_add_f32_e32 v104, 1.0, v104
	v_add_f32_e32 v105, v105, v101
	v_exp_f32_e32 v118, v108
	v_mul_f32_e32 v108, 0xbf60028b, v110
	v_rcp_f32_e32 v104, v104
	v_mul_f32_e32 v105, 0xbfb8aa3b, v105
	v_exp_f32_e32 v119, v108
	v_exp_f32_e32 v105, v105
	v_add_u32_e32 v108, 0x90, v153
	v_mad_i64_i32 v[108:109], s[0:1], v108, s81, v[144:145]
	v_lshl_add_u64 v[108:109], v[108:109], 0, v[142:143]
	v_mul_f32_e32 v104, 0xbf60028b, v104
	flat_store_dwordx4 v[108:109], v[116:119] nt
	v_add_f32_e32 v128, v128, v100
	v_add_f32_e32 v129, v129, v101
	v_exp_f32_e32 v116, v104
	v_add_f32_e32 v104, 1.0, v105
	v_add_f32_e32 v105, v106, v102
	v_add_f32_e32 v130, v130, v102
	v_add_f32_e32 v131, v131, v103
	v_mul_f32_e32 v105, 0xbfb8aa3b, v105
	v_add_f32_e32 v106, v107, v103
	v_add_f32_e32 v96, v96, v100
	v_add_f32_e32 v97, v97, v101
	v_add_f32_e32 v98, v98, v102
	v_add_f32_e32 v99, v99, v103
	v_mul_f32_e32 v128, 0xbfb8aa3b, v128
	v_mul_f32_e32 v129, 0xbfb8aa3b, v129
	v_mul_f32_e32 v130, 0xbfb8aa3b, v130
	v_mul_f32_e32 v131, 0xbfb8aa3b, v131
	v_exp_f32_e32 v105, v105
	v_mul_f32_e32 v106, 0xbfb8aa3b, v106
	v_mul_f32_e32 v96, 0xbfb8aa3b, v96
	v_mul_f32_e32 v97, 0xbfb8aa3b, v97
	v_mul_f32_e32 v98, 0xbfb8aa3b, v98
	v_mul_f32_e32 v99, 0xbfb8aa3b, v99
	v_exp_f32_e32 v128, v128
	v_exp_f32_e32 v129, v129
	v_exp_f32_e32 v130, v130
	v_exp_f32_e32 v131, v131
	v_exp_f32_e32 v106, v106
	v_exp_f32_e32 v96, v96
	v_exp_f32_e32 v97, v97
	v_exp_f32_e32 v98, v98
	v_exp_f32_e32 v99, v99
	v_rcp_f32_e32 v104, v104
	v_add_f32_e32 v105, 1.0, v105
	v_add_f32_e32 v128, 1.0, v128
	v_add_f32_e32 v129, 1.0, v129
	v_add_f32_e32 v130, 1.0, v130
	v_add_f32_e32 v131, 1.0, v131
	v_rcp_f32_e32 v105, v105
	v_add_f32_e32 v106, 1.0, v106
	v_add_f32_e32 v96, 1.0, v96
	v_add_f32_e32 v97, 1.0, v97
	v_add_f32_e32 v98, 1.0, v98
	v_add_f32_e32 v99, 1.0, v99
	v_rcp_f32_e32 v128, v128
	v_rcp_f32_e32 v129, v129
	v_rcp_f32_e32 v130, v130
	v_rcp_f32_e32 v131, v131
	v_rcp_f32_e32 v106, v106
	v_rcp_f32_e32 v96, v96
	v_rcp_f32_e32 v97, v97
	v_rcp_f32_e32 v98, v98
	v_rcp_f32_e32 v99, v99
	v_mul_f32_e32 v104, 0xbf60028b, v104
	v_exp_f32_e32 v117, v104
	v_mul_f32_e32 v104, 0xbf60028b, v105
	v_mul_f32_e32 v128, 0xbf60028b, v128
	v_mul_f32_e32 v129, 0xbf60028b, v129
	v_mul_f32_e32 v130, 0xbf60028b, v130
	v_mul_f32_e32 v131, 0xbf60028b, v131
	v_exp_f32_e32 v118, v104
	v_mul_f32_e32 v104, 0xbf60028b, v106
	v_mul_f32_e32 v96, 0xbf60028b, v96
	v_mul_f32_e32 v97, 0xbf60028b, v97
	v_mul_f32_e32 v98, 0xbf60028b, v98
	v_mul_f32_e32 v99, 0xbf60028b, v99
	v_exp_f32_e32 v128, v128
	v_exp_f32_e32 v129, v129
	v_exp_f32_e32 v130, v130
	v_exp_f32_e32 v131, v131
	v_exp_f32_e32 v119, v104
	v_exp_f32_e32 v96, v96
	v_exp_f32_e32 v97, v97
	v_exp_f32_e32 v98, v98
	v_exp_f32_e32 v99, v99
	v_add_u32_e32 v104, 0xa0, v153
	v_add_u32_e32 v100, 0xb0, v153
	v_mad_i64_i32 v[120:121], s[0:1], v154, s81, v[144:145]
	v_mad_i64_i32 v[104:105], s[0:1], v104, s81, v[144:145]
	v_mad_i64_i32 v[100:101], s[0:1], v100, s81, v[144:145]
	v_lshl_add_u64 v[120:121], v[120:121], 0, v[142:143]
	v_lshl_add_u64 v[104:105], v[104:105], 0, v[142:143]
	v_lshl_add_u64 v[100:101], v[100:101], 0, v[142:143]
	flat_store_dwordx4 v[120:121], v[128:131] nt
	flat_store_dwordx4 v[104:105], v[116:119] nt
	flat_store_dwordx4 v[100:101], v[96:99] nt
	s_nop 3
	v_mov_b64_e32 v[96:97], v[212:213]
	v_mov_b64_e32 v[98:99], v[214:215]
	v_add_f32_e32 v92, v92, v96
	v_add_f32_e32 v93, v93, v97
	v_add_f32_e32 v94, v94, v98
	v_add_f32_e32 v95, v95, v99
	v_add_f32_e32 v76, v76, v96
	v_add_f32_e32 v77, v77, v97
	v_add_f32_e32 v78, v78, v98
	v_add_f32_e32 v79, v79, v99
	v_mul_f32_e32 v92, 0xbfb8aa3b, v92
	v_mul_f32_e32 v93, 0xbfb8aa3b, v93
	v_mul_f32_e32 v94, 0xbfb8aa3b, v94
	v_mul_f32_e32 v95, 0xbfb8aa3b, v95
	v_add_f32_e32 v88, v88, v96
	v_add_f32_e32 v89, v89, v97
	v_add_f32_e32 v90, v90, v98
	v_add_f32_e32 v91, v91, v99
	v_mul_f32_e32 v76, 0xbfb8aa3b, v76
	v_mul_f32_e32 v77, 0xbfb8aa3b, v77
	v_mul_f32_e32 v78, 0xbfb8aa3b, v78
	v_mul_f32_e32 v79, 0xbfb8aa3b, v79
	v_exp_f32_e32 v92, v92
	v_exp_f32_e32 v93, v93
	v_exp_f32_e32 v94, v94
	v_exp_f32_e32 v95, v95
	v_mul_f32_e32 v88, 0xbfb8aa3b, v88
	v_mul_f32_e32 v89, 0xbfb8aa3b, v89
	v_mul_f32_e32 v90, 0xbfb8aa3b, v90
	v_mul_f32_e32 v91, 0xbfb8aa3b, v91
	v_add_f32_e32 v84, v84, v96
	v_add_f32_e32 v85, v85, v97
	v_add_f32_e32 v86, v86, v98
	v_add_f32_e32 v87, v87, v99
	v_exp_f32_e32 v76, v76
	v_exp_f32_e32 v77, v77
	v_exp_f32_e32 v78, v78
	v_exp_f32_e32 v79, v79
	v_exp_f32_e32 v88, v88
	v_exp_f32_e32 v89, v89
	v_exp_f32_e32 v90, v90
	v_exp_f32_e32 v91, v91
	v_mul_f32_e32 v84, 0xbfb8aa3b, v84
	v_mul_f32_e32 v85, 0xbfb8aa3b, v85
	v_mul_f32_e32 v86, 0xbfb8aa3b, v86
	v_mul_f32_e32 v87, 0xbfb8aa3b, v87
	v_exp_f32_e32 v84, v84
	v_exp_f32_e32 v85, v85
	v_exp_f32_e32 v86, v86
	v_exp_f32_e32 v87, v87
	v_add_f32_e32 v92, 1.0, v92
	v_add_f32_e32 v93, 1.0, v93
	v_add_f32_e32 v94, 1.0, v94
	v_add_f32_e32 v95, 1.0, v95
	v_add_f32_e32 v76, 1.0, v76
	v_add_f32_e32 v77, 1.0, v77
	v_add_f32_e32 v78, 1.0, v78
	v_add_f32_e32 v79, 1.0, v79
	v_rcp_f32_e32 v92, v92
	v_rcp_f32_e32 v93, v93
	v_rcp_f32_e32 v94, v94
	v_rcp_f32_e32 v95, v95
	v_add_f32_e32 v88, 1.0, v88
	v_add_f32_e32 v89, 1.0, v89
	v_add_f32_e32 v90, 1.0, v90
	v_add_f32_e32 v91, 1.0, v91
	v_rcp_f32_e32 v76, v76
	v_rcp_f32_e32 v77, v77
	v_rcp_f32_e32 v78, v78
	v_rcp_f32_e32 v79, v79
	v_rcp_f32_e32 v88, v88
	v_rcp_f32_e32 v89, v89
	v_rcp_f32_e32 v90, v90
	v_rcp_f32_e32 v91, v91
	v_add_f32_e32 v84, 1.0, v84
	v_add_f32_e32 v85, 1.0, v85
	v_add_f32_e32 v86, 1.0, v86
	v_add_f32_e32 v87, 1.0, v87
	v_rcp_f32_e32 v84, v84
	v_rcp_f32_e32 v85, v85
;     __device__ __forceinline__ void operator()(const f32x4 (&acc)[2][2][4][2], const Unit& u, int wr, int wc, int fr, int fq) const {
;     ...
;             for (int n = 0; n < 2; ++n) { const f32x4 bv = *(const f32x4*)(bias + col0 + bj * HALF + n * 16);
; #pragma unroll
;                 for (int ai = 0; ai < 2; ++ai)
; #pragma unroll
;                     for (int m = 0; m < 4; ++m) { f32x4 v = acc[ai][bj][m][n] + bv, o;
; #pragma unroll
;                         for (int e = 0; e < 4; ++e) { const float z = v[e];
;                             const float sg = __builtin_amdgcn_rcpf(1.0f + __builtin_amdgcn_exp2f(-1.4426950408889634f * z));
;                             if (MODE == 0) o[e] = __builtin_amdgcn_exp2f(-0.8750387749f * sg);
;                             else o[e] = sg; }
;                         __builtin_nontemporal_store(o, (f32x4*)(O + (size_t)(row0 + ai * HALF + m * 16) * 1536 + col0 + bj * HALF + n * 16)); } }
	v_rcp_f32_e32 v86, v86
	v_rcp_f32_e32 v87, v87
	v_mul_f32_e32 v92, 0xbf60028b, v92
	v_mul_f32_e32 v93, 0xbf60028b, v93
	v_mul_f32_e32 v94, 0xbf60028b, v94
	v_mul_f32_e32 v95, 0xbf60028b, v95
	v_mul_f32_e32 v76, 0xbf60028b, v76
	v_mul_f32_e32 v77, 0xbf60028b, v77
	v_mul_f32_e32 v78, 0xbf60028b, v78
	v_mul_f32_e32 v79, 0xbf60028b, v79
	v_exp_f32_e32 v92, v92
	v_exp_f32_e32 v93, v93
	v_exp_f32_e32 v94, v94
	v_exp_f32_e32 v95, v95
	v_mul_f32_e32 v88, 0xbf60028b, v88
	v_mul_f32_e32 v89, 0xbf60028b, v89
	v_mul_f32_e32 v90, 0xbf60028b, v90
	v_mul_f32_e32 v91, 0xbf60028b, v91
	v_exp_f32_e32 v76, v76
	v_exp_f32_e32 v77, v77
	v_exp_f32_e32 v78, v78
	v_exp_f32_e32 v79, v79
	v_exp_f32_e32 v88, v88
	v_exp_f32_e32 v89, v89
	v_exp_f32_e32 v90, v90
	v_exp_f32_e32 v91, v91
	v_mul_f32_e32 v84, 0xbf60028b, v84
	v_mul_f32_e32 v85, 0xbf60028b, v85
	v_mul_f32_e32 v86, 0xbf60028b, v86
	v_mul_f32_e32 v87, 0xbf60028b, v87
	v_exp_f32_e32 v84, v84
	v_exp_f32_e32 v85, v85
	v_exp_f32_e32 v86, v86
	v_exp_f32_e32 v87, v87
	flat_store_dwordx4 v[136:137], v[92:95] offset:64 nt
	flat_store_dwordx4 v[138:139], v[88:91] offset:64 nt
	flat_store_dwordx4 v[120:121], v[84:87] offset:64 nt
	v_add_f32_e32 v80, v80, v96
	v_add_f32_e32 v81, v81, v97
	flat_store_dwordx4 v[114:115], v[76:79] offset:64 nt
	v_mul_f32_e32 v80, 0xbfb8aa3b, v80
	v_mul_f32_e32 v81, 0xbfb8aa3b, v81
	v_add_f32_e32 v78, v82, v98
	v_add_f32_e32 v79, v83, v99
	v_mul_f32_e32 v78, 0xbfb8aa3b, v78
	v_mul_f32_e32 v79, 0xbfb8aa3b, v79
	v_add_f32_e32 v72, v72, v96
	v_add_f32_e32 v73, v73, v97
	v_add_f32_e32 v74, v74, v98
	v_add_f32_e32 v75, v75, v99
	v_exp_f32_e32 v80, v80
	v_exp_f32_e32 v81, v81
	v_exp_f32_e32 v78, v78
	v_exp_f32_e32 v79, v79
	v_mul_f32_e32 v72, 0xbfb8aa3b, v72
	v_mul_f32_e32 v73, 0xbfb8aa3b, v73
	v_mul_f32_e32 v74, 0xbfb8aa3b, v74
	v_mul_f32_e32 v75, 0xbfb8aa3b, v75
	v_add_f32_e32 v68, v68, v96
	v_add_f32_e32 v69, v69, v97
	v_add_f32_e32 v70, v70, v98
	v_add_f32_e32 v71, v71, v99
	v_exp_f32_e32 v72, v72
	v_exp_f32_e32 v73, v73
	v_exp_f32_e32 v74, v74
	v_exp_f32_e32 v75, v75
	v_mul_f32_e32 v68, 0xbfb8aa3b, v68
	v_mul_f32_e32 v69, 0xbfb8aa3b, v69
	v_mul_f32_e32 v70, 0xbfb8aa3b, v70
	v_mul_f32_e32 v71, 0xbfb8aa3b, v71
	v_add_f32_e32 v64, v64, v96
	v_add_f32_e32 v65, v65, v97
	v_add_f32_e32 v66, v66, v98
	v_add_f32_e32 v67, v67, v99
	v_exp_f32_e32 v68, v68
	v_exp_f32_e32 v69, v69
	v_exp_f32_e32 v70, v70
	v_exp_f32_e32 v71, v71
	v_mul_f32_e32 v64, 0xbfb8aa3b, v64
	v_mul_f32_e32 v65, 0xbfb8aa3b, v65
	v_mul_f32_e32 v66, 0xbfb8aa3b, v66
	v_mul_f32_e32 v67, 0xbfb8aa3b, v67
	v_exp_f32_e32 v64, v64
	v_exp_f32_e32 v65, v65
	v_exp_f32_e32 v66, v66
	v_exp_f32_e32 v67, v67
	v_add_f32_e32 v80, 1.0, v80
	v_add_f32_e32 v77, 1.0, v81
	v_add_f32_e32 v78, 1.0, v78
	v_add_f32_e32 v79, 1.0, v79
	v_rcp_f32_e32 v80, v80
	v_rcp_f32_e32 v77, v77
	v_rcp_f32_e32 v78, v78
	v_rcp_f32_e32 v79, v79
	v_add_f32_e32 v72, 1.0, v72
	v_add_f32_e32 v73, 1.0, v73
	v_add_f32_e32 v74, 1.0, v74
	v_add_f32_e32 v75, 1.0, v75
	v_rcp_f32_e32 v72, v72
	v_rcp_f32_e32 v73, v73
	v_rcp_f32_e32 v74, v74
	v_rcp_f32_e32 v75, v75
	v_add_f32_e32 v68, 1.0, v68
	v_add_f32_e32 v69, 1.0, v69
	v_add_f32_e32 v70, 1.0, v70
	v_add_f32_e32 v71, 1.0, v71
	v_rcp_f32_e32 v68, v68
	v_rcp_f32_e32 v69, v69
	v_rcp_f32_e32 v70, v70
	v_rcp_f32_e32 v71, v71
	v_add_f32_e32 v64, 1.0, v64
	v_add_f32_e32 v65, 1.0, v65
	v_add_f32_e32 v66, 1.0, v66
	v_add_f32_e32 v67, 1.0, v67
	v_rcp_f32_e32 v64, v64
	v_rcp_f32_e32 v65, v65
	v_rcp_f32_e32 v66, v66
	v_rcp_f32_e32 v67, v67
	v_mul_f32_e32 v76, 0xbf60028b, v80
	v_mul_f32_e32 v77, 0xbf60028b, v77
	v_mul_f32_e32 v78, 0xbf60028b, v78
	v_mul_f32_e32 v79, 0xbf60028b, v79
	v_exp_f32_e32 v76, v76
	v_exp_f32_e32 v77, v77
	v_exp_f32_e32 v78, v78
	v_exp_f32_e32 v79, v79
	v_mul_f32_e32 v72, 0xbf60028b, v72
	v_mul_f32_e32 v73, 0xbf60028b, v73
	v_mul_f32_e32 v74, 0xbf60028b, v74
	v_mul_f32_e32 v75, 0xbf60028b, v75
	v_exp_f32_e32 v72, v72
	v_exp_f32_e32 v73, v73
	v_exp_f32_e32 v74, v74
	v_exp_f32_e32 v75, v75
	v_mul_f32_e32 v68, 0xbf60028b, v68
	v_mul_f32_e32 v69, 0xbf60028b, v69
	v_mul_f32_e32 v70, 0xbf60028b, v70
	v_mul_f32_e32 v71, 0xbf60028b, v71
	v_exp_f32_e32 v68, v68
	v_exp_f32_e32 v69, v69
	v_exp_f32_e32 v70, v70
	v_exp_f32_e32 v71, v71
	v_mul_f32_e32 v64, 0xbf60028b, v64
	v_mul_f32_e32 v65, 0xbf60028b, v65
	v_mul_f32_e32 v66, 0xbf60028b, v66
	v_mul_f32_e32 v67, 0xbf60028b, v67
	v_exp_f32_e32 v64, v64
	v_exp_f32_e32 v65, v65
	v_exp_f32_e32 v66, v66
	v_exp_f32_e32 v67, v67
	flat_store_dwordx4 v[112:113], v[76:79] offset:64 nt
	flat_store_dwordx4 v[108:109], v[72:75] offset:64 nt
	flat_store_dwordx4 v[104:105], v[68:71] offset:64 nt
	flat_store_dwordx4 v[100:101], v[64:67] offset:64 nt
	s_nop 3
	v_mov_b64_e32 v[64:65], v[216:217]
	v_mov_b64_e32 v[66:67], v[218:219]
	v_add_f32_e32 v60, v60, v64
	v_add_f32_e32 v61, v61, v65
	v_add_f32_e32 v62, v62, v66
	v_add_f32_e32 v63, v63, v67
	v_add_f32_e32 v44, v44, v64
	v_add_f32_e32 v45, v45, v65
	v_add_f32_e32 v46, v46, v66
	v_add_f32_e32 v47, v47, v67
	v_mul_f32_e32 v60, 0xbfb8aa3b, v60
	v_mul_f32_e32 v61, 0xbfb8aa3b, v61
	v_mul_f32_e32 v62, 0xbfb8aa3b, v62
	v_mul_f32_e32 v63, 0xbfb8aa3b, v63
	v_add_f32_e32 v56, v56, v64
	v_add_f32_e32 v57, v57, v65
	v_add_f32_e32 v58, v58, v66
	v_add_f32_e32 v59, v59, v67
	v_mul_f32_e32 v44, 0xbfb8aa3b, v44
	v_mul_f32_e32 v45, 0xbfb8aa3b, v45
	v_mul_f32_e32 v46, 0xbfb8aa3b, v46
	v_mul_f32_e32 v47, 0xbfb8aa3b, v47
	v_exp_f32_e32 v60, v60
	v_exp_f32_e32 v61, v61
	v_exp_f32_e32 v62, v62
	v_exp_f32_e32 v63, v63
	v_mul_f32_e32 v56, 0xbfb8aa3b, v56
	v_mul_f32_e32 v57, 0xbfb8aa3b, v57
	v_mul_f32_e32 v58, 0xbfb8aa3b, v58
	v_mul_f32_e32 v59, 0xbfb8aa3b, v59
;     __device__ __forceinline__ void operator()(const f32x4 (&acc)[2][2][4][2], const Unit& u, int wr, int wc, int fr, int fq) const {
;     ...
;             for (int n = 0; n < 2; ++n) { const f32x4 bv = *(const f32x4*)(bias + col0 + bj * HALF + n * 16);
; #pragma unroll
;                 for (int ai = 0; ai < 2; ++ai)
; #pragma unroll
;                     for (int m = 0; m < 4; ++m) { f32x4 v = acc[ai][bj][m][n] + bv, o;
; #pragma unroll
;                         for (int e = 0; e < 4; ++e) { const float z = v[e];
;                             const float sg = __builtin_amdgcn_rcpf(1.0f + __builtin_amdgcn_exp2f(-1.4426950408889634f * z));
;                             if (MODE == 0) o[e] = __builtin_amdgcn_exp2f(-0.8750387749f * sg);
;                             else o[e] = sg; }
;                         __builtin_nontemporal_store(o, (f32x4*)(O + (size_t)(row0 + ai * HALF + m * 16) * 1536 + col0 + bj * HALF + n * 16)); } }
	v_add_f32_e32 v52, v52, v64
	v_add_f32_e32 v53, v53, v65
	v_add_f32_e32 v54, v54, v66
	v_add_f32_e32 v55, v55, v67
	v_exp_f32_e32 v44, v44
	v_exp_f32_e32 v45, v45
	v_exp_f32_e32 v46, v46
	v_exp_f32_e32 v47, v47
	v_exp_f32_e32 v56, v56
	v_exp_f32_e32 v57, v57
	v_exp_f32_e32 v58, v58
	v_exp_f32_e32 v59, v59
	v_mul_f32_e32 v52, 0xbfb8aa3b, v52
	v_mul_f32_e32 v53, 0xbfb8aa3b, v53
	v_mul_f32_e32 v54, 0xbfb8aa3b, v54
	v_mul_f32_e32 v55, 0xbfb8aa3b, v55
	v_exp_f32_e32 v52, v52
	v_exp_f32_e32 v53, v53
	v_exp_f32_e32 v54, v54
	v_exp_f32_e32 v55, v55
	v_add_f32_e32 v60, 1.0, v60
	v_add_f32_e32 v61, 1.0, v61
	v_add_f32_e32 v62, 1.0, v62
	v_add_f32_e32 v63, 1.0, v63
	v_add_f32_e32 v44, 1.0, v44
	v_add_f32_e32 v45, 1.0, v45
	v_add_f32_e32 v46, 1.0, v46
	v_add_f32_e32 v47, 1.0, v47
	v_rcp_f32_e32 v60, v60
	v_rcp_f32_e32 v61, v61
	v_rcp_f32_e32 v62, v62
	v_rcp_f32_e32 v63, v63
	v_add_f32_e32 v56, 1.0, v56
	v_add_f32_e32 v57, 1.0, v57
	v_add_f32_e32 v58, 1.0, v58
	v_add_f32_e32 v59, 1.0, v59
	v_rcp_f32_e32 v44, v44
	v_rcp_f32_e32 v45, v45
	v_rcp_f32_e32 v46, v46
	v_rcp_f32_e32 v47, v47
	v_rcp_f32_e32 v56, v56
	v_rcp_f32_e32 v57, v57
	v_rcp_f32_e32 v58, v58
	v_rcp_f32_e32 v59, v59
	v_add_f32_e32 v52, 1.0, v52
	v_add_f32_e32 v53, 1.0, v53
	v_add_f32_e32 v54, 1.0, v54
	v_add_f32_e32 v55, 1.0, v55
	v_rcp_f32_e32 v52, v52
	v_rcp_f32_e32 v53, v53
	v_rcp_f32_e32 v54, v54
	v_rcp_f32_e32 v55, v55
	v_mul_f32_e32 v60, 0xbf60028b, v60
	v_mul_f32_e32 v61, 0xbf60028b, v61
	v_mul_f32_e32 v62, 0xbf60028b, v62
	v_mul_f32_e32 v63, 0xbf60028b, v63
	v_mul_f32_e32 v44, 0xbf60028b, v44
	v_mul_f32_e32 v45, 0xbf60028b, v45
	v_mul_f32_e32 v46, 0xbf60028b, v46
	v_mul_f32_e32 v47, 0xbf60028b, v47
	v_exp_f32_e32 v60, v60
	v_exp_f32_e32 v61, v61
	v_exp_f32_e32 v62, v62
	v_exp_f32_e32 v63, v63
	v_mul_f32_e32 v56, 0xbf60028b, v56
	v_mul_f32_e32 v57, 0xbf60028b, v57
	v_mul_f32_e32 v58, 0xbf60028b, v58
	v_mul_f32_e32 v59, 0xbf60028b, v59
	v_exp_f32_e32 v44, v44
	v_exp_f32_e32 v45, v45
	v_exp_f32_e32 v46, v46
	v_exp_f32_e32 v47, v47
	v_exp_f32_e32 v56, v56
	v_exp_f32_e32 v57, v57
	v_exp_f32_e32 v58, v58
	v_exp_f32_e32 v59, v59
	v_mul_f32_e32 v52, 0xbf60028b, v52
	v_mul_f32_e32 v53, 0xbf60028b, v53
	v_mul_f32_e32 v54, 0xbf60028b, v54
	v_mul_f32_e32 v55, 0xbf60028b, v55
	v_exp_f32_e32 v52, v52
	v_exp_f32_e32 v53, v53
	v_exp_f32_e32 v54, v54
	v_exp_f32_e32 v55, v55
	flat_store_dwordx4 v[136:137], v[60:63] offset:512 nt
	flat_store_dwordx4 v[138:139], v[56:59] offset:512 nt
	flat_store_dwordx4 v[120:121], v[52:55] offset:512 nt
	v_add_f32_e32 v48, v48, v64
	v_add_f32_e32 v49, v49, v65
	flat_store_dwordx4 v[114:115], v[44:47] offset:512 nt
	v_mul_f32_e32 v48, 0xbfb8aa3b, v48
	v_mul_f32_e32 v49, 0xbfb8aa3b, v49
	v_add_f32_e32 v46, v50, v66
	v_add_f32_e32 v47, v51, v67
	v_mul_f32_e32 v46, 0xbfb8aa3b, v46
	v_mul_f32_e32 v47, 0xbfb8aa3b, v47
	v_add_f32_e32 v40, v40, v64
	v_add_f32_e32 v41, v41, v65
	v_add_f32_e32 v42, v42, v66
	v_add_f32_e32 v43, v43, v67
	v_exp_f32_e32 v48, v48
	v_exp_f32_e32 v49, v49
	v_exp_f32_e32 v46, v46
	v_exp_f32_e32 v47, v47
	v_mul_f32_e32 v40, 0xbfb8aa3b, v40
	v_mul_f32_e32 v41, 0xbfb8aa3b, v41
	v_mul_f32_e32 v42, 0xbfb8aa3b, v42
	v_mul_f32_e32 v43, 0xbfb8aa3b, v43
	v_add_f32_e32 v36, v36, v64
	v_add_f32_e32 v37, v37, v65
	v_add_f32_e32 v38, v38, v66
	v_add_f32_e32 v39, v39, v67
	v_exp_f32_e32 v40, v40
	v_exp_f32_e32 v41, v41
	v_exp_f32_e32 v42, v42
	v_exp_f32_e32 v43, v43
	v_mul_f32_e32 v36, 0xbfb8aa3b, v36
	v_mul_f32_e32 v37, 0xbfb8aa3b, v37
	v_mul_f32_e32 v38, 0xbfb8aa3b, v38
	v_mul_f32_e32 v39, 0xbfb8aa3b, v39
	v_add_f32_e32 v32, v32, v64
	v_add_f32_e32 v33, v33, v65
	v_add_f32_e32 v34, v34, v66
	v_add_f32_e32 v35, v35, v67
	v_exp_f32_e32 v36, v36
	v_exp_f32_e32 v37, v37
	v_exp_f32_e32 v38, v38
	v_exp_f32_e32 v39, v39
	v_mul_f32_e32 v32, 0xbfb8aa3b, v32
	v_mul_f32_e32 v33, 0xbfb8aa3b, v33
	v_mul_f32_e32 v34, 0xbfb8aa3b, v34
	v_mul_f32_e32 v35, 0xbfb8aa3b, v35
	v_exp_f32_e32 v32, v32
	v_exp_f32_e32 v33, v33
	v_exp_f32_e32 v34, v34
	v_exp_f32_e32 v35, v35
	v_add_f32_e32 v48, 1.0, v48
	v_add_f32_e32 v45, 1.0, v49
	v_add_f32_e32 v46, 1.0, v46
	v_add_f32_e32 v47, 1.0, v47
	v_rcp_f32_e32 v48, v48
	v_rcp_f32_e32 v45, v45
	v_rcp_f32_e32 v46, v46
	v_rcp_f32_e32 v47, v47
	v_add_f32_e32 v40, 1.0, v40
	v_add_f32_e32 v41, 1.0, v41
	v_add_f32_e32 v42, 1.0, v42
	v_add_f32_e32 v43, 1.0, v43
	v_rcp_f32_e32 v40, v40
	v_rcp_f32_e32 v41, v41
	v_rcp_f32_e32 v42, v42
	v_rcp_f32_e32 v43, v43
	v_add_f32_e32 v36, 1.0, v36
	v_add_f32_e32 v37, 1.0, v37
	v_add_f32_e32 v38, 1.0, v38
	v_add_f32_e32 v39, 1.0, v39
	v_rcp_f32_e32 v36, v36
	v_rcp_f32_e32 v37, v37
	v_rcp_f32_e32 v38, v38
	v_rcp_f32_e32 v39, v39
	v_add_f32_e32 v32, 1.0, v32
	v_add_f32_e32 v33, 1.0, v33
	v_add_f32_e32 v34, 1.0, v34
	v_add_f32_e32 v35, 1.0, v35
	v_rcp_f32_e32 v32, v32
	v_rcp_f32_e32 v33, v33
	v_rcp_f32_e32 v34, v34
	v_rcp_f32_e32 v35, v35
	v_mul_f32_e32 v44, 0xbf60028b, v48
	v_mul_f32_e32 v45, 0xbf60028b, v45
	v_mul_f32_e32 v46, 0xbf60028b, v46
	v_mul_f32_e32 v47, 0xbf60028b, v47
	v_exp_f32_e32 v44, v44
	v_exp_f32_e32 v45, v45
	v_exp_f32_e32 v46, v46
	v_exp_f32_e32 v47, v47
	v_mul_f32_e32 v40, 0xbf60028b, v40
	v_mul_f32_e32 v41, 0xbf60028b, v41
	v_mul_f32_e32 v42, 0xbf60028b, v42
	v_mul_f32_e32 v43, 0xbf60028b, v43
	v_exp_f32_e32 v40, v40
	v_exp_f32_e32 v41, v41
	v_exp_f32_e32 v42, v42
	v_exp_f32_e32 v43, v43
	v_mul_f32_e32 v36, 0xbf60028b, v36
	v_mul_f32_e32 v37, 0xbf60028b, v37
	v_mul_f32_e32 v38, 0xbf60028b, v38
	v_mul_f32_e32 v39, 0xbf60028b, v39
	v_exp_f32_e32 v36, v36
	v_exp_f32_e32 v37, v37
	v_exp_f32_e32 v38, v38
	v_exp_f32_e32 v39, v39
	v_mul_f32_e32 v32, 0xbf60028b, v32
	v_mul_f32_e32 v33, 0xbf60028b, v33
;     __device__ __forceinline__ void operator()(const f32x4 (&acc)[2][2][4][2], const Unit& u, int wr, int wc, int fr, int fq) const {
;     ...
;             for (int n = 0; n < 2; ++n) { const f32x4 bv = *(const f32x4*)(bias + col0 + bj * HALF + n * 16);
; #pragma unroll
;                 for (int ai = 0; ai < 2; ++ai)
; #pragma unroll
;                     for (int m = 0; m < 4; ++m) { f32x4 v = acc[ai][bj][m][n] + bv, o;
; #pragma unroll
;                         for (int e = 0; e < 4; ++e) { const float z = v[e];
;                             const float sg = __builtin_amdgcn_rcpf(1.0f + __builtin_amdgcn_exp2f(-1.4426950408889634f * z));
;                             if (MODE == 0) o[e] = __builtin_amdgcn_exp2f(-0.8750387749f * sg);
;                             else o[e] = sg; }
;                         __builtin_nontemporal_store(o, (f32x4*)(O + (size_t)(row0 + ai * HALF + m * 16) * 1536 + col0 + bj * HALF + n * 16)); } }
	v_mul_f32_e32 v34, 0xbf60028b, v34
	v_mul_f32_e32 v35, 0xbf60028b, v35
	v_exp_f32_e32 v32, v32
	v_exp_f32_e32 v33, v33
	v_exp_f32_e32 v34, v34
	v_exp_f32_e32 v35, v35
	flat_store_dwordx4 v[112:113], v[44:47] offset:512 nt
	flat_store_dwordx4 v[108:109], v[40:43] offset:512 nt
	flat_store_dwordx4 v[104:105], v[36:39] offset:512 nt
	flat_store_dwordx4 v[100:101], v[32:35] offset:512 nt
	s_nop 3
	v_mov_b64_e32 v[32:33], v[220:221]
	v_mov_b64_e32 v[34:35], v[222:223]
	v_add_f32_e32 v28, v28, v32
	v_add_f32_e32 v29, v29, v33
	v_add_f32_e32 v30, v30, v34
	v_add_f32_e32 v31, v31, v35
	v_add_f32_e32 v12, v12, v32
	v_add_f32_e32 v13, v13, v33
	v_add_f32_e32 v14, v14, v34
	v_add_f32_e32 v15, v15, v35
	v_mul_f32_e32 v28, 0xbfb8aa3b, v28
	v_mul_f32_e32 v29, 0xbfb8aa3b, v29
	v_mul_f32_e32 v30, 0xbfb8aa3b, v30
	v_mul_f32_e32 v31, 0xbfb8aa3b, v31
	v_add_f32_e32 v24, v24, v32
	v_add_f32_e32 v25, v25, v33
	v_add_f32_e32 v26, v26, v34
	v_add_f32_e32 v27, v27, v35
	v_mul_f32_e32 v12, 0xbfb8aa3b, v12
	v_mul_f32_e32 v13, 0xbfb8aa3b, v13
	v_mul_f32_e32 v14, 0xbfb8aa3b, v14
	v_mul_f32_e32 v15, 0xbfb8aa3b, v15
	v_exp_f32_e32 v28, v28
	v_exp_f32_e32 v29, v29
	v_exp_f32_e32 v30, v30
	v_exp_f32_e32 v31, v31
	v_mul_f32_e32 v24, 0xbfb8aa3b, v24
	v_mul_f32_e32 v25, 0xbfb8aa3b, v25
	v_mul_f32_e32 v26, 0xbfb8aa3b, v26
	v_mul_f32_e32 v27, 0xbfb8aa3b, v27
	v_add_f32_e32 v20, v20, v32
	v_add_f32_e32 v21, v21, v33
	v_add_f32_e32 v22, v22, v34
	v_add_f32_e32 v23, v23, v35
	v_exp_f32_e32 v12, v12
	v_exp_f32_e32 v13, v13
	v_exp_f32_e32 v14, v14
	v_exp_f32_e32 v15, v15
	v_exp_f32_e32 v24, v24
	v_exp_f32_e32 v25, v25
	v_exp_f32_e32 v26, v26
	v_exp_f32_e32 v27, v27
	v_mul_f32_e32 v20, 0xbfb8aa3b, v20
	v_mul_f32_e32 v21, 0xbfb8aa3b, v21
	v_mul_f32_e32 v22, 0xbfb8aa3b, v22
	v_mul_f32_e32 v23, 0xbfb8aa3b, v23
	v_exp_f32_e32 v20, v20
	v_exp_f32_e32 v21, v21
	v_exp_f32_e32 v22, v22
	v_exp_f32_e32 v23, v23
	v_add_f32_e32 v28, 1.0, v28
	v_add_f32_e32 v29, 1.0, v29
	v_add_f32_e32 v30, 1.0, v30
	v_add_f32_e32 v31, 1.0, v31
	v_add_f32_e32 v12, 1.0, v12
	v_add_f32_e32 v13, 1.0, v13
	v_add_f32_e32 v14, 1.0, v14
	v_add_f32_e32 v15, 1.0, v15
	v_rcp_f32_e32 v28, v28
	v_rcp_f32_e32 v29, v29
	v_rcp_f32_e32 v30, v30
	v_rcp_f32_e32 v31, v31
	v_add_f32_e32 v24, 1.0, v24
	v_add_f32_e32 v25, 1.0, v25
	v_add_f32_e32 v26, 1.0, v26
	v_add_f32_e32 v27, 1.0, v27
	v_rcp_f32_e32 v12, v12
	v_rcp_f32_e32 v13, v13
	v_rcp_f32_e32 v14, v14
	v_rcp_f32_e32 v15, v15
	v_rcp_f32_e32 v24, v24
	v_rcp_f32_e32 v25, v25
	v_rcp_f32_e32 v26, v26
	v_rcp_f32_e32 v27, v27
	v_add_f32_e32 v20, 1.0, v20
	v_add_f32_e32 v21, 1.0, v21
	v_add_f32_e32 v22, 1.0, v22
	v_add_f32_e32 v23, 1.0, v23
	v_rcp_f32_e32 v20, v20
	v_rcp_f32_e32 v21, v21
	v_rcp_f32_e32 v22, v22
	v_rcp_f32_e32 v23, v23
	v_mul_f32_e32 v28, 0xbf60028b, v28
	v_mul_f32_e32 v29, 0xbf60028b, v29
	v_mul_f32_e32 v30, 0xbf60028b, v30
	v_mul_f32_e32 v31, 0xbf60028b, v31
	v_mul_f32_e32 v12, 0xbf60028b, v12
	v_mul_f32_e32 v13, 0xbf60028b, v13
	v_mul_f32_e32 v14, 0xbf60028b, v14
	v_mul_f32_e32 v15, 0xbf60028b, v15
	v_exp_f32_e32 v28, v28
	v_exp_f32_e32 v29, v29
	v_exp_f32_e32 v30, v30
	v_exp_f32_e32 v31, v31
	v_mul_f32_e32 v24, 0xbf60028b, v24
	v_mul_f32_e32 v25, 0xbf60028b, v25
	v_mul_f32_e32 v26, 0xbf60028b, v26
	v_mul_f32_e32 v27, 0xbf60028b, v27
	v_exp_f32_e32 v12, v12
	v_exp_f32_e32 v13, v13
	v_exp_f32_e32 v14, v14
	v_exp_f32_e32 v15, v15
	v_exp_f32_e32 v24, v24
	v_exp_f32_e32 v25, v25
	v_exp_f32_e32 v26, v26
	v_exp_f32_e32 v27, v27
	v_mul_f32_e32 v20, 0xbf60028b, v20
	v_mul_f32_e32 v21, 0xbf60028b, v21
	v_mul_f32_e32 v22, 0xbf60028b, v22
	v_mul_f32_e32 v23, 0xbf60028b, v23
	v_exp_f32_e32 v20, v20
	v_exp_f32_e32 v21, v21
	v_exp_f32_e32 v22, v22
; #define PG8_BAR __builtin_amdgcn_s_barrier()
;     __device__ __forceinline__ void operator()(const f32x4 (&acc)[2][2][4][2], const Unit& u, int wr, int wc, int fr, int fq) const {
;     ...
;             for (int n = 0; n < 2; ++n) { const f32x4 bv = *(const f32x4*)(bias + col0 + bj * HALF + n * 16);
; #pragma unroll
;                 for (int ai = 0; ai < 2; ++ai)
; #pragma unroll
;                     for (int m = 0; m < 4; ++m) { f32x4 v = acc[ai][bj][m][n] + bv, o;
; #pragma unroll
;                         for (int e = 0; e < 4; ++e) { const float z = v[e];
;                             const float sg = __builtin_amdgcn_rcpf(1.0f + __builtin_amdgcn_exp2f(-1.4426950408889634f * z));
;                             if (MODE == 0) o[e] = __builtin_amdgcn_exp2f(-0.8750387749f * sg);
;                             else o[e] = sg; }
;                         __builtin_nontemporal_store(o, (f32x4*)(O + (size_t)(row0 + ai * HALF + m * 16) * 1536 + col0 + bj * HALF + n * 16)); } }
; template <class Epi, class Sched, bool ALIGN_EPI = false, bool SP2 = false>
; __device__ __forceinline__ void gemm_phase(PG8_LAS unsigned char* lds, const Gemm g, const Sched& S, const Epi& E, int tid_in) {
;     ...
;         if constexpr (ALIGN_EPI) { if (wr == 0) PG8_BAR; }
;         if constexpr (!Epi::AFTER_DRAIN) { E(acc, cur, wr, wc, fr, fq); S.done(cur); }
;         if (!has_next) break;
; #pragma unroll
;         for (int a = 0; a < 2; ++a)
; #pragma unroll
;             for (int b = 0; b < 2; ++b)
; #pragma unroll
;                 for (int m = 0; m < 4; ++m)
; #pragma unroll
;                     for (int n = 0; n < 2; ++n) acc[a][b][m][n] = (f32x4){0.f, 0.f, 0.f, 0.f};
;         cur = nxt; cA = nA; cB = nB; ++ui;
;         if constexpr (ALIGN_EPI) { if (wr == 1) PG8_BAR; }
	v_exp_f32_e32 v23, v23
	flat_store_dwordx4 v[136:137], v[28:31] offset:576 nt
	flat_store_dwordx4 v[138:139], v[24:27] offset:576 nt
	flat_store_dwordx4 v[120:121], v[20:23] offset:576 nt
	v_add_f32_e32 v16, v16, v32
	v_add_f32_e32 v17, v17, v33
	flat_store_dwordx4 v[114:115], v[12:15] offset:576 nt
	v_mul_f32_e32 v16, 0xbfb8aa3b, v16
	v_mul_f32_e32 v17, 0xbfb8aa3b, v17
	v_add_f32_e32 v14, v18, v34
	v_add_f32_e32 v15, v19, v35
	v_mul_f32_e32 v14, 0xbfb8aa3b, v14
	v_mul_f32_e32 v15, 0xbfb8aa3b, v15
	v_add_f32_e32 v8, v8, v32
	v_add_f32_e32 v9, v9, v33
	v_add_f32_e32 v10, v10, v34
	v_add_f32_e32 v11, v11, v35
	v_exp_f32_e32 v16, v16
	v_exp_f32_e32 v17, v17
	v_exp_f32_e32 v14, v14
	v_exp_f32_e32 v15, v15
	v_mul_f32_e32 v8, 0xbfb8aa3b, v8
	v_mul_f32_e32 v9, 0xbfb8aa3b, v9
	v_mul_f32_e32 v10, 0xbfb8aa3b, v10
	v_mul_f32_e32 v11, 0xbfb8aa3b, v11
	v_add_f32_e32 v4, v4, v32
	v_add_f32_e32 v5, v5, v33
	v_add_f32_e32 v6, v6, v34
	v_add_f32_e32 v7, v7, v35
	v_exp_f32_e32 v8, v8
	v_exp_f32_e32 v9, v9
	v_exp_f32_e32 v10, v10
	v_exp_f32_e32 v11, v11
	v_mul_f32_e32 v4, 0xbfb8aa3b, v4
	v_mul_f32_e32 v5, 0xbfb8aa3b, v5
	v_mul_f32_e32 v6, 0xbfb8aa3b, v6
	v_mul_f32_e32 v7, 0xbfb8aa3b, v7
	v_add_f32_e32 v0, v0, v32
	v_add_f32_e32 v1, v1, v33
	v_add_f32_e32 v2, v2, v34
	v_add_f32_e32 v3, v3, v35
	v_exp_f32_e32 v4, v4
	v_exp_f32_e32 v5, v5
	v_exp_f32_e32 v6, v6
	v_exp_f32_e32 v7, v7
	v_mul_f32_e32 v0, 0xbfb8aa3b, v0
	v_mul_f32_e32 v1, 0xbfb8aa3b, v1
	v_mul_f32_e32 v2, 0xbfb8aa3b, v2
	v_mul_f32_e32 v3, 0xbfb8aa3b, v3
	v_exp_f32_e32 v0, v0
	v_exp_f32_e32 v1, v1
	v_exp_f32_e32 v2, v2
	v_exp_f32_e32 v3, v3
	v_add_f32_e32 v16, 1.0, v16
	v_add_f32_e32 v13, 1.0, v17
	v_add_f32_e32 v14, 1.0, v14
	v_add_f32_e32 v15, 1.0, v15
	v_rcp_f32_e32 v16, v16
	v_rcp_f32_e32 v13, v13
	v_rcp_f32_e32 v14, v14
	v_rcp_f32_e32 v15, v15
	v_add_f32_e32 v8, 1.0, v8
	v_add_f32_e32 v9, 1.0, v9
	v_add_f32_e32 v10, 1.0, v10
	v_add_f32_e32 v11, 1.0, v11
	v_rcp_f32_e32 v8, v8
	v_rcp_f32_e32 v9, v9
	v_rcp_f32_e32 v10, v10
	v_rcp_f32_e32 v11, v11
	v_add_f32_e32 v4, 1.0, v4
	v_add_f32_e32 v5, 1.0, v5
	v_add_f32_e32 v6, 1.0, v6
	v_add_f32_e32 v7, 1.0, v7
	v_rcp_f32_e32 v4, v4
	v_rcp_f32_e32 v5, v5
	v_rcp_f32_e32 v6, v6
	v_rcp_f32_e32 v7, v7
	v_add_f32_e32 v0, 1.0, v0
	v_add_f32_e32 v1, 1.0, v1
	v_add_f32_e32 v2, 1.0, v2
	v_add_f32_e32 v3, 1.0, v3
	v_rcp_f32_e32 v0, v0
	v_rcp_f32_e32 v1, v1
	v_rcp_f32_e32 v2, v2
	v_rcp_f32_e32 v3, v3
	v_mul_f32_e32 v12, 0xbf60028b, v16
	v_mul_f32_e32 v13, 0xbf60028b, v13
	v_mul_f32_e32 v14, 0xbf60028b, v14
	v_mul_f32_e32 v15, 0xbf60028b, v15
	v_exp_f32_e32 v12, v12
	v_exp_f32_e32 v13, v13
	v_exp_f32_e32 v14, v14
	v_exp_f32_e32 v15, v15
	v_mul_f32_e32 v8, 0xbf60028b, v8
	v_mul_f32_e32 v9, 0xbf60028b, v9
	v_mul_f32_e32 v10, 0xbf60028b, v10
	v_mul_f32_e32 v11, 0xbf60028b, v11
	v_exp_f32_e32 v8, v8
	v_exp_f32_e32 v9, v9
	v_exp_f32_e32 v10, v10
	v_exp_f32_e32 v11, v11
	v_mul_f32_e32 v4, 0xbf60028b, v4
	v_mul_f32_e32 v5, 0xbf60028b, v5
	v_mul_f32_e32 v6, 0xbf60028b, v6
	v_mul_f32_e32 v7, 0xbf60028b, v7
	v_exp_f32_e32 v4, v4
	v_exp_f32_e32 v5, v5
	v_exp_f32_e32 v6, v6
	v_exp_f32_e32 v7, v7
	v_mul_f32_e32 v0, 0xbf60028b, v0
	v_mul_f32_e32 v1, 0xbf60028b, v1
	v_mul_f32_e32 v2, 0xbf60028b, v2
	v_mul_f32_e32 v3, 0xbf60028b, v3
	v_exp_f32_e32 v0, v0
	v_exp_f32_e32 v1, v1
	v_exp_f32_e32 v2, v2
	v_exp_f32_e32 v3, v3
	flat_store_dwordx4 v[112:113], v[12:15] offset:576 nt
	flat_store_dwordx4 v[108:109], v[8:11] offset:576 nt
	flat_store_dwordx4 v[104:105], v[4:7] offset:576 nt
	flat_store_dwordx4 v[100:101], v[0:3] offset:576 nt
	s_cbranch_vccnz .LBB0_373
	s_andn2_b64 vcc, exec, s[10:11]
	s_cbranch_vccnz .LBB0_372
	s_barrier
	s_branch .LBB0_372

;     __device__ __forceinline__ void operator()(const f32x4 (&acc)[2][2][4][2], const Unit& u, int wr, int wc, int fr, int fq) const {
;         const int row0 = u.pm * BM + wr * 64 + fr, col0 = u.pn * BM + wc * 32 + 4 * fq;
; #pragma unroll
;         for (int bj = 0; bj < 2; ++bj)
; #pragma unroll
;             for (int n = 0; n < 2; ++n) { const f32x4 bv = *(const f32x4*)(bias + col0 + bj * HALF + n * 16);
; #pragma unroll
;                 for (int ai = 0; ai < 2; ++ai)
; #pragma unroll
;                     for (int m = 0; m < 4; ++m) { f32x4 v = acc[ai][bj][m][n] + bv, o;
; #pragma unroll
;                         for (int e = 0; e < 4; ++e) { const float z = v[e];
;                             const float sg = __builtin_amdgcn_rcpf(1.0f + __builtin_amdgcn_exp2f(-1.4426950408889634f * z));
;                             if (MODE == 0) o[e] = __builtin_amdgcn_exp2f(-0.8750387749f * sg);
;                             else o[e] = sg; }
;                         __builtin_nontemporal_store(o, (f32x4*)(O + (size_t)(row0 + ai * HALF + m * 16) * 1536 + col0 + bj * HALF + n * 16)); } }
.LBB0_397:
	s_load_dwordx16 s[80:95], s[62:63], 0x0
	v_lshl_or_b32 v104, s0, 8, v149
	v_ashrrev_i32_e32 v105, 31, v104
	v_lshlrev_b64 v[144:145], 2, v[104:105]
	v_lshl_add_u32 v155, s1, 8, v148
	s_waitcnt lgkmcnt(0)
	v_lshl_add_u64 v[138:139], s[94:95], 0, v[144:145]
	global_load_dwordx4 v[104:107], v[138:139], off
	global_load_dwordx4 v[212:215], v[138:139], off offset:64
	global_load_dwordx4 v[216:219], v[138:139], off offset:512
	global_load_dwordx4 v[220:223], v[138:139], off offset:576
	v_mov_b64_e32 v[146:147], s[6:7]
	v_or_b32_e32 v142, 32, v155
	v_mad_i64_i32 v[136:137], s[0:1], v155, s25, v[146:147]
	v_mad_i64_i32 v[156:157], s[0:1], v142, s25, v[146:147]
	v_lshl_add_u64 v[142:143], v[136:137], 0, v[144:145]
	v_lshl_add_u64 v[136:137], v[156:157], 0, v[144:145]
	v_or_b32_e32 v140, 16, v155
	v_mad_i64_i32 v[140:141], s[0:1], v140, s25, v[146:147]
	v_lshl_add_u64 v[140:141], v[140:141], 0, v[144:145]
	s_andn2_b64 vcc, exec, s[20:21]
	s_mov_b64 s[20:21], -1
	s_waitcnt vmcnt(0)
	v_add_f32_e32 v120, v120, v104
	v_add_f32_e32 v121, v121, v105
	v_add_f32_e32 v122, v122, v106
	v_add_f32_e32 v123, v123, v107
	v_add_f32_e32 v124, v124, v104
	v_add_f32_e32 v125, v125, v105
	v_add_f32_e32 v126, v126, v106
	v_add_f32_e32 v127, v127, v107
	v_add_f32_e32 v128, v128, v104
	v_add_f32_e32 v129, v129, v105
	v_add_f32_e32 v130, v130, v106
	v_add_f32_e32 v131, v131, v107
	v_add_f32_e32 v116, v116, v104
	v_add_f32_e32 v117, v117, v105
	v_mul_f32_e32 v120, 0xbfb8aa3b, v120
	v_mul_f32_e32 v121, 0xbfb8aa3b, v121
	v_mul_f32_e32 v122, 0xbfb8aa3b, v122
	v_mul_f32_e32 v123, 0xbfb8aa3b, v123
	v_mul_f32_e32 v124, 0xbfb8aa3b, v124
	v_mul_f32_e32 v125, 0xbfb8aa3b, v125
	v_mul_f32_e32 v126, 0xbfb8aa3b, v126
	v_mul_f32_e32 v127, 0xbfb8aa3b, v127
	v_mul_f32_e32 v128, 0xbfb8aa3b, v128
	v_mul_f32_e32 v129, 0xbfb8aa3b, v129
	v_mul_f32_e32 v130, 0xbfb8aa3b, v130
	v_mul_f32_e32 v131, 0xbfb8aa3b, v131
	v_mul_f32_e32 v116, 0xbfb8aa3b, v116
	v_mul_f32_e32 v117, 0xbfb8aa3b, v117
	v_exp_f32_e32 v120, v120
	v_exp_f32_e32 v121, v121
	v_exp_f32_e32 v122, v122
	v_exp_f32_e32 v123, v123
	v_exp_f32_e32 v124, v124
	v_exp_f32_e32 v125, v125
	v_exp_f32_e32 v126, v126
	v_exp_f32_e32 v127, v127
	v_exp_f32_e32 v128, v128
	v_exp_f32_e32 v129, v129
	v_exp_f32_e32 v130, v130
	v_exp_f32_e32 v131, v131
	v_exp_f32_e32 v116, v116
	v_exp_f32_e32 v117, v117
	v_add_f32_e32 v118, v118, v106
	v_add_f32_e32 v119, v119, v107
	v_add_f32_e32 v112, v112, v104
	v_mul_f32_e32 v118, 0xbfb8aa3b, v118
	v_mul_f32_e32 v119, 0xbfb8aa3b, v119
	v_mul_f32_e32 v112, 0xbfb8aa3b, v112
	v_add_f32_e32 v113, v113, v105
	v_exp_f32_e32 v156, v118
	v_exp_f32_e32 v157, v119
	v_add_f32_e32 v118, 1.0, v120
	v_add_f32_e32 v119, 1.0, v121
	v_add_f32_e32 v120, 1.0, v122
	v_add_f32_e32 v121, 1.0, v123
	v_exp_f32_e32 v112, v112
	v_mul_f32_e32 v113, 0xbfb8aa3b, v113
	v_add_f32_e32 v122, 1.0, v124
	v_add_f32_e32 v123, 1.0, v125
	v_add_f32_e32 v124, 1.0, v126
	v_add_f32_e32 v125, 1.0, v127
	v_add_f32_e32 v126, 1.0, v128
	v_add_f32_e32 v127, 1.0, v129
	v_add_f32_e32 v128, 1.0, v130
	v_add_f32_e32 v129, 1.0, v131
	v_add_f32_e32 v130, 1.0, v116
	v_add_f32_e32 v131, 1.0, v117
	v_rcp_f32_e32 v116, v118
	v_rcp_f32_e32 v117, v119
	v_rcp_f32_e32 v118, v120
	v_rcp_f32_e32 v119, v121
	v_exp_f32_e32 v113, v113
	v_rcp_f32_e32 v120, v122
	v_rcp_f32_e32 v121, v123
	v_rcp_f32_e32 v122, v124
	v_rcp_f32_e32 v123, v125
	v_rcp_f32_e32 v124, v126
	v_rcp_f32_e32 v125, v127
	v_rcp_f32_e32 v126, v128
	v_rcp_f32_e32 v127, v129
	v_add_f32_e32 v112, 1.0, v112
	flat_store_dwordx4 v[142:143], v[116:119] nt
	flat_store_dwordx4 v[140:141], v[120:123] nt
	flat_store_dwordx4 v[136:137], v[124:127] nt
	v_rcp_f32_e32 v118, v112
	v_add_f32_e32 v112, 1.0, v113
	v_add_f32_e32 v113, v114, v106
	v_mul_f32_e32 v113, 0xbfb8aa3b, v113
	v_add_f32_e32 v114, v115, v107
	v_exp_f32_e32 v113, v113
	v_mul_f32_e32 v114, 0xbfb8aa3b, v114
	v_exp_f32_e32 v114, v114
	v_add_f32_e32 v108, v108, v104
	v_rcp_f32_e32 v119, v112
	v_add_f32_e32 v112, 1.0, v113
	v_mul_f32_e32 v108, 0xbfb8aa3b, v108
	v_add_f32_e32 v109, v109, v105
	v_rcp_f32_e32 v120, v112
	v_add_f32_e32 v112, 1.0, v114
	v_exp_f32_e32 v108, v108
	v_mul_f32_e32 v109, 0xbfb8aa3b, v109
	v_rcp_f32_e32 v121, v112
	v_exp_f32_e32 v109, v109
	v_add_u32_e32 v122, 0x80, v155
	v_mad_i64_i32 v[112:113], s[0:1], v122, s25, v[146:147]
	v_lshl_add_u64 v[112:113], v[112:113], 0, v[144:145]
	v_add_f32_e32 v108, 1.0, v108
	flat_store_dwordx4 v[112:113], v[118:121] nt
	v_add_f32_e32 v100, v100, v104
	v_mul_f32_e32 v100, 0xbfb8aa3b, v100
	v_rcp_f32_e32 v118, v108
	v_add_f32_e32 v108, 1.0, v109
	v_add_f32_e32 v109, v110, v106
	v_mul_f32_e32 v109, 0xbfb8aa3b, v109
	v_add_f32_e32 v110, v111, v107
	v_exp_f32_e32 v109, v109
	v_mul_f32_e32 v110, 0xbfb8aa3b, v110
	v_exp_f32_e32 v110, v110
	v_rcp_f32_e32 v119, v108
	v_add_f32_e32 v108, 1.0, v109
	v_add_f32_e32 v101, v101, v105
	v_rcp_f32_e32 v120, v108
	v_add_f32_e32 v108, 1.0, v110
	v_exp_f32_e32 v100, v100
	v_mul_f32_e32 v101, 0xbfb8aa3b, v101
	v_rcp_f32_e32 v121, v108
	v_exp_f32_e32 v101, v101
	v_add_u32_e32 v108, 0x90, v155
	v_mad_i64_i32 v[108:109], s[0:1], v108, s25, v[146:147]
	v_lshl_add_u64 v[108:109], v[108:109], 0, v[144:145]
	v_add_f32_e32 v100, 1.0, v100
	flat_store_dwordx4 v[108:109], v[118:121] nt
	v_add_f32_e32 v96, v96, v104
	v_mul_f32_e32 v96, 0xbfb8aa3b, v96
	v_rcp_f32_e32 v118, v100
	v_add_f32_e32 v100, 1.0, v101
	v_add_f32_e32 v101, v102, v106
	v_mul_f32_e32 v101, 0xbfb8aa3b, v101
	v_add_f32_e32 v102, v103, v107
	v_add_f32_e32 v97, v97, v105
	v_exp_f32_e32 v101, v101
	v_mul_f32_e32 v102, 0xbfb8aa3b, v102
	v_exp_f32_e32 v96, v96
	v_mul_f32_e32 v97, 0xbfb8aa3b, v97
	v_exp_f32_e32 v102, v102
;     __device__ __forceinline__ void operator()(const f32x4 (&acc)[2][2][4][2], const Unit& u, int wr, int wc, int fr, int fq) const {
;         const int row0 = u.pm * BM + wr * 64 + fr, col0 = u.pn * BM + wc * 32 + 4 * fq;
; #pragma unroll
;         for (int bj = 0; bj < 2; ++bj)
; #pragma unroll
;             for (int n = 0; n < 2; ++n) { const f32x4 bv = *(const f32x4*)(bias + col0 + bj * HALF + n * 16);
; #pragma unroll
;                 for (int ai = 0; ai < 2; ++ai)
; #pragma unroll
;                     for (int m = 0; m < 4; ++m) { f32x4 v = acc[ai][bj][m][n] + bv, o;
; #pragma unroll
;                         for (int e = 0; e < 4; ++e) { const float z = v[e];
;                             const float sg = __builtin_amdgcn_rcpf(1.0f + __builtin_amdgcn_exp2f(-1.4426950408889634f * z));
;                             if (MODE == 0) o[e] = __builtin_amdgcn_exp2f(-0.8750387749f * sg);
;                             else o[e] = sg; }
;                         __builtin_nontemporal_store(o, (f32x4*)(O + (size_t)(row0 + ai * HALF + m * 16) * 1536 + col0 + bj * HALF + n * 16)); } }
	v_exp_f32_e32 v97, v97
	v_rcp_f32_e32 v119, v100
	v_add_f32_e32 v100, 1.0, v101
	v_add_f32_e32 v96, 1.0, v96
	v_rcp_f32_e32 v120, v100
	v_add_f32_e32 v100, 1.0, v102
	v_rcp_f32_e32 v102, v96
	v_add_f32_e32 v96, 1.0, v97
	v_add_f32_e32 v97, v98, v106
	v_mul_f32_e32 v97, 0xbfb8aa3b, v97
	v_add_f32_e32 v98, v99, v107
	v_exp_f32_e32 v97, v97
	v_mul_f32_e32 v98, 0xbfb8aa3b, v98
	v_exp_f32_e32 v98, v98
	v_add_f32_e32 v116, 1.0, v156
	v_rcp_f32_e32 v103, v96
	v_add_f32_e32 v96, 1.0, v97
	v_rcp_f32_e32 v128, v130
	v_rcp_f32_e32 v130, v116
	v_add_f32_e32 v116, 1.0, v157
	v_rcp_f32_e32 v104, v96
	v_add_f32_e32 v96, 1.0, v98
	v_rcp_f32_e32 v129, v131
	v_rcp_f32_e32 v131, v116
	v_rcp_f32_e32 v121, v100
	v_rcp_f32_e32 v105, v96
	v_or_b32_e32 v116, 48, v155
	v_add_u32_e32 v100, 0xa0, v155
	v_add_u32_e32 v96, 0xb0, v155
	v_mad_i64_i32 v[116:117], s[0:1], v116, s25, v[146:147]
	v_mad_i64_i32 v[100:101], s[0:1], v100, s25, v[146:147]
	v_mad_i64_i32 v[96:97], s[0:1], v96, s25, v[146:147]
	v_lshl_add_u64 v[116:117], v[116:117], 0, v[144:145]
	v_lshl_add_u64 v[100:101], v[100:101], 0, v[144:145]
	v_lshl_add_u64 v[96:97], v[96:97], 0, v[144:145]
	flat_store_dwordx4 v[116:117], v[128:131] nt
	flat_store_dwordx4 v[100:101], v[118:121] nt
	flat_store_dwordx4 v[96:97], v[102:105] nt
	s_nop 3
	v_mov_b64_e32 v[102:103], v[212:213]
	v_mov_b64_e32 v[104:105], v[214:215]
	v_add_f32_e32 v80, v80, v102
	v_add_f32_e32 v81, v81, v103
	v_add_f32_e32 v82, v82, v104
	v_add_f32_e32 v83, v83, v105
	v_add_f32_e32 v72, v72, v102
	v_add_f32_e32 v73, v73, v103
	v_add_f32_e32 v74, v74, v104
	v_add_f32_e32 v75, v75, v105
	v_mul_f32_e32 v80, 0xbfb8aa3b, v80
	v_mul_f32_e32 v81, 0xbfb8aa3b, v81
	v_mul_f32_e32 v82, 0xbfb8aa3b, v82
	v_mul_f32_e32 v83, 0xbfb8aa3b, v83
	v_mul_f32_e32 v72, 0xbfb8aa3b, v72
	v_mul_f32_e32 v73, 0xbfb8aa3b, v73
	v_mul_f32_e32 v74, 0xbfb8aa3b, v74
	v_mul_f32_e32 v75, 0xbfb8aa3b, v75
	v_exp_f32_e32 v80, v80
	v_exp_f32_e32 v81, v81
	v_exp_f32_e32 v82, v82
	v_exp_f32_e32 v83, v83
	v_exp_f32_e32 v72, v72
	v_exp_f32_e32 v73, v73
	v_exp_f32_e32 v74, v74
	v_exp_f32_e32 v75, v75
	v_add_f32_e32 v80, 1.0, v80
	v_add_f32_e32 v81, 1.0, v81
	v_add_f32_e32 v82, 1.0, v82
	v_add_f32_e32 v83, 1.0, v83
	v_add_f32_e32 v72, 1.0, v72
	v_add_f32_e32 v73, 1.0, v73
	v_add_f32_e32 v74, 1.0, v74
	v_add_f32_e32 v75, 1.0, v75
	v_rcp_f32_e32 v80, v80
	v_rcp_f32_e32 v81, v81
	v_rcp_f32_e32 v82, v82
	v_rcp_f32_e32 v83, v83
	v_rcp_f32_e32 v72, v72
	v_rcp_f32_e32 v73, v73
	v_rcp_f32_e32 v74, v74
	v_rcp_f32_e32 v75, v75
	v_add_f32_e32 v92, v92, v102
	v_add_f32_e32 v93, v93, v103
	v_add_f32_e32 v94, v94, v104
	v_add_f32_e32 v95, v95, v105
	v_add_f32_e32 v88, v88, v102
	v_add_f32_e32 v89, v89, v103
	v_add_f32_e32 v90, v90, v104
	v_add_f32_e32 v91, v91, v105
	flat_store_dwordx4 v[136:137], v[80:83] offset:64 nt
	flat_store_dwordx4 v[116:117], v[72:75] offset:64 nt
	v_mul_f32_e32 v92, 0xbfb8aa3b, v92
	v_add_f32_e32 v80, v84, v102
	v_add_f32_e32 v81, v85, v103
	v_add_f32_e32 v74, v86, v104
	v_add_f32_e32 v75, v87, v105
	v_mul_f32_e32 v93, 0xbfb8aa3b, v93
	v_mul_f32_e32 v94, 0xbfb8aa3b, v94
	v_mul_f32_e32 v95, 0xbfb8aa3b, v95
	v_mul_f32_e32 v88, 0xbfb8aa3b, v88
	v_mul_f32_e32 v89, 0xbfb8aa3b, v89
	v_mul_f32_e32 v90, 0xbfb8aa3b, v90
	v_mul_f32_e32 v91, 0xbfb8aa3b, v91
	v_mul_f32_e32 v80, 0xbfb8aa3b, v80
	v_mul_f32_e32 v81, 0xbfb8aa3b, v81
	v_mul_f32_e32 v74, 0xbfb8aa3b, v74
	v_mul_f32_e32 v75, 0xbfb8aa3b, v75
	v_add_f32_e32 v76, v76, v102
	v_add_f32_e32 v77, v77, v103
	v_add_f32_e32 v78, v78, v104
	v_add_f32_e32 v79, v79, v105
	v_exp_f32_e32 v92, v92
	v_exp_f32_e32 v93, v93
	v_exp_f32_e32 v94, v94
	v_exp_f32_e32 v95, v95
	v_exp_f32_e32 v88, v88
	v_exp_f32_e32 v89, v89
	v_exp_f32_e32 v90, v90
	v_exp_f32_e32 v91, v91
	v_exp_f32_e32 v80, v80
	v_exp_f32_e32 v81, v81
	v_exp_f32_e32 v74, v74
	v_exp_f32_e32 v75, v75
	v_mul_f32_e32 v76, 0xbfb8aa3b, v76
	v_mul_f32_e32 v77, 0xbfb8aa3b, v77
	v_mul_f32_e32 v78, 0xbfb8aa3b, v78
	v_mul_f32_e32 v79, 0xbfb8aa3b, v79
	v_add_f32_e32 v68, v68, v102
	v_add_f32_e32 v69, v69, v103
	v_add_f32_e32 v70, v70, v104
	v_add_f32_e32 v71, v71, v105
	v_exp_f32_e32 v76, v76
	v_exp_f32_e32 v77, v77
	v_exp_f32_e32 v78, v78
	v_exp_f32_e32 v79, v79
	v_mul_f32_e32 v68, 0xbfb8aa3b, v68
	v_mul_f32_e32 v69, 0xbfb8aa3b, v69
	v_mul_f32_e32 v70, 0xbfb8aa3b, v70
	v_mul_f32_e32 v71, 0xbfb8aa3b, v71
	v_add_f32_e32 v64, v64, v102
	v_add_f32_e32 v65, v65, v103
	v_add_f32_e32 v66, v66, v104
	v_add_f32_e32 v67, v67, v105
	v_exp_f32_e32 v68, v68
	v_exp_f32_e32 v69, v69
	v_exp_f32_e32 v70, v70
	v_exp_f32_e32 v71, v71
	v_mul_f32_e32 v64, 0xbfb8aa3b, v64
	v_mul_f32_e32 v65, 0xbfb8aa3b, v65
	v_mul_f32_e32 v66, 0xbfb8aa3b, v66
	v_mul_f32_e32 v67, 0xbfb8aa3b, v67
	v_exp_f32_e32 v64, v64
	v_exp_f32_e32 v65, v65
	v_exp_f32_e32 v66, v66
	v_exp_f32_e32 v67, v67
	v_add_f32_e32 v92, 1.0, v92
	v_add_f32_e32 v93, 1.0, v93
	v_add_f32_e32 v94, 1.0, v94
	v_add_f32_e32 v95, 1.0, v95
	v_add_f32_e32 v88, 1.0, v88
	v_add_f32_e32 v89, 1.0, v89
	v_add_f32_e32 v90, 1.0, v90
	v_add_f32_e32 v91, 1.0, v91
	v_add_f32_e32 v72, 1.0, v80
	v_add_f32_e32 v73, 1.0, v81
	v_add_f32_e32 v74, 1.0, v74
	v_add_f32_e32 v75, 1.0, v75
	v_rcp_f32_e32 v92, v92
	v_rcp_f32_e32 v93, v93
	v_rcp_f32_e32 v94, v94
	v_rcp_f32_e32 v95, v95
	v_rcp_f32_e32 v88, v88
	v_rcp_f32_e32 v89, v89
	v_rcp_f32_e32 v90, v90
	v_rcp_f32_e32 v91, v91
	v_rcp_f32_e32 v72, v72
	v_rcp_f32_e32 v73, v73
	v_rcp_f32_e32 v74, v74
	v_rcp_f32_e32 v75, v75
	v_add_f32_e32 v76, 1.0, v76
	v_add_f32_e32 v77, 1.0, v77
	v_add_f32_e32 v78, 1.0, v78
	v_add_f32_e32 v79, 1.0, v79
	v_rcp_f32_e32 v76, v76
	v_rcp_f32_e32 v77, v77
	v_rcp_f32_e32 v78, v78
	v_rcp_f32_e32 v79, v79
	v_add_f32_e32 v68, 1.0, v68
;     __device__ __forceinline__ void operator()(const f32x4 (&acc)[2][2][4][2], const Unit& u, int wr, int wc, int fr, int fq) const {
;         const int row0 = u.pm * BM + wr * 64 + fr, col0 = u.pn * BM + wc * 32 + 4 * fq;
; #pragma unroll
;         for (int bj = 0; bj < 2; ++bj)
; #pragma unroll
;             for (int n = 0; n < 2; ++n) { const f32x4 bv = *(const f32x4*)(bias + col0 + bj * HALF + n * 16);
; #pragma unroll
;                 for (int ai = 0; ai < 2; ++ai)
; #pragma unroll
;                     for (int m = 0; m < 4; ++m) { f32x4 v = acc[ai][bj][m][n] + bv, o;
; #pragma unroll
;                         for (int e = 0; e < 4; ++e) { const float z = v[e];
;                             const float sg = __builtin_amdgcn_rcpf(1.0f + __builtin_amdgcn_exp2f(-1.4426950408889634f * z));
;                             if (MODE == 0) o[e] = __builtin_amdgcn_exp2f(-0.8750387749f * sg);
;                             else o[e] = sg; }
;                         __builtin_nontemporal_store(o, (f32x4*)(O + (size_t)(row0 + ai * HALF + m * 16) * 1536 + col0 + bj * HALF + n * 16)); } }
	v_add_f32_e32 v69, 1.0, v69
	v_add_f32_e32 v70, 1.0, v70
	v_add_f32_e32 v71, 1.0, v71
	v_rcp_f32_e32 v68, v68
	v_rcp_f32_e32 v69, v69
	v_rcp_f32_e32 v70, v70
	v_rcp_f32_e32 v71, v71
	v_add_f32_e32 v64, 1.0, v64
	v_add_f32_e32 v65, 1.0, v65
	v_add_f32_e32 v66, 1.0, v66
	v_add_f32_e32 v67, 1.0, v67
	v_rcp_f32_e32 v64, v64
	v_rcp_f32_e32 v65, v65
	v_rcp_f32_e32 v66, v66
	v_rcp_f32_e32 v67, v67
	flat_store_dwordx4 v[142:143], v[92:95] offset:64 nt
	flat_store_dwordx4 v[140:141], v[88:91] offset:64 nt
	flat_store_dwordx4 v[112:113], v[72:75] offset:64 nt
	flat_store_dwordx4 v[108:109], v[76:79] offset:64 nt
	flat_store_dwordx4 v[100:101], v[68:71] offset:64 nt
	flat_store_dwordx4 v[96:97], v[64:67] offset:64 nt
	s_nop 3
	v_mov_b64_e32 v[64:65], v[216:217]
	v_mov_b64_e32 v[66:67], v[218:219]
	v_add_f32_e32 v48, v48, v64
	v_add_f32_e32 v49, v49, v65
	v_add_f32_e32 v50, v50, v66
	v_add_f32_e32 v51, v51, v67
	v_add_f32_e32 v40, v40, v64
	v_add_f32_e32 v41, v41, v65
	v_add_f32_e32 v42, v42, v66
	v_add_f32_e32 v43, v43, v67
	v_mul_f32_e32 v48, 0xbfb8aa3b, v48
	v_mul_f32_e32 v49, 0xbfb8aa3b, v49
	v_mul_f32_e32 v50, 0xbfb8aa3b, v50
	v_mul_f32_e32 v51, 0xbfb8aa3b, v51
	v_mul_f32_e32 v40, 0xbfb8aa3b, v40
	v_mul_f32_e32 v41, 0xbfb8aa3b, v41
	v_mul_f32_e32 v42, 0xbfb8aa3b, v42
	v_mul_f32_e32 v43, 0xbfb8aa3b, v43
	v_exp_f32_e32 v48, v48
	v_exp_f32_e32 v49, v49
	v_exp_f32_e32 v50, v50
	v_exp_f32_e32 v51, v51
	v_exp_f32_e32 v40, v40
	v_exp_f32_e32 v41, v41
	v_exp_f32_e32 v42, v42
	v_exp_f32_e32 v43, v43
	v_add_f32_e32 v48, 1.0, v48
	v_add_f32_e32 v49, 1.0, v49
	v_add_f32_e32 v50, 1.0, v50
	v_add_f32_e32 v51, 1.0, v51
	v_add_f32_e32 v40, 1.0, v40
	v_add_f32_e32 v41, 1.0, v41
	v_add_f32_e32 v42, 1.0, v42
	v_add_f32_e32 v43, 1.0, v43
	v_rcp_f32_e32 v48, v48
	v_rcp_f32_e32 v49, v49
	v_rcp_f32_e32 v50, v50
	v_rcp_f32_e32 v51, v51
	v_rcp_f32_e32 v40, v40
	v_rcp_f32_e32 v41, v41
	v_rcp_f32_e32 v42, v42
	v_rcp_f32_e32 v43, v43
	v_add_f32_e32 v60, v60, v64
	v_add_f32_e32 v61, v61, v65
	v_add_f32_e32 v62, v62, v66
	v_add_f32_e32 v63, v63, v67
	v_add_f32_e32 v56, v56, v64
	v_add_f32_e32 v57, v57, v65
	v_add_f32_e32 v58, v58, v66
	v_add_f32_e32 v59, v59, v67
	flat_store_dwordx4 v[136:137], v[48:51] offset:512 nt
	flat_store_dwordx4 v[116:117], v[40:43] offset:512 nt
	v_mul_f32_e32 v60, 0xbfb8aa3b, v60
	v_add_f32_e32 v48, v52, v64
	v_add_f32_e32 v49, v53, v65
	v_add_f32_e32 v42, v54, v66
	v_add_f32_e32 v43, v55, v67
	v_mul_f32_e32 v61, 0xbfb8aa3b, v61
	v_mul_f32_e32 v62, 0xbfb8aa3b, v62
	v_mul_f32_e32 v63, 0xbfb8aa3b, v63
	v_mul_f32_e32 v56, 0xbfb8aa3b, v56
	v_mul_f32_e32 v57, 0xbfb8aa3b, v57
	v_mul_f32_e32 v58, 0xbfb8aa3b, v58
	v_mul_f32_e32 v59, 0xbfb8aa3b, v59
	v_mul_f32_e32 v48, 0xbfb8aa3b, v48
	v_mul_f32_e32 v49, 0xbfb8aa3b, v49
	v_mul_f32_e32 v42, 0xbfb8aa3b, v42
	v_mul_f32_e32 v43, 0xbfb8aa3b, v43
	v_add_f32_e32 v44, v44, v64
	v_add_f32_e32 v45, v45, v65
	v_add_f32_e32 v46, v46, v66
	v_add_f32_e32 v47, v47, v67
	v_exp_f32_e32 v60, v60
	v_exp_f32_e32 v61, v61
	v_exp_f32_e32 v62, v62
	v_exp_f32_e32 v63, v63
	v_exp_f32_e32 v56, v56
	v_exp_f32_e32 v57, v57
	v_exp_f32_e32 v58, v58
	v_exp_f32_e32 v59, v59
	v_exp_f32_e32 v48, v48
	v_exp_f32_e32 v49, v49
	v_exp_f32_e32 v42, v42
	v_exp_f32_e32 v43, v43
	v_mul_f32_e32 v44, 0xbfb8aa3b, v44
	v_mul_f32_e32 v45, 0xbfb8aa3b, v45
	v_mul_f32_e32 v46, 0xbfb8aa3b, v46
	v_mul_f32_e32 v47, 0xbfb8aa3b, v47
	v_add_f32_e32 v36, v36, v64
	v_add_f32_e32 v37, v37, v65
	v_add_f32_e32 v38, v38, v66
	v_add_f32_e32 v39, v39, v67
	v_exp_f32_e32 v44, v44
	v_exp_f32_e32 v45, v45
	v_exp_f32_e32 v46, v46
	v_exp_f32_e32 v47, v47
	v_mul_f32_e32 v36, 0xbfb8aa3b, v36
	v_mul_f32_e32 v37, 0xbfb8aa3b, v37
	v_mul_f32_e32 v38, 0xbfb8aa3b, v38
	v_mul_f32_e32 v39, 0xbfb8aa3b, v39
	v_add_f32_e32 v32, v32, v64
	v_add_f32_e32 v33, v33, v65
	v_add_f32_e32 v34, v34, v66
	v_add_f32_e32 v35, v35, v67
	v_exp_f32_e32 v36, v36
	v_exp_f32_e32 v37, v37
	v_exp_f32_e32 v38, v38
	v_exp_f32_e32 v39, v39
	v_mul_f32_e32 v32, 0xbfb8aa3b, v32
	v_mul_f32_e32 v33, 0xbfb8aa3b, v33
	v_mul_f32_e32 v34, 0xbfb8aa3b, v34
	v_mul_f32_e32 v35, 0xbfb8aa3b, v35
	v_exp_f32_e32 v32, v32
	v_exp_f32_e32 v33, v33
	v_exp_f32_e32 v34, v34
	v_exp_f32_e32 v35, v35
	v_add_f32_e32 v60, 1.0, v60
	v_add_f32_e32 v61, 1.0, v61
	v_add_f32_e32 v62, 1.0, v62
	v_add_f32_e32 v63, 1.0, v63
	v_add_f32_e32 v56, 1.0, v56
	v_add_f32_e32 v57, 1.0, v57
	v_add_f32_e32 v58, 1.0, v58
	v_add_f32_e32 v59, 1.0, v59
	v_add_f32_e32 v40, 1.0, v48
	v_add_f32_e32 v41, 1.0, v49
	v_add_f32_e32 v42, 1.0, v42
	v_add_f32_e32 v43, 1.0, v43
	v_rcp_f32_e32 v60, v60
	v_rcp_f32_e32 v61, v61
	v_rcp_f32_e32 v62, v62
	v_rcp_f32_e32 v63, v63
	v_rcp_f32_e32 v56, v56
	v_rcp_f32_e32 v57, v57
	v_rcp_f32_e32 v58, v58
	v_rcp_f32_e32 v59, v59
	v_rcp_f32_e32 v40, v40
	v_rcp_f32_e32 v41, v41
	v_rcp_f32_e32 v42, v42
	v_rcp_f32_e32 v43, v43
	v_add_f32_e32 v44, 1.0, v44
	v_add_f32_e32 v45, 1.0, v45
	v_add_f32_e32 v46, 1.0, v46
	v_add_f32_e32 v47, 1.0, v47
	v_rcp_f32_e32 v44, v44
	v_rcp_f32_e32 v45, v45
	v_rcp_f32_e32 v46, v46
	v_rcp_f32_e32 v47, v47
	v_add_f32_e32 v36, 1.0, v36
	v_add_f32_e32 v37, 1.0, v37
	v_add_f32_e32 v38, 1.0, v38
	v_add_f32_e32 v39, 1.0, v39
	v_rcp_f32_e32 v36, v36
	v_rcp_f32_e32 v37, v37
	v_rcp_f32_e32 v38, v38
	v_rcp_f32_e32 v39, v39
	v_add_f32_e32 v32, 1.0, v32
	v_add_f32_e32 v33, 1.0, v33
	v_add_f32_e32 v34, 1.0, v34
	v_add_f32_e32 v35, 1.0, v35
	v_rcp_f32_e32 v32, v32
	v_rcp_f32_e32 v33, v33
	v_rcp_f32_e32 v34, v34
; #define PG8_BAR __builtin_amdgcn_s_barrier()
;     __device__ __forceinline__ void operator()(const f32x4 (&acc)[2][2][4][2], const Unit& u, int wr, int wc, int fr, int fq) const {
;         const int row0 = u.pm * BM + wr * 64 + fr, col0 = u.pn * BM + wc * 32 + 4 * fq;
; #pragma unroll
;         for (int bj = 0; bj < 2; ++bj)
; #pragma unroll
;             for (int n = 0; n < 2; ++n) { const f32x4 bv = *(const f32x4*)(bias + col0 + bj * HALF + n * 16);
; #pragma unroll
;                 for (int ai = 0; ai < 2; ++ai)
; #pragma unroll
;                     for (int m = 0; m < 4; ++m) { f32x4 v = acc[ai][bj][m][n] + bv, o;
; #pragma unroll
;                         for (int e = 0; e < 4; ++e) { const float z = v[e];
;                             const float sg = __builtin_amdgcn_rcpf(1.0f + __builtin_amdgcn_exp2f(-1.4426950408889634f * z));
;                             if (MODE == 0) o[e] = __builtin_amdgcn_exp2f(-0.8750387749f * sg);
;                             else o[e] = sg; }
;                         __builtin_nontemporal_store(o, (f32x4*)(O + (size_t)(row0 + ai * HALF + m * 16) * 1536 + col0 + bj * HALF + n * 16)); } }
; template <class Epi, class Sched, bool ALIGN_EPI = false, bool SP2 = false>
; __device__ __forceinline__ void gemm_phase(PG8_LAS unsigned char* lds, const Gemm g, const Sched& S, const Epi& E, int tid_in) {
;     ...
;         if constexpr (ALIGN_EPI) { if (wr == 0) PG8_BAR; }
;         if constexpr (!Epi::AFTER_DRAIN) { E(acc, cur, wr, wc, fr, fq); S.done(cur); }
;         if (!has_next) break;
; #pragma unroll
;         for (int a = 0; a < 2; ++a)
; #pragma unroll
;             for (int b = 0; b < 2; ++b)
; #pragma unroll
;                 for (int m = 0; m < 4; ++m)
; #pragma unroll
;                     for (int n = 0; n < 2; ++n) acc[a][b][m][n] = (f32x4){0.f, 0.f, 0.f, 0.f};
;         cur = nxt; cA = nA; cB = nB; ++ui;
;         if constexpr (ALIGN_EPI) { if (wr == 1) PG8_BAR; }
	v_rcp_f32_e32 v35, v35
	flat_store_dwordx4 v[142:143], v[60:63] offset:512 nt
	flat_store_dwordx4 v[140:141], v[56:59] offset:512 nt
	flat_store_dwordx4 v[112:113], v[40:43] offset:512 nt
	flat_store_dwordx4 v[108:109], v[44:47] offset:512 nt
	flat_store_dwordx4 v[100:101], v[36:39] offset:512 nt
	flat_store_dwordx4 v[96:97], v[32:35] offset:512 nt
	s_nop 3
	v_mov_b64_e32 v[32:33], v[220:221]
	v_mov_b64_e32 v[34:35], v[222:223]
	v_add_f32_e32 v16, v16, v32
	v_add_f32_e32 v17, v17, v33
	v_add_f32_e32 v18, v18, v34
	v_add_f32_e32 v19, v19, v35
	v_add_f32_e32 v8, v8, v32
	v_add_f32_e32 v9, v9, v33
	v_add_f32_e32 v10, v10, v34
	v_add_f32_e32 v11, v11, v35
	v_mul_f32_e32 v16, 0xbfb8aa3b, v16
	v_mul_f32_e32 v17, 0xbfb8aa3b, v17
	v_mul_f32_e32 v18, 0xbfb8aa3b, v18
	v_mul_f32_e32 v19, 0xbfb8aa3b, v19
	v_mul_f32_e32 v8, 0xbfb8aa3b, v8
	v_mul_f32_e32 v9, 0xbfb8aa3b, v9
	v_mul_f32_e32 v10, 0xbfb8aa3b, v10
	v_mul_f32_e32 v11, 0xbfb8aa3b, v11
	v_exp_f32_e32 v16, v16
	v_exp_f32_e32 v17, v17
	v_exp_f32_e32 v18, v18
	v_exp_f32_e32 v19, v19
	v_exp_f32_e32 v8, v8
	v_exp_f32_e32 v9, v9
	v_exp_f32_e32 v10, v10
	v_exp_f32_e32 v11, v11
	v_add_f32_e32 v16, 1.0, v16
	v_add_f32_e32 v17, 1.0, v17
	v_add_f32_e32 v18, 1.0, v18
	v_add_f32_e32 v19, 1.0, v19
	v_add_f32_e32 v8, 1.0, v8
	v_add_f32_e32 v9, 1.0, v9
	v_add_f32_e32 v10, 1.0, v10
	v_add_f32_e32 v11, 1.0, v11
	v_rcp_f32_e32 v16, v16
	v_rcp_f32_e32 v17, v17
	v_rcp_f32_e32 v18, v18
	v_rcp_f32_e32 v19, v19
	v_rcp_f32_e32 v8, v8
	v_rcp_f32_e32 v9, v9
	v_rcp_f32_e32 v10, v10
	v_rcp_f32_e32 v11, v11
	v_add_f32_e32 v28, v28, v32
	v_add_f32_e32 v29, v29, v33
	v_add_f32_e32 v30, v30, v34
	v_add_f32_e32 v31, v31, v35
	v_add_f32_e32 v24, v24, v32
	v_add_f32_e32 v25, v25, v33
	v_add_f32_e32 v26, v26, v34
	v_add_f32_e32 v27, v27, v35
	flat_store_dwordx4 v[136:137], v[16:19] offset:576 nt
	flat_store_dwordx4 v[116:117], v[8:11] offset:576 nt
	v_mul_f32_e32 v28, 0xbfb8aa3b, v28
	v_add_f32_e32 v16, v20, v32
	v_add_f32_e32 v17, v21, v33
	v_add_f32_e32 v10, v22, v34
	v_add_f32_e32 v11, v23, v35
	v_mul_f32_e32 v29, 0xbfb8aa3b, v29
	v_mul_f32_e32 v30, 0xbfb8aa3b, v30
	v_mul_f32_e32 v31, 0xbfb8aa3b, v31
	v_mul_f32_e32 v24, 0xbfb8aa3b, v24
	v_mul_f32_e32 v25, 0xbfb8aa3b, v25
	v_mul_f32_e32 v26, 0xbfb8aa3b, v26
	v_mul_f32_e32 v27, 0xbfb8aa3b, v27
	v_mul_f32_e32 v16, 0xbfb8aa3b, v16
	v_mul_f32_e32 v17, 0xbfb8aa3b, v17
	v_mul_f32_e32 v10, 0xbfb8aa3b, v10
	v_mul_f32_e32 v11, 0xbfb8aa3b, v11
	v_add_f32_e32 v12, v12, v32
	v_add_f32_e32 v13, v13, v33
	v_add_f32_e32 v14, v14, v34
	v_add_f32_e32 v15, v15, v35
	v_exp_f32_e32 v28, v28
	v_exp_f32_e32 v29, v29
	v_exp_f32_e32 v30, v30
	v_exp_f32_e32 v31, v31
	v_exp_f32_e32 v24, v24
	v_exp_f32_e32 v25, v25
	v_exp_f32_e32 v26, v26
	v_exp_f32_e32 v27, v27
	v_exp_f32_e32 v16, v16
	v_exp_f32_e32 v17, v17
	v_exp_f32_e32 v10, v10
	v_exp_f32_e32 v11, v11
	v_mul_f32_e32 v12, 0xbfb8aa3b, v12
	v_mul_f32_e32 v13, 0xbfb8aa3b, v13
	v_mul_f32_e32 v14, 0xbfb8aa3b, v14
	v_mul_f32_e32 v15, 0xbfb8aa3b, v15
	v_add_f32_e32 v4, v4, v32
	v_add_f32_e32 v5, v5, v33
	v_add_f32_e32 v6, v6, v34
	v_add_f32_e32 v7, v7, v35
	v_exp_f32_e32 v12, v12
	v_exp_f32_e32 v13, v13
	v_exp_f32_e32 v14, v14
	v_exp_f32_e32 v15, v15
	v_mul_f32_e32 v4, 0xbfb8aa3b, v4
	v_mul_f32_e32 v5, 0xbfb8aa3b, v5
	v_mul_f32_e32 v6, 0xbfb8aa3b, v6
	v_mul_f32_e32 v7, 0xbfb8aa3b, v7
	v_add_f32_e32 v0, v0, v32
	v_add_f32_e32 v1, v1, v33
	v_add_f32_e32 v2, v2, v34
	v_add_f32_e32 v3, v3, v35
	v_exp_f32_e32 v4, v4
	v_exp_f32_e32 v5, v5
	v_exp_f32_e32 v6, v6
	v_exp_f32_e32 v7, v7
	v_mul_f32_e32 v0, 0xbfb8aa3b, v0
	v_mul_f32_e32 v1, 0xbfb8aa3b, v1
	v_mul_f32_e32 v2, 0xbfb8aa3b, v2
	v_mul_f32_e32 v3, 0xbfb8aa3b, v3
	v_exp_f32_e32 v0, v0
	v_exp_f32_e32 v1, v1
	v_exp_f32_e32 v2, v2
	v_exp_f32_e32 v3, v3
	v_add_f32_e32 v28, 1.0, v28
	v_add_f32_e32 v29, 1.0, v29
	v_add_f32_e32 v30, 1.0, v30
	v_add_f32_e32 v31, 1.0, v31
	v_add_f32_e32 v24, 1.0, v24
	v_add_f32_e32 v25, 1.0, v25
	v_add_f32_e32 v26, 1.0, v26
	v_add_f32_e32 v27, 1.0, v27
	v_add_f32_e32 v8, 1.0, v16
	v_add_f32_e32 v9, 1.0, v17
	v_add_f32_e32 v10, 1.0, v10
	v_add_f32_e32 v11, 1.0, v11
	v_rcp_f32_e32 v28, v28
	v_rcp_f32_e32 v29, v29
	v_rcp_f32_e32 v30, v30
	v_rcp_f32_e32 v31, v31
	v_rcp_f32_e32 v24, v24
	v_rcp_f32_e32 v25, v25
	v_rcp_f32_e32 v26, v26
	v_rcp_f32_e32 v27, v27
	v_rcp_f32_e32 v8, v8
	v_rcp_f32_e32 v9, v9
	v_rcp_f32_e32 v10, v10
	v_rcp_f32_e32 v11, v11
	v_add_f32_e32 v12, 1.0, v12
	v_add_f32_e32 v13, 1.0, v13
	v_add_f32_e32 v14, 1.0, v14
	v_add_f32_e32 v15, 1.0, v15
	v_rcp_f32_e32 v12, v12
	v_rcp_f32_e32 v13, v13
	v_rcp_f32_e32 v14, v14
	v_rcp_f32_e32 v15, v15
	v_add_f32_e32 v4, 1.0, v4
	v_add_f32_e32 v5, 1.0, v5
	v_add_f32_e32 v6, 1.0, v6
	v_add_f32_e32 v7, 1.0, v7
	v_rcp_f32_e32 v4, v4
	v_rcp_f32_e32 v5, v5
	v_rcp_f32_e32 v6, v6
	v_rcp_f32_e32 v7, v7
	v_add_f32_e32 v0, 1.0, v0
	v_add_f32_e32 v1, 1.0, v1
	v_add_f32_e32 v2, 1.0, v2
	v_add_f32_e32 v3, 1.0, v3
	v_rcp_f32_e32 v0, v0
	v_rcp_f32_e32 v1, v1
	v_rcp_f32_e32 v2, v2
	v_rcp_f32_e32 v3, v3
	flat_store_dwordx4 v[142:143], v[28:31] offset:576 nt
	flat_store_dwordx4 v[140:141], v[24:27] offset:576 nt
	flat_store_dwordx4 v[112:113], v[8:11] offset:576 nt
	flat_store_dwordx4 v[108:109], v[12:15] offset:576 nt
	flat_store_dwordx4 v[100:101], v[4:7] offset:576 nt
	flat_store_dwordx4 v[96:97], v[0:3] offset:576 nt
	s_cbranch_vccnz .LBB0_392
	s_andn2_b64 vcc, exec, s[2:3]
	s_cbranch_vccnz .LBB0_391
	s_barrier
	s_branch .LBB0_391

; #define PG8_WAIT_V(n) asm volatile("s_waitcnt vmcnt(" #n ")" ::: "memory")
; template <class Epi, class Sched, bool ALIGN_EPI = false, bool SP2 = false>
; __device__ __forceinline__ void gemm_phase(PG8_LAS unsigned char* lds, const Gemm g, const Sched& S, const Epi& E, int tid_in) {
;     ...
;     const char* cA = (const char*)g.A + (size_t)cur.pm * tstep; const char* cB = (const char*)g.Bt + (size_t)cur.pn * tstep;
;     S.a_ready(cur);
;     if constexpr (SP2) {
;         PG8_STAGE(PG8_SB(0, 0), cB, voffB); PG8_STAGE(PG8_SB(0, 1), cB + hstep, voffB); PG8_STAGE(PG8_SA(0, 0), cA, voffA); PG8_STAGE(PG8_SA(0, 1), cA + hstep, voffA);
;         if (wr == 1) PG8_BAR;
;         PG8_WAIT_V(2); PG8_BAR;
;         PG8_STAGE(PG8_SB(1, 0), cB + kstep, voffB); PG8_STAGE(PG8_SA(1, 0), cA + kstep, voffA); PG8_STAGE(PG8_SB(1, 1), cB + hstep + kstep, voffB);
;         PG8_WAIT_V(6); PG8_BAR;
;     } else {
;         PG8_STAGE(PG8_SB(0, 0), cB, voffB); PG8_STAGE(PG8_SA(0, 0), cA, voffA); PG8_STAGE(PG8_SB(0, 1), cB + hstep, voffB); PG8_STAGE(PG8_SA(0, 1), cA + hstep, voffA);
;         if (wr == 1) PG8_BAR;
;         PG8_WAIT_V(4); PG8_BAR;
;         PG8_STAGE(PG8_SB(1, 0), cB + kstep, voffB); PG8_STAGE(PG8_SA(1, 0), cA + kstep, voffA); PG8_STAGE(PG8_SB(1, 1), cB + hstep + kstep, voffB);
;         PG8_WAIT_V(6); PG8_BAR;
;     }
;     for (;;) {
;         const bool has_next = S.next(ui + 1, nxt);
;         const char* nA = has_next ? (const char*)g.A + (size_t)nxt.pm * tstep : cA; const char* nB = has_next ? (const char*)g.Bt + (size_t)nxt.pn * tstep : cB;
;         for (int t = 0; t < nt; t += 2) {
;             const bool last = (t == nt - 2);
;             const char* a1 = cA + (size_t)(t + 1) * kstep;
;             const char* a2 = last ? nA : cA + (size_t)(t + 2) * kstep; const char* b2 = last ? nB : cB + (size_t)(t + 2) * kstep;
;             const char* a3 = a2 + kstep; const char* b3 = b2 + kstep;
;             if (last && has_next) S.a_ready(nxt);
;             if constexpr (SP2) {
;             PG8_LDB(B0, 0, 0); PG8_LDB(B1, 0, 1); PG8_SCHED; PG8_LDA(At, 0, 0); PG8_STAGE(PG8_SA(1, 1), a1 + hstep, voffA);
;             PG8_WAIT_V(8); PG8_WAIT_L(0); PG8_BAR; PG8_MMA(0, 0, At, B0); PG8_MMA(0, 1, At, B1); PG8_BAR; PG8_SCHED;
;             PG8_LDA(At, 0, 1); PG8_STAGE(PG8_SB(0, 0), b2, voffB); PG8_STAGE(PG8_SB(0, 1), b2 + hstep, voffB); PG8_STAGE(PG8_SA(0, 0), a2, voffA);
.LBB0_698:
	s_lshl_b32 s0, s0, 5
	s_and_b32 s49, s0, 0x60
	s_add_i32 s0, s62, s29
	v_lshl_add_u64 v[2:3], v[26:27], 0, s[14:15]
	s_mov_b32 m0, s0
	s_add_i32 s6, s0, 0x2000
	s_lshl_b32 s33, s28, 13
	s_lshl_b32 s65, s49, 7
	s_waitcnt vmcnt(2)
	s_barrier
	global_load_lds_dwordx4 v[2:3], off
	v_lshl_add_u64 v[4:5], v[28:29], 0, s[14:15]
	s_mov_b32 m0, s6
	s_add_i32 s1, s26, 0x8000
	s_add_i32 s7, s26, 0xa000
	global_load_lds_dwordx4 v[4:5], off
	v_lshl_add_u64 v[0:1], v[20:21], 0, s[14:15]
	s_mov_b32 m0, s1
	s_add_u32 s66, s4, 0x10080
	global_load_lds_dwordx4 v[0:1], off
	v_lshl_add_u64 v[6:7], v[18:19], 0, s[14:15]
	s_mov_b32 m0, s7
	s_addc_u32 s67, s5, 0
	s_add_i32 s19, s63, s29
	global_load_lds_dwordx4 v[6:7], off
	v_lshl_add_u64 v[8:9], s[66:67], 0, v[128:129]
	s_mov_b32 m0, s19
	s_add_i32 s25, s19, 0x2000
	global_load_lds_dwordx4 v[8:9], off
	v_lshl_add_u64 v[10:11], s[66:67], 0, v[16:17]
	s_mov_b32 m0, s25
	v_bfe_u32 v62, v30, 4, 2
	global_load_lds_dwordx4 v[10:11], off
	v_and_b32_e32 v31, 15, v30
	v_lshlrev_b32_e32 v32, 4, v62
	v_lshlrev_b32_e32 v30, 2, v30
	v_lshl_or_b32 v124, s28, 6, v31
	v_lshl_or_b32 v31, v31, 6, v32
	v_and_b32_e32 v30, 32, v30
	v_bitop3_b32 v63, v31, s33, v30 bitop3:0xde
	v_bitop3_b32 v64, v31, s65, v30 bitop3:0xde
	s_add_i32 s33, 0, 0x10000
	s_add_i32 s65, 0, 0x14000
	v_add_u32_e32 v127, s33, v64
	s_waitcnt vmcnt(6)
	s_barrier
	v_add_u32_e32 v126, s65, v64
	ds_read_b128 v[30:33], v127
	ds_read_b128 v[34:37], v127 offset:1024
	ds_read_b128 v[38:41], v127 offset:2048
	ds_read_b128 v[42:45], v127 offset:3072
	ds_read_b128 v[46:49], v126
	ds_read_b128 v[50:53], v126 offset:1024
	ds_read_b128 v[54:57], v126 offset:2048
	ds_read_b128 v[58:61], v126 offset:3072
	v_lshl_or_b32 v125, v62, 2, s49
	v_add_u32_e32 v252, 0, v63
	v_add_u32_e32 v240, s63, v64
	v_add_u32_e32 v241, s62, v64
	s_add_u32 s68, s2, 0x10080
	s_addc_u32 s69, s3, 0
	s_add_i32 s66, s26, 0xc000
	v_lshl_add_u64 v[94:95], s[68:69], 0, v[128:129]
	s_mov_b32 m0, s66
	s_add_i32 s28, s26, 0xe000
	ds_read_b128 v[62:65], v252
	ds_read_b128 v[66:69], v252 offset:1024
	ds_read_b128 v[70:73], v252 offset:2048
	ds_read_b128 v[74:77], v252 offset:3072
	ds_read_b128 v[78:81], v252 offset:4096
	ds_read_b128 v[82:85], v252 offset:5120
	ds_read_b128 v[86:89], v252 offset:6144
	ds_read_b128 v[90:93], v252 offset:7168
	global_load_lds_dwordx4 v[94:95], off
	v_lshl_add_u64 v[94:95], s[68:69], 0, v[16:17]
	s_mov_b32 m0, s28
	s_nop 0
	global_load_lds_dwordx4 v[94:95], off
	s_waitcnt vmcnt(8)
	s_waitcnt lgkmcnt(0)
	s_barrier
	s_setprio 1
	s_waitcnt lgkmcnt(0)
	v_mfma_f32_16x16x32_bf16 v[94:97], v[30:33], v[62:65], 0
	v_mfma_f32_16x16x32_bf16 v[98:101], v[38:41], v[62:65], 0
	v_mfma_f32_16x16x32_bf16 v[102:105], v[30:33], v[70:73], 0
	v_mfma_f32_16x16x32_bf16 v[106:109], v[38:41], v[70:73], 0
	v_mfma_f32_16x16x32_bf16 v[110:113], v[30:33], v[78:81], 0
	v_mfma_f32_16x16x32_bf16 v[114:117], v[38:41], v[78:81], 0
	v_mfma_f32_16x16x32_bf16 v[118:121], v[30:33], v[86:89], 0
	v_mfma_f32_16x16x32_bf16 v[130:133], v[38:41], v[86:89], 0
	v_mfma_f32_16x16x32_bf16 v[94:97], v[34:37], v[66:69], v[94:97]
	v_mfma_f32_16x16x32_bf16 v[98:101], v[42:45], v[66:69], v[98:101]
	v_mfma_f32_16x16x32_bf16 v[102:105], v[34:37], v[74:77], v[102:105]
	v_mfma_f32_16x16x32_bf16 v[106:109], v[42:45], v[74:77], v[106:109]
	v_mfma_f32_16x16x32_bf16 v[110:113], v[34:37], v[82:85], v[110:113]
	v_mfma_f32_16x16x32_bf16 v[114:117], v[42:45], v[82:85], v[114:117]
	v_mfma_f32_16x16x32_bf16 v[118:121], v[34:37], v[90:93], v[118:121]
	v_mfma_f32_16x16x32_bf16 v[130:133], v[42:45], v[90:93], v[130:133]
	s_setprio 0
	s_setprio 1
	v_mfma_f32_16x16x32_bf16 v[136:139], v[46:49], v[62:65], 0
	v_mfma_f32_16x16x32_bf16 v[62:65], v[54:57], v[62:65], 0
	v_mfma_f32_16x16x32_bf16 v[136:139], v[50:53], v[66:69], v[136:139]
	v_mfma_f32_16x16x32_bf16 v[62:65], v[58:61], v[66:69], v[62:65]
	v_mfma_f32_16x16x32_bf16 v[66:69], v[46:49], v[70:73], 0
	v_mfma_f32_16x16x32_bf16 v[70:73], v[54:57], v[70:73], 0
	v_mfma_f32_16x16x32_bf16 v[66:69], v[50:53], v[74:77], v[66:69]
	v_mfma_f32_16x16x32_bf16 v[70:73], v[58:61], v[74:77], v[70:73]
	v_mfma_f32_16x16x32_bf16 v[74:77], v[46:49], v[78:81], 0
	v_mfma_f32_16x16x32_bf16 v[78:81], v[54:57], v[78:81], 0
	v_mfma_f32_16x16x32_bf16 v[74:77], v[50:53], v[82:85], v[74:77]
	v_mfma_f32_16x16x32_bf16 v[78:81], v[58:61], v[82:85], v[78:81]
	v_mfma_f32_16x16x32_bf16 v[82:85], v[46:49], v[86:89], 0
	v_mfma_f32_16x16x32_bf16 v[86:89], v[54:57], v[86:89], 0
	v_mfma_f32_16x16x32_bf16 v[82:85], v[50:53], v[90:93], v[82:85]
	v_mfma_f32_16x16x32_bf16 v[86:89], v[58:61], v[90:93], v[86:89]
	s_setprio 0
	s_barrier
	s_add_i32 s33, s33, s29
	s_add_i32 s49, s33, 0x2000
	v_lshl_add_u64 v[122:123], v[26:27], 0, s[16:17]
	s_mov_b32 m0, s33
	s_add_u32 s68, s4, 0x10100
	ds_read_b128 v[90:93], v252 offset:16384
	ds_read_b128 v[140:143], v252 offset:17408
	ds_read_b128 v[144:147], v252 offset:18432
	ds_read_b128 v[148:151], v252 offset:19456
	ds_read_b128 v[152:155], v252 offset:20480
	ds_read_b128 v[156:159], v252 offset:21504
	ds_read_b128 v[160:163], v252 offset:22528
	ds_read_b128 v[164:167], v252 offset:23552
	global_load_lds_dwordx4 v[122:123], off
	v_lshl_add_u64 v[122:123], v[28:29], 0, s[16:17]
	s_mov_b32 m0, s49
	s_addc_u32 s69, s5, 0
	s_add_i32 s29, s65, s29
	global_load_lds_dwordx4 v[122:123], off
	v_lshl_add_u64 v[122:123], s[68:69], 0, v[128:129]
	s_mov_b32 m0, s29
	s_add_i32 s65, s29, 0x2000
	global_load_lds_dwordx4 v[122:123], off
	v_lshl_add_u64 v[122:123], s[68:69], 0, v[16:17]
	s_mov_b32 m0, s65
	s_nop 0
	global_load_lds_dwordx4 v[122:123], off
	v_lshl_add_u64 v[122:123], v[20:21], 0, s[16:17]
	s_mov_b32 m0, s26
	s_nop 0
	global_load_lds_dwordx4 v[122:123], off
	v_lshl_add_u64 v[122:123], v[18:19], 0, s[16:17]
	s_mov_b32 m0, s27
	s_nop 0
	global_load_lds_dwordx4 v[122:123], off
	s_waitcnt vmcnt(8)
	s_waitcnt lgkmcnt(0)
	s_barrier
; #define PG8_STAGE(bufoff, gbase, voff) do { _Pragma("unroll") for (int _i = 0; _i < 2; ++_i) \
;         __builtin_amdgcn_global_load_lds((const unsigned*)((const char*)(gbase) + (voff)[_i]), (PG8_LAS unsigned*)(lds + (bufoff) + ldsw + _i * 8192), 16, 0, 0); } while (0)
; #define PG8_LDA(dst, b, h) do { _Pragma("unroll") for (int m = 0; m < 4; ++m) _Pragma("unroll") for (int k = 0; k < 2; ++k) dst[m][k] = *(const PG8_LAS bf16x8*)(lds + PG8_SA(b, h) + aoff + m * 2048 + k * 1024); } while (0)
; #define PG8_LDB(dst, b, h) do { _Pragma("unroll") for (int n = 0; n < 2; ++n) _Pragma("unroll") for (int k = 0; k < 2; ++k) dst[n][k] = *(const PG8_LAS bf16x8*)(lds + PG8_SB(b, h) + boff + n * 2048 + k * 1024); } while (0)
; #define PG8_MMA(ai, bj, At, Bt) do { __builtin_amdgcn_s_setprio(1); _Pragma("unroll") for (int m = 0; m < 4; ++m) _Pragma("unroll") for (int n = 0; n < 2; ++n) _Pragma("unroll") for (int k = 0; k < 2; ++k) \
;         acc[ai][bj][m][n] = __builtin_amdgcn_mfma_f32_16x16x32_bf16(Bt[n][k], At[m][k], acc[ai][bj][m][n], 0, 0, 0); __builtin_amdgcn_s_setprio(0); } while (0)
; #define PG8_BAR __builtin_amdgcn_s_barrier()
; template <class Epi, class Sched, bool ALIGN_EPI = false, bool SP2 = false>
; __device__ __forceinline__ void gemm_phase(PG8_LAS unsigned char* lds, const Gemm g, const Sched& S, const Epi& E, int tid_in) {
;     ...
;             PG8_LDB(B0, 0, 0); PG8_LDB(B1, 0, 1); PG8_SCHED; PG8_LDA(At, 0, 0); PG8_STAGE(PG8_SA(1, 1), a1 + hstep, voffA);
;             PG8_WAIT_V(8); PG8_WAIT_L(0); PG8_BAR; PG8_MMA(0, 0, At, B0); PG8_MMA(0, 1, At, B1); PG8_BAR; PG8_SCHED;
;             PG8_LDA(At, 0, 1); PG8_STAGE(PG8_SB(0, 0), b2, voffB); PG8_STAGE(PG8_SB(0, 1), b2 + hstep, voffB); PG8_STAGE(PG8_SA(0, 0), a2, voffA);
;             PG8_WAIT_V(8); PG8_WAIT_L(0); PG8_BAR; PG8_MMA(1, 0, At, B0); PG8_MMA(1, 1, At, B1); PG8_BAR; PG8_SCHED;
;             PG8_LDB(B0, 1, 0); PG8_LDB(B1, 1, 1); PG8_SCHED; PG8_LDA(At, 1, 0); PG8_STAGE(PG8_SA(0, 1), a2 + hstep, voffA);
;             PG8_WAIT_V(8); PG8_WAIT_L(0); PG8_BAR; PG8_MMA(0, 0, At, B0); PG8_MMA(0, 1, At, B1); PG8_BAR; PG8_SCHED;
;             PG8_LDA(At, 1, 1); PG8_STAGE(PG8_SB(1, 0), b3, voffB); PG8_STAGE(PG8_SB(1, 1), b3 + hstep, voffB); PG8_STAGE(PG8_SA(1, 0), a3, voffA);
;             PG8_WAIT_V(8); PG8_WAIT_L(0); PG8_BAR; PG8_MMA(1, 0, At, B0); PG8_MMA(1, 1, At, B1); PG8_BAR; PG8_SCHED;
	s_setprio 1
	s_waitcnt lgkmcnt(0)
	v_mfma_f32_16x16x32_bf16 v[168:171], v[30:33], v[90:93], 0
	v_mfma_f32_16x16x32_bf16 v[176:179], v[30:33], v[144:147], 0
	v_mfma_f32_16x16x32_bf16 v[184:187], v[30:33], v[152:155], 0
	v_mfma_f32_16x16x32_bf16 v[30:33], v[30:33], v[160:163], 0
	v_mfma_f32_16x16x32_bf16 v[168:171], v[34:37], v[140:143], v[168:171]
	v_mfma_f32_16x16x32_bf16 v[172:175], v[38:41], v[90:93], 0
	v_mfma_f32_16x16x32_bf16 v[176:179], v[34:37], v[148:151], v[176:179]
	v_mfma_f32_16x16x32_bf16 v[180:183], v[38:41], v[144:147], 0
	v_mfma_f32_16x16x32_bf16 v[184:187], v[34:37], v[156:159], v[184:187]
	v_mfma_f32_16x16x32_bf16 v[188:191], v[38:41], v[152:155], 0
	v_mfma_f32_16x16x32_bf16 v[30:33], v[34:37], v[164:167], v[30:33]
	v_mfma_f32_16x16x32_bf16 v[34:37], v[38:41], v[160:163], 0
	v_mfma_f32_16x16x32_bf16 v[172:175], v[42:45], v[140:143], v[172:175]
	v_mfma_f32_16x16x32_bf16 v[180:183], v[42:45], v[148:151], v[180:183]
	v_mfma_f32_16x16x32_bf16 v[188:191], v[42:45], v[156:159], v[188:191]
	v_mfma_f32_16x16x32_bf16 v[34:37], v[42:45], v[164:167], v[34:37]
	s_setprio 0
	s_setprio 1
	v_mfma_f32_16x16x32_bf16 v[38:41], v[46:49], v[90:93], 0
	v_mfma_f32_16x16x32_bf16 v[42:45], v[54:57], v[90:93], 0
	v_mfma_f32_16x16x32_bf16 v[38:41], v[50:53], v[140:143], v[38:41]
	v_mfma_f32_16x16x32_bf16 v[42:45], v[58:61], v[140:143], v[42:45]
	v_mfma_f32_16x16x32_bf16 v[90:93], v[46:49], v[144:147], 0
	v_mfma_f32_16x16x32_bf16 v[140:143], v[54:57], v[144:147], 0
	v_mfma_f32_16x16x32_bf16 v[144:147], v[46:49], v[152:155], 0
	v_mfma_f32_16x16x32_bf16 v[46:49], v[46:49], v[160:163], 0
	v_mfma_f32_16x16x32_bf16 v[90:93], v[50:53], v[148:151], v[90:93]
	v_mfma_f32_16x16x32_bf16 v[140:143], v[58:61], v[148:151], v[140:143]
	v_mfma_f32_16x16x32_bf16 v[144:147], v[50:53], v[156:159], v[144:147]
	v_mfma_f32_16x16x32_bf16 v[148:151], v[54:57], v[152:155], 0
	v_mfma_f32_16x16x32_bf16 v[46:49], v[50:53], v[164:167], v[46:49]
	v_mfma_f32_16x16x32_bf16 v[50:53], v[54:57], v[160:163], 0
	v_mfma_f32_16x16x32_bf16 v[148:151], v[58:61], v[156:159], v[148:151]
	v_mfma_f32_16x16x32_bf16 v[50:53], v[58:61], v[164:167], v[50:53]
	s_setprio 0
	s_barrier
	ds_read_b128 v[54:57], v241
	ds_read_b128 v[58:61], v241 offset:1024
	ds_read_b128 v[152:155], v241 offset:2048
	ds_read_b128 v[156:159], v241 offset:3072
	ds_read_b128 v[160:163], v240
	ds_read_b128 v[164:167], v240 offset:1024
	ds_read_b128 v[192:195], v240 offset:2048
	ds_read_b128 v[196:199], v240 offset:3072
	s_add_u32 s68, s2, 0x10100
	s_addc_u32 s69, s3, 0
	s_mov_b32 m0, s18
	v_lshl_add_u64 v[122:123], s[68:69], 0, v[128:129]
	ds_read_b128 v[200:203], v252 offset:32768
	ds_read_b128 v[204:207], v252 offset:33792
	ds_read_b128 v[208:211], v252 offset:34816
	ds_read_b128 v[212:215], v252 offset:35840
	ds_read_b128 v[216:219], v252 offset:36864
	ds_read_b128 v[220:223], v252 offset:37888
	ds_read_b128 v[224:227], v252 offset:38912
	ds_read_b128 v[228:231], v252 offset:39936
	global_load_lds_dwordx4 v[122:123], off
	v_lshl_add_u64 v[122:123], s[68:69], 0, v[16:17]
	s_mov_b32 m0, s24
	s_nop 0
	global_load_lds_dwordx4 v[122:123], off
	s_waitcnt vmcnt(8)
	s_waitcnt lgkmcnt(0)
	s_barrier
	s_setprio 1
	s_waitcnt lgkmcnt(0)
	v_mfma_f32_16x16x32_bf16 v[94:97], v[54:57], v[200:203], v[94:97]
	v_mfma_f32_16x16x32_bf16 v[98:101], v[152:155], v[200:203], v[98:101]
	v_mfma_f32_16x16x32_bf16 v[102:105], v[54:57], v[208:211], v[102:105]
	v_mfma_f32_16x16x32_bf16 v[106:109], v[152:155], v[208:211], v[106:109]
	v_mfma_f32_16x16x32_bf16 v[110:113], v[54:57], v[216:219], v[110:113]
	v_mfma_f32_16x16x32_bf16 v[114:117], v[152:155], v[216:219], v[114:117]
	v_mfma_f32_16x16x32_bf16 v[118:121], v[54:57], v[224:227], v[118:121]
	v_mfma_f32_16x16x32_bf16 v[130:133], v[152:155], v[224:227], v[130:133]
	v_mfma_f32_16x16x32_bf16 v[94:97], v[58:61], v[204:207], v[94:97]
	v_mfma_f32_16x16x32_bf16 v[98:101], v[156:159], v[204:207], v[98:101]
	v_mfma_f32_16x16x32_bf16 v[102:105], v[58:61], v[212:215], v[102:105]
	v_mfma_f32_16x16x32_bf16 v[106:109], v[156:159], v[212:215], v[106:109]
	v_mfma_f32_16x16x32_bf16 v[110:113], v[58:61], v[220:223], v[110:113]
	v_mfma_f32_16x16x32_bf16 v[114:117], v[156:159], v[220:223], v[114:117]
	v_mfma_f32_16x16x32_bf16 v[118:121], v[58:61], v[228:231], v[118:121]
	v_mfma_f32_16x16x32_bf16 v[130:133], v[156:159], v[228:231], v[130:133]
	s_setprio 0
	s_setprio 1
	v_mfma_f32_16x16x32_bf16 v[136:139], v[160:163], v[200:203], v[136:139]
	v_mfma_f32_16x16x32_bf16 v[62:65], v[192:195], v[200:203], v[62:65]
	v_mfma_f32_16x16x32_bf16 v[66:69], v[160:163], v[208:211], v[66:69]
	v_mfma_f32_16x16x32_bf16 v[70:73], v[192:195], v[208:211], v[70:73]
	v_mfma_f32_16x16x32_bf16 v[74:77], v[160:163], v[216:219], v[74:77]
	v_mfma_f32_16x16x32_bf16 v[78:81], v[192:195], v[216:219], v[78:81]
	v_mfma_f32_16x16x32_bf16 v[82:85], v[160:163], v[224:227], v[82:85]
	v_mfma_f32_16x16x32_bf16 v[86:89], v[192:195], v[224:227], v[86:89]
	v_mfma_f32_16x16x32_bf16 v[136:139], v[164:167], v[204:207], v[136:139]
	v_mfma_f32_16x16x32_bf16 v[62:65], v[196:199], v[204:207], v[62:65]
	v_mfma_f32_16x16x32_bf16 v[66:69], v[164:167], v[212:215], v[66:69]
	v_mfma_f32_16x16x32_bf16 v[70:73], v[196:199], v[212:215], v[70:73]
	v_mfma_f32_16x16x32_bf16 v[74:77], v[164:167], v[220:223], v[74:77]
	v_mfma_f32_16x16x32_bf16 v[78:81], v[196:199], v[220:223], v[78:81]
	v_mfma_f32_16x16x32_bf16 v[82:85], v[164:167], v[228:231], v[82:85]
	v_mfma_f32_16x16x32_bf16 v[86:89], v[196:199], v[228:231], v[86:89]
	s_setprio 0
	s_barrier
; #define PG8_STAGE(bufoff, gbase, voff) do { _Pragma("unroll") for (int _i = 0; _i < 2; ++_i) \
;         __builtin_amdgcn_global_load_lds((const unsigned*)((const char*)(gbase) + (voff)[_i]), (PG8_LAS unsigned*)(lds + (bufoff) + ldsw + _i * 8192), 16, 0, 0); } while (0)
; #define PG8_LDA(dst, b, h) do { _Pragma("unroll") for (int m = 0; m < 4; ++m) _Pragma("unroll") for (int k = 0; k < 2; ++k) dst[m][k] = *(const PG8_LAS bf16x8*)(lds + PG8_SA(b, h) + aoff + m * 2048 + k * 1024); } while (0)
; #define PG8_LDB(dst, b, h) do { _Pragma("unroll") for (int n = 0; n < 2; ++n) _Pragma("unroll") for (int k = 0; k < 2; ++k) dst[n][k] = *(const PG8_LAS bf16x8*)(lds + PG8_SB(b, h) + boff + n * 2048 + k * 1024); } while (0)
; #define PG8_MMA(ai, bj, At, Bt) do { __builtin_amdgcn_s_setprio(1); _Pragma("unroll") for (int m = 0; m < 4; ++m) _Pragma("unroll") for (int n = 0; n < 2; ++n) _Pragma("unroll") for (int k = 0; k < 2; ++k) \
;         acc[ai][bj][m][n] = __builtin_amdgcn_mfma_f32_16x16x32_bf16(Bt[n][k], At[m][k], acc[ai][bj][m][n], 0, 0, 0); __builtin_amdgcn_s_setprio(0); } while (0)
; #define PG8_BAR __builtin_amdgcn_s_barrier()
; template <class Epi, class Sched, bool ALIGN_EPI = false, bool SP2 = false>
; __device__ __forceinline__ void gemm_phase(PG8_LAS unsigned char* lds, const Gemm g, const Sched& S, const Epi& E, int tid_in) {
;     ...
;             PG8_LDB(B0, 0, 0); PG8_LDB(B1, 0, 1); PG8_SCHED; PG8_LDA(At, 0, 0); PG8_STAGE(PG8_SA(1, 1), a1 + hstep, voffA);
;             PG8_WAIT_V(8); PG8_WAIT_L(0); PG8_BAR; PG8_MMA(0, 0, At, B0); PG8_MMA(0, 1, At, B1); PG8_BAR; PG8_SCHED;
;             PG8_LDA(At, 0, 1); PG8_STAGE(PG8_SB(0, 0), b2, voffB); PG8_STAGE(PG8_SB(0, 1), b2 + hstep, voffB); PG8_STAGE(PG8_SA(0, 0), a2, voffA);
;             PG8_WAIT_V(8); PG8_WAIT_L(0); PG8_BAR; PG8_MMA(1, 0, At, B0); PG8_MMA(1, 1, At, B1); PG8_BAR; PG8_SCHED;
;             PG8_LDB(B0, 1, 0); PG8_LDB(B1, 1, 1); PG8_SCHED; PG8_LDA(At, 1, 0); PG8_STAGE(PG8_SA(0, 1), a2 + hstep, voffA);
;             PG8_WAIT_V(8); PG8_WAIT_L(0); PG8_BAR; PG8_MMA(0, 0, At, B0); PG8_MMA(0, 1, At, B1); PG8_BAR; PG8_SCHED;
;             PG8_LDA(At, 1, 1); PG8_STAGE(PG8_SB(1, 0), b3, voffB); PG8_STAGE(PG8_SB(1, 1), b3 + hstep, voffB); PG8_STAGE(PG8_SA(1, 0), a3, voffA);
;             PG8_WAIT_V(8); PG8_WAIT_L(0); PG8_BAR; PG8_MMA(1, 0, At, B0); PG8_MMA(1, 1, At, B1); PG8_BAR; PG8_SCHED;
	s_mov_b32 m0, s0
	v_lshl_add_u64 v[122:123], v[26:27], 0, s[30:31]
	s_add_u32 s4, s4, 0x10180
	ds_read_b128 v[200:203], v252 offset:49152
	ds_read_b128 v[204:207], v252 offset:50176
	ds_read_b128 v[208:211], v252 offset:51200
	ds_read_b128 v[212:215], v252 offset:52224
	ds_read_b128 v[216:219], v252 offset:53248
	ds_read_b128 v[220:223], v252 offset:54272
	ds_read_b128 v[224:227], v252 offset:55296
	ds_read_b128 v[228:231], v252 offset:56320
	global_load_lds_dwordx4 v[122:123], off
	v_lshl_add_u64 v[122:123], v[28:29], 0, s[30:31]
	s_mov_b32 m0, s6
	s_addc_u32 s5, s5, 0
	global_load_lds_dwordx4 v[122:123], off
	v_lshl_add_u64 v[122:123], s[4:5], 0, v[128:129]
	s_mov_b32 m0, s19
	s_nop 0
	global_load_lds_dwordx4 v[122:123], off
	v_lshl_add_u64 v[122:123], s[4:5], 0, v[16:17]
	s_mov_b32 m0, s25
	s_nop 0
	global_load_lds_dwordx4 v[122:123], off
	v_lshl_add_u64 v[122:123], v[20:21], 0, s[30:31]
	s_mov_b32 m0, s1
	s_nop 0
	global_load_lds_dwordx4 v[122:123], off
	v_lshl_add_u64 v[122:123], v[18:19], 0, s[30:31]
	s_mov_b32 m0, s7
	s_nop 0
	global_load_lds_dwordx4 v[122:123], off
	s_waitcnt vmcnt(8)
	s_waitcnt lgkmcnt(0)
	s_barrier
	s_setprio 1
	s_waitcnt lgkmcnt(0)
	v_mfma_f32_16x16x32_bf16 v[168:171], v[54:57], v[200:203], v[168:171]
	v_mfma_f32_16x16x32_bf16 v[172:175], v[152:155], v[200:203], v[172:175]
	v_mfma_f32_16x16x32_bf16 v[176:179], v[54:57], v[208:211], v[176:179]
	v_mfma_f32_16x16x32_bf16 v[180:183], v[152:155], v[208:211], v[180:183]
	v_mfma_f32_16x16x32_bf16 v[184:187], v[54:57], v[216:219], v[184:187]
	v_mfma_f32_16x16x32_bf16 v[188:191], v[152:155], v[216:219], v[188:191]
	v_mfma_f32_16x16x32_bf16 v[30:33], v[54:57], v[224:227], v[30:33]
	v_mfma_f32_16x16x32_bf16 v[34:37], v[152:155], v[224:227], v[34:37]
	v_mfma_f32_16x16x32_bf16 v[168:171], v[58:61], v[204:207], v[168:171]
	v_mfma_f32_16x16x32_bf16 v[172:175], v[156:159], v[204:207], v[172:175]
	v_mfma_f32_16x16x32_bf16 v[176:179], v[58:61], v[212:215], v[176:179]
	v_mfma_f32_16x16x32_bf16 v[180:183], v[156:159], v[212:215], v[180:183]
	v_mfma_f32_16x16x32_bf16 v[184:187], v[58:61], v[220:223], v[184:187]
	v_mfma_f32_16x16x32_bf16 v[188:191], v[156:159], v[220:223], v[188:191]
	v_mfma_f32_16x16x32_bf16 v[30:33], v[58:61], v[228:231], v[30:33]
	v_mfma_f32_16x16x32_bf16 v[34:37], v[156:159], v[228:231], v[34:37]
	s_setprio 0
	s_setprio 1
	v_mfma_f32_16x16x32_bf16 v[38:41], v[160:163], v[200:203], v[38:41]
	v_mfma_f32_16x16x32_bf16 v[42:45], v[192:195], v[200:203], v[42:45]
	v_mfma_f32_16x16x32_bf16 v[54:57], v[160:163], v[208:211], v[90:93]
	v_mfma_f32_16x16x32_bf16 v[58:61], v[192:195], v[208:211], v[140:143]
	v_mfma_f32_16x16x32_bf16 v[90:93], v[160:163], v[216:219], v[144:147]
	v_mfma_f32_16x16x32_bf16 v[140:143], v[192:195], v[216:219], v[148:151]
	v_mfma_f32_16x16x32_bf16 v[46:49], v[160:163], v[224:227], v[46:49]
	v_mfma_f32_16x16x32_bf16 v[50:53], v[192:195], v[224:227], v[50:53]
	v_mfma_f32_16x16x32_bf16 v[38:41], v[164:167], v[204:207], v[38:41]
	v_mfma_f32_16x16x32_bf16 v[42:45], v[196:199], v[204:207], v[42:45]
	v_mfma_f32_16x16x32_bf16 v[54:57], v[164:167], v[212:215], v[54:57]
	v_mfma_f32_16x16x32_bf16 v[58:61], v[196:199], v[212:215], v[58:61]
	v_mfma_f32_16x16x32_bf16 v[90:93], v[164:167], v[220:223], v[90:93]
	v_mfma_f32_16x16x32_bf16 v[140:143], v[196:199], v[220:223], v[140:143]
	v_mfma_f32_16x16x32_bf16 v[46:49], v[164:167], v[228:231], v[46:49]
	v_mfma_f32_16x16x32_bf16 v[50:53], v[196:199], v[228:231], v[50:53]
	s_setprio 0
	s_barrier
	ds_read_b128 v[144:147], v127
	ds_read_b128 v[148:151], v127 offset:1024
	ds_read_b128 v[152:155], v127 offset:2048
	ds_read_b128 v[156:159], v127 offset:3072
	ds_read_b128 v[160:163], v126
	ds_read_b128 v[164:167], v126 offset:1024
	ds_read_b128 v[192:195], v126 offset:2048
	ds_read_b128 v[196:199], v126 offset:3072
	s_add_u32 s2, s2, 0x10180
	s_addc_u32 s3, s3, 0
	s_mov_b32 m0, s66
	v_lshl_add_u64 v[122:123], s[2:3], 0, v[128:129]
	ds_read_b128 v[200:203], v252
	ds_read_b128 v[204:207], v252 offset:1024
	ds_read_b128 v[208:211], v252 offset:2048
	ds_read_b128 v[212:215], v252 offset:3072
	ds_read_b128 v[216:219], v252 offset:4096
	ds_read_b128 v[220:223], v252 offset:5120
	ds_read_b128 v[224:227], v252 offset:6144
	ds_read_b128 v[228:231], v252 offset:7168
	global_load_lds_dwordx4 v[122:123], off
	v_lshl_add_u64 v[16:17], s[2:3], 0, v[16:17]
	s_mov_b32 m0, s28
	s_nop 0
	global_load_lds_dwordx4 v[16:17], off
	s_waitcnt vmcnt(8)
	s_waitcnt lgkmcnt(0)
	s_barrier
	s_setprio 1
	s_waitcnt lgkmcnt(0)
	v_mfma_f32_16x16x32_bf16 v[106:109], v[152:155], v[208:211], v[106:109]
	v_mfma_f32_16x16x32_bf16 v[232:235], v[156:159], v[212:215], v[106:109]
	v_mfma_f32_16x16x32_bf16 v[106:109], v[144:147], v[216:219], v[110:113]
	v_mfma_f32_16x16x32_bf16 v[236:239], v[148:151], v[220:223], v[106:109]
	v_mfma_f32_16x16x32_bf16 v[106:109], v[152:155], v[216:219], v[114:117]
	v_mfma_f32_16x16x32_bf16 v[112:115], v[156:159], v[220:223], v[106:109]
	v_mfma_f32_16x16x32_bf16 v[106:109], v[144:147], v[224:227], v[118:121]
	v_mfma_f32_16x16x32_bf16 v[94:97], v[144:147], v[200:203], v[94:97]
	v_mfma_f32_16x16x32_bf16 v[98:101], v[152:155], v[200:203], v[98:101]
	v_mfma_f32_16x16x32_bf16 v[102:105], v[144:147], v[208:211], v[102:105]
	v_mfma_f32_16x16x32_bf16 v[116:119], v[148:151], v[228:231], v[106:109]
	v_mfma_f32_16x16x32_bf16 v[106:109], v[152:155], v[224:227], v[130:133]
	v_mfma_f32_16x16x32_bf16 v[94:97], v[148:151], v[204:207], v[94:97]
	v_mfma_f32_16x16x32_bf16 v[98:101], v[156:159], v[204:207], v[98:101]
	v_mfma_f32_16x16x32_bf16 v[102:105], v[148:151], v[212:215], v[102:105]
	v_mfma_f32_16x16x32_bf16 v[130:133], v[156:159], v[228:231], v[106:109]
	s_setprio 0
	s_setprio 1
	v_mfma_f32_16x16x32_bf16 v[70:73], v[192:195], v[208:211], v[70:73]
	v_mfma_f32_16x16x32_bf16 v[106:109], v[160:163], v[200:203], v[136:139]
	v_mfma_f32_16x16x32_bf16 v[62:65], v[192:195], v[200:203], v[62:65]
	v_mfma_f32_16x16x32_bf16 v[200:203], v[196:199], v[212:215], v[70:73]
	v_mfma_f32_16x16x32_bf16 v[70:73], v[160:163], v[216:219], v[74:77]
	v_mfma_f32_16x16x32_bf16 v[136:139], v[164:167], v[204:207], v[106:109]
	v_mfma_f32_16x16x32_bf16 v[62:65], v[196:199], v[204:207], v[62:65]
	v_mfma_f32_16x16x32_bf16 v[204:207], v[164:167], v[220:223], v[70:73]
	v_mfma_f32_16x16x32_bf16 v[70:73], v[192:195], v[216:219], v[78:81]
	v_mfma_f32_16x16x32_bf16 v[66:69], v[160:163], v[208:211], v[66:69]
	v_mfma_f32_16x16x32_bf16 v[208:211], v[196:199], v[220:223], v[70:73]
	v_mfma_f32_16x16x32_bf16 v[70:73], v[160:163], v[224:227], v[82:85]
	v_mfma_f32_16x16x32_bf16 v[66:69], v[164:167], v[212:215], v[66:69]
	v_mfma_f32_16x16x32_bf16 v[212:215], v[164:167], v[228:231], v[70:73]
	v_mfma_f32_16x16x32_bf16 v[70:73], v[192:195], v[224:227], v[86:89]
	v_mfma_f32_16x16x32_bf16 v[216:219], v[196:199], v[228:231], v[70:73]
	s_setprio 0
	s_barrier
; #define PG8_STAGE(bufoff, gbase, voff) do { _Pragma("unroll") for (int _i = 0; _i < 2; ++_i) \
;         __builtin_amdgcn_global_load_lds((const unsigned*)((const char*)(gbase) + (voff)[_i]), (PG8_LAS unsigned*)(lds + (bufoff) + ldsw + _i * 8192), 16, 0, 0); } while (0)
; #define PG8_LDA(dst, b, h) do { _Pragma("unroll") for (int m = 0; m < 4; ++m) _Pragma("unroll") for (int k = 0; k < 2; ++k) dst[m][k] = *(const PG8_LAS bf16x8*)(lds + PG8_SA(b, h) + aoff + m * 2048 + k * 1024); } while (0)
; #define PG8_LDB(dst, b, h) do { _Pragma("unroll") for (int n = 0; n < 2; ++n) _Pragma("unroll") for (int k = 0; k < 2; ++k) dst[n][k] = *(const PG8_LAS bf16x8*)(lds + PG8_SB(b, h) + boff + n * 2048 + k * 1024); } while (0)
; #define PG8_MMA(ai, bj, At, Bt) do { __builtin_amdgcn_s_setprio(1); _Pragma("unroll") for (int m = 0; m < 4; ++m) _Pragma("unroll") for (int n = 0; n < 2; ++n) _Pragma("unroll") for (int k = 0; k < 2; ++k) \
;         acc[ai][bj][m][n] = __builtin_amdgcn_mfma_f32_16x16x32_bf16(Bt[n][k], At[m][k], acc[ai][bj][m][n], 0, 0, 0); __builtin_amdgcn_s_setprio(0); } while (0)
; #define PG8_BAR __builtin_amdgcn_s_barrier()
; template <class Epi, class Sched, bool ALIGN_EPI = false, bool SP2 = false>
; __device__ __forceinline__ void gemm_phase(PG8_LAS unsigned char* lds, const Gemm g, const Sched& S, const Epi& E, int tid_in) {
;     ...
;             PG8_LDB(B0, 0, 0); PG8_LDB(B1, 0, 1); PG8_SCHED; PG8_LDA(At, 0, 0); PG8_STAGE(PG8_SA(1, 1), a1 + hstep, voffA);
;             PG8_WAIT_V(8); PG8_WAIT_L(0); PG8_BAR; PG8_MMA(0, 0, At, B0); PG8_MMA(0, 1, At, B1); PG8_BAR; PG8_SCHED;
;             PG8_LDA(At, 0, 1); PG8_STAGE(PG8_SB(0, 0), b2, voffB); PG8_STAGE(PG8_SB(0, 1), b2 + hstep, voffB); PG8_STAGE(PG8_SA(0, 0), a2, voffA);
;             PG8_WAIT_V(8); PG8_WAIT_L(0); PG8_BAR; PG8_MMA(1, 0, At, B0); PG8_MMA(1, 1, At, B1); PG8_BAR; PG8_SCHED;
;             PG8_LDB(B0, 1, 0); PG8_LDB(B1, 1, 1); PG8_SCHED; PG8_LDA(At, 1, 0); PG8_STAGE(PG8_SA(0, 1), a2 + hstep, voffA);
;             PG8_WAIT_V(8); PG8_WAIT_L(0); PG8_BAR; PG8_MMA(0, 0, At, B0); PG8_MMA(0, 1, At, B1); PG8_BAR; PG8_SCHED;
;             PG8_LDA(At, 1, 1); PG8_STAGE(PG8_SB(1, 0), b3, voffB); PG8_STAGE(PG8_SB(1, 1), b3 + hstep, voffB); PG8_STAGE(PG8_SA(1, 0), a3, voffA);
;             PG8_WAIT_V(8); PG8_WAIT_L(0); PG8_BAR; PG8_MMA(1, 0, At, B0); PG8_MMA(1, 1, At, B1); PG8_BAR; PG8_SCHED;
	s_mov_b32 m0, s33
	s_nop 3
	ds_read_b128 v[70:73], v252 offset:16384
	ds_read_b128 v[74:77], v252 offset:17408
	ds_read_b128 v[78:81], v252 offset:18432
	ds_read_b128 v[82:85], v252 offset:19456
	ds_read_b128 v[86:89], v252 offset:20480
	ds_read_b128 v[106:109], v252 offset:21504
	ds_read_b128 v[120:123], v252 offset:22528
	ds_read_b128 v[220:223], v252 offset:23552
	global_load_lds_dwordx4 v[26:27], off
	s_mov_b32 m0, s49
	s_nop 0
	global_load_lds_dwordx4 v[28:29], off
	s_mov_b32 m0, s29
	s_nop 0
	global_load_lds_dwordx4 v[24:25], off
	s_mov_b32 m0, s65
	s_nop 0
	global_load_lds_dwordx4 v[22:23], off
	s_mov_b32 m0, s26
	s_nop 0
	global_load_lds_dwordx4 v[20:21], off
	s_mov_b32 m0, s27
	s_nop 0
	global_load_lds_dwordx4 v[18:19], off
	s_waitcnt vmcnt(8)
	s_waitcnt lgkmcnt(0)
	s_barrier
	s_setprio 1
	s_waitcnt lgkmcnt(0)
	v_mfma_f32_16x16x32_bf16 v[28:31], v[144:147], v[120:123], v[30:33]
	v_mfma_f32_16x16x32_bf16 v[16:19], v[144:147], v[70:73], v[168:171]
	v_mfma_f32_16x16x32_bf16 v[20:23], v[152:155], v[70:73], v[172:175]
	v_mfma_f32_16x16x32_bf16 v[24:27], v[144:147], v[78:81], v[176:179]
	v_mfma_f32_16x16x32_bf16 v[168:171], v[152:155], v[78:81], v[180:183]
	v_mfma_f32_16x16x32_bf16 v[172:175], v[144:147], v[86:89], v[184:187]
	v_mfma_f32_16x16x32_bf16 v[176:179], v[152:155], v[86:89], v[188:191]
	v_mfma_f32_16x16x32_bf16 v[144:147], v[148:151], v[220:223], v[28:31]
	v_mfma_f32_16x16x32_bf16 v[28:31], v[152:155], v[120:123], v[34:37]
	v_mfma_f32_16x16x32_bf16 v[16:19], v[148:151], v[74:77], v[16:19]
	v_mfma_f32_16x16x32_bf16 v[20:23], v[156:159], v[74:77], v[20:23]
	v_mfma_f32_16x16x32_bf16 v[24:27], v[148:151], v[82:85], v[24:27]
	v_mfma_f32_16x16x32_bf16 v[168:171], v[156:159], v[82:85], v[168:171]
	v_mfma_f32_16x16x32_bf16 v[172:175], v[148:151], v[106:109], v[172:175]
	v_mfma_f32_16x16x32_bf16 v[176:179], v[156:159], v[106:109], v[176:179]
	v_mfma_f32_16x16x32_bf16 v[32:35], v[156:159], v[220:223], v[28:31]
	s_setprio 0
	s_setprio 1
	v_mfma_f32_16x16x32_bf16 v[28:31], v[160:163], v[70:73], v[38:41]
	v_mfma_f32_16x16x32_bf16 v[36:39], v[164:167], v[74:77], v[28:31]
	v_mfma_f32_16x16x32_bf16 v[28:31], v[192:195], v[70:73], v[42:45]
	v_mfma_f32_16x16x32_bf16 v[148:151], v[196:199], v[74:77], v[28:31]
	v_mfma_f32_16x16x32_bf16 v[28:31], v[160:163], v[78:81], v[54:57]
	v_mfma_f32_16x16x32_bf16 v[152:155], v[164:167], v[82:85], v[28:31]
	v_mfma_f32_16x16x32_bf16 v[28:31], v[192:195], v[78:81], v[58:61]
	v_mfma_f32_16x16x32_bf16 v[156:159], v[196:199], v[82:85], v[28:31]
	v_mfma_f32_16x16x32_bf16 v[28:31], v[160:163], v[86:89], v[90:93]
	v_mfma_f32_16x16x32_bf16 v[180:183], v[164:167], v[106:109], v[28:31]
	v_mfma_f32_16x16x32_bf16 v[28:31], v[192:195], v[86:89], v[140:143]
	v_mfma_f32_16x16x32_bf16 v[140:143], v[196:199], v[106:109], v[28:31]
	v_mfma_f32_16x16x32_bf16 v[28:31], v[160:163], v[120:123], v[46:49]
	v_mfma_f32_16x16x32_bf16 v[160:163], v[164:167], v[220:223], v[28:31]
	v_mfma_f32_16x16x32_bf16 v[28:31], v[192:195], v[120:123], v[50:53]
	v_mfma_f32_16x16x32_bf16 v[164:167], v[196:199], v[220:223], v[28:31]
	s_setprio 0
	s_barrier
	ds_read_b128 v[48:51], v241
	ds_read_b128 v[52:55], v241 offset:1024
	ds_read_b128 v[184:187], v241 offset:2048
	ds_read_b128 v[188:191], v241 offset:3072
	ds_read_b128 v[192:195], v240
	ds_read_b128 v[196:199], v240 offset:1024
	ds_read_b128 v[220:223], v240 offset:2048
	ds_read_b128 v[224:227], v240 offset:3072
	s_mov_b32 m0, s18
	ds_read_b128 v[28:31], v252 offset:32768
	ds_read_b128 v[40:43], v252 offset:33792
	ds_read_b128 v[44:47], v252 offset:34816
	ds_read_b128 v[56:59], v252 offset:35840
	ds_read_b128 v[80:83], v252 offset:36864
	ds_read_b128 v[228:231], v252 offset:37888
	ds_read_b128 v[240:243], v252 offset:38912
	ds_read_b128 v[244:247], v252 offset:39936
	global_load_lds_dwordx4 v[12:13], off
	s_mov_b32 m0, s24
	s_nop 0
	global_load_lds_dwordx4 v[14:15], off
	s_waitcnt vmcnt(8)
	s_waitcnt lgkmcnt(0)
	s_barrier
	s_setprio 1
	s_waitcnt lgkmcnt(0)
	v_mfma_f32_16x16x32_bf16 v[12:15], v[48:51], v[28:31], v[94:97]
	v_mfma_f32_16x16x32_bf16 v[248:251], v[52:55], v[40:43], v[12:15]
	v_mfma_f32_16x16x32_bf16 v[12:15], v[184:187], v[28:31], v[98:101]
	v_mfma_f32_16x16x32_bf16 v[120:123], v[188:191], v[40:43], v[12:15]
	v_mfma_f32_16x16x32_bf16 v[12:15], v[48:51], v[44:47], v[102:105]
	v_mfma_f32_16x16x32_bf16 v[108:111], v[52:55], v[56:59], v[12:15]
	v_mfma_f32_16x16x32_bf16 v[12:15], v[184:187], v[44:47], v[232:235]
	v_mfma_f32_16x16x32_bf16 v[104:107], v[188:191], v[56:59], v[12:15]
	v_mfma_f32_16x16x32_bf16 v[12:15], v[48:51], v[80:83], v[236:239]
	v_mfma_f32_16x16x32_bf16 v[92:95], v[52:55], v[228:231], v[12:15]
	v_mfma_f32_16x16x32_bf16 v[12:15], v[184:187], v[80:83], v[112:115]
	v_mfma_f32_16x16x32_bf16 v[88:91], v[188:191], v[228:231], v[12:15]
	v_mfma_f32_16x16x32_bf16 v[12:15], v[48:51], v[240:243], v[116:119]
	v_mfma_f32_16x16x32_bf16 v[76:79], v[52:55], v[244:247], v[12:15]
	v_mfma_f32_16x16x32_bf16 v[12:15], v[184:187], v[240:243], v[130:133]
	v_mfma_f32_16x16x32_bf16 v[72:75], v[188:191], v[244:247], v[12:15]
	s_setprio 0
	s_setprio 1
	v_mfma_f32_16x16x32_bf16 v[12:15], v[192:195], v[28:31], v[136:139]
	v_mfma_f32_16x16x32_bf16 v[116:119], v[196:199], v[40:43], v[12:15]
	v_mfma_f32_16x16x32_bf16 v[12:15], v[220:223], v[28:31], v[62:65]
	v_mfma_f32_16x16x32_bf16 v[112:115], v[224:227], v[40:43], v[12:15]
	v_mfma_f32_16x16x32_bf16 v[12:15], v[192:195], v[44:47], v[66:69]
	v_mfma_f32_16x16x32_bf16 v[100:103], v[196:199], v[56:59], v[12:15]
	v_mfma_f32_16x16x32_bf16 v[12:15], v[220:223], v[44:47], v[200:203]
	v_mfma_f32_16x16x32_bf16 v[96:99], v[224:227], v[56:59], v[12:15]
	v_mfma_f32_16x16x32_bf16 v[12:15], v[192:195], v[80:83], v[204:207]
	v_mfma_f32_16x16x32_bf16 v[84:87], v[196:199], v[228:231], v[12:15]
	v_mfma_f32_16x16x32_bf16 v[12:15], v[220:223], v[80:83], v[208:211]
	v_mfma_f32_16x16x32_bf16 v[80:83], v[224:227], v[228:231], v[12:15]
	v_mfma_f32_16x16x32_bf16 v[12:15], v[192:195], v[240:243], v[212:215]
	v_mfma_f32_16x16x32_bf16 v[68:71], v[196:199], v[244:247], v[12:15]
	v_mfma_f32_16x16x32_bf16 v[12:15], v[220:223], v[240:243], v[216:219]
	v_mfma_f32_16x16x32_bf16 v[64:67], v[224:227], v[244:247], v[12:15]
	s_setprio 0
	s_barrier
; __device__ __forceinline__ float sigmoidf_(float z) { return 1.0f / (1.0f + __expf(-z)); }
;     __device__ __forceinline__ void operator()(const f32x4 (&acc)[2][2][4][2], const Unit& u, int wr, int wc, int fr, int fq) const {
;         const int h = u.pm >> 5, mt = u.pm & 31; const int row0 = mt * BM + wr * 64 + fr, col0 = 3072 + h * 256 + wc * 32 + 4 * fq;
; #pragma unroll
;         for (int ai = 0; ai < 2; ++ai)
; #pragma unroll
;             for (int m = 0; m < 4; ++m) { const size_t ro = (size_t)(row0 + ai * HALF + m * 16) * 4096 + col0;
; #pragma unroll
;                 for (int bj = 0; bj < 2; ++bj)
; #pragma unroll
;                     for (int n = 0; n < 2; ++n) { const u32x2 gw = *(const u32x2*)(G + ro + bj * HALF + n * 16); f32x4 v = acc[ai][bj][m][n];
;                         const float g0 = __uint_as_float(gw.x << 16), g1 = __uint_as_float(gw.x & 0xffff0000u), g2 = __uint_as_float(gw.y << 16), g3 = __uint_as_float(gw.y & 0xffff0000u);
;                         v[0] *= g0 * sigmoidf_(g0); v[1] *= g1 * sigmoidf_(g1); v[2] *= g2 * sigmoidf_(g2); v[3] *= g3 * sigmoidf_(g3);
;                         u32x2 w; w.x = cvt_pk_bf16(v[0], v[1]); w.y = cvt_pk_bf16(v[2], v[3]); *(u32x2*)(YC + ro + bj * HALF + n * 16) = w; } }
; template <class Epi, class Sched, bool ALIGN_EPI = false, bool SP2 = false>
; __device__ __forceinline__ void gemm_phase(PG8_LAS unsigned char* lds, const Gemm g, const Sched& S, const Epi& E, int tid_in) {
;     ...
;             PG8_WAIT_V(8); PG8_WAIT_L(0); PG8_BAR; PG8_MMA(0, 0, At, B0); PG8_MMA(0, 1, At, B1); PG8_BAR; PG8_SCHED;
;             PG8_LDA(At, 0, 1); PG8_STAGE(PG8_SB(0, 0), b2, voffB); PG8_STAGE(PG8_SB(0, 1), b2 + hstep, voffB); PG8_STAGE(PG8_SA(0, 0), a2, voffA);
;             PG8_WAIT_V(8); PG8_WAIT_L(0); PG8_BAR; PG8_MMA(1, 0, At, B0); PG8_MMA(1, 1, At, B1); PG8_BAR; PG8_SCHED;
;             PG8_LDB(B0, 1, 0); PG8_LDB(B1, 1, 1); PG8_SCHED; PG8_LDA(At, 1, 0); PG8_STAGE(PG8_SA(0, 1), a2 + hstep, voffA);
;             PG8_WAIT_V(8); PG8_WAIT_L(0); PG8_BAR; PG8_MMA(0, 0, At, B0); PG8_MMA(0, 1, At, B1); PG8_BAR; PG8_SCHED;
;             PG8_LDA(At, 1, 1); PG8_STAGE(PG8_SB(1, 0), b3, voffB); PG8_STAGE(PG8_SB(1, 1), b3 + hstep, voffB); PG8_STAGE(PG8_SA(1, 0), a3, voffA);
;             PG8_WAIT_V(8); PG8_WAIT_L(0); PG8_BAR; PG8_MMA(1, 0, At, B0); PG8_MMA(1, 1, At, B1); PG8_BAR; PG8_SCHED;
	s_mov_b32 m0, s0
	ds_read_b128 v[130:133], v252 offset:49152
	ds_read_b128 v[136:139], v252 offset:50176
	ds_read_b128 v[200:203], v252 offset:51200
	ds_read_b128 v[204:207], v252 offset:52224
	ds_read_b128 v[208:211], v252 offset:53248
	ds_read_b128 v[212:215], v252 offset:54272
	ds_read_b128 v[216:219], v252 offset:55296
	ds_read_b128 v[228:231], v252 offset:56320
	global_load_lds_dwordx4 v[2:3], off
	s_mov_b32 m0, s6
	s_nop 0
	global_load_lds_dwordx4 v[4:5], off
	s_mov_b32 m0, s19
	s_nop 0
	global_load_lds_dwordx4 v[8:9], off
	s_mov_b32 m0, s25
	s_nop 0
	global_load_lds_dwordx4 v[10:11], off
	s_mov_b32 m0, s1
	s_nop 0
	global_load_lds_dwordx4 v[0:1], off
	s_mov_b32 m0, s7
	s_nop 0
	global_load_lds_dwordx4 v[6:7], off
	s_waitcnt vmcnt(8)
	s_waitcnt lgkmcnt(0)
	s_barrier
	s_setprio 1
	s_waitcnt lgkmcnt(0)
	v_mfma_f32_16x16x32_bf16 v[0:3], v[48:51], v[130:133], v[16:19]
	v_mfma_f32_16x16x32_bf16 v[60:63], v[52:55], v[136:139], v[0:3]
	v_mfma_f32_16x16x32_bf16 v[0:3], v[184:187], v[130:133], v[20:23]
	v_mfma_f32_16x16x32_bf16 v[56:59], v[188:191], v[136:139], v[0:3]
	v_mfma_f32_16x16x32_bf16 v[0:3], v[48:51], v[200:203], v[24:27]
	v_mfma_f32_16x16x32_bf16 v[44:47], v[52:55], v[204:207], v[0:3]
	v_mfma_f32_16x16x32_bf16 v[0:3], v[184:187], v[200:203], v[168:171]
	v_mfma_f32_16x16x32_bf16 v[40:43], v[188:191], v[204:207], v[0:3]
	v_mfma_f32_16x16x32_bf16 v[0:3], v[48:51], v[208:211], v[172:175]
	v_mfma_f32_16x16x32_bf16 v[28:31], v[52:55], v[212:215], v[0:3]
	v_mfma_f32_16x16x32_bf16 v[0:3], v[184:187], v[208:211], v[176:179]
	v_mfma_f32_16x16x32_bf16 v[24:27], v[188:191], v[212:215], v[0:3]
	v_mfma_f32_16x16x32_bf16 v[0:3], v[48:51], v[216:219], v[144:147]
	v_mfma_f32_16x16x32_bf16 v[12:15], v[52:55], v[228:231], v[0:3]
	v_mfma_f32_16x16x32_bf16 v[0:3], v[184:187], v[216:219], v[32:35]
	v_mfma_f32_16x16x32_bf16 v[8:11], v[188:191], v[228:231], v[0:3]
	s_setprio 0
	s_setprio 1
	v_mfma_f32_16x16x32_bf16 v[0:3], v[192:195], v[130:133], v[36:39]
	v_mfma_f32_16x16x32_bf16 v[52:55], v[196:199], v[136:139], v[0:3]
	v_mfma_f32_16x16x32_bf16 v[0:3], v[220:223], v[130:133], v[148:151]
	v_mfma_f32_16x16x32_bf16 v[48:51], v[224:227], v[136:139], v[0:3]
	v_mfma_f32_16x16x32_bf16 v[0:3], v[192:195], v[200:203], v[152:155]
	v_mfma_f32_16x16x32_bf16 v[36:39], v[196:199], v[204:207], v[0:3]
	v_mfma_f32_16x16x32_bf16 v[0:3], v[220:223], v[200:203], v[156:159]
	v_mfma_f32_16x16x32_bf16 v[32:35], v[224:227], v[204:207], v[0:3]
	v_mfma_f32_16x16x32_bf16 v[0:3], v[192:195], v[208:211], v[180:183]
	v_mfma_f32_16x16x32_bf16 v[20:23], v[196:199], v[212:215], v[0:3]
	v_mfma_f32_16x16x32_bf16 v[0:3], v[220:223], v[208:211], v[140:143]
	v_mfma_f32_16x16x32_bf16 v[16:19], v[224:227], v[212:215], v[0:3]
	v_mfma_f32_16x16x32_bf16 v[0:3], v[192:195], v[216:219], v[160:163]
	v_mfma_f32_16x16x32_bf16 v[4:7], v[196:199], v[228:231], v[0:3]
	v_mfma_f32_16x16x32_bf16 v[0:3], v[220:223], v[216:219], v[164:167]
	v_mfma_f32_16x16x32_bf16 v[0:3], v[224:227], v[228:231], v[0:3]
	s_setprio 0
	s_barrier
	s_and_b32 s0, s60, 0x1f00
	v_add_u32_e32 v126, s0, v124
	s_and_b32 s0, s58, 0x7fffff00
	v_or_b32_e32 v124, s0, v125
	v_ashrrev_i32_e32 v127, 31, v126
	v_add_u32_e32 v128, 0xc00, v124
	v_lshlrev_b64 v[124:125], 12, v[126:127]
	v_lshl_add_u64 v[124:125], v[124:125], 0, v[128:129]
	v_lshlrev_b64 v[124:125], 1, v[124:125]
	v_lshl_add_u64 v[132:133], s[8:9], 0, v[124:125]
	flat_load_dwordx2 v[130:131], v[132:133]
	flat_load_dwordx2 v[164:165], v[132:133] offset:32
	flat_load_dwordx2 v[166:167], v[132:133] offset:256
	flat_load_dwordx2 v[168:169], v[132:133] offset:288
	s_mov_b64 s[0:1], 0x20000
	v_lshl_add_u64 v[228:229], v[132:133], 0, s[0:1]
	flat_load_dwordx2 v[170:171], v[228:229]
	flat_load_dwordx2 v[172:173], v[228:229] offset:32
	flat_load_dwordx2 v[174:175], v[228:229] offset:256
	flat_load_dwordx2 v[176:177], v[228:229] offset:288
	s_mov_b64 s[0:1], 0x40000
	v_lshl_add_u64 v[230:231], v[132:133], 0, s[0:1]
	flat_load_dwordx2 v[178:179], v[230:231]
	flat_load_dwordx2 v[180:181], v[230:231] offset:32
	flat_load_dwordx2 v[182:183], v[230:231] offset:256
	flat_load_dwordx2 v[184:185], v[230:231] offset:288
	s_mov_b64 s[0:1], 0x60000
	v_lshl_add_u64 v[232:233], v[132:133], 0, s[0:1]
	flat_load_dwordx2 v[186:187], v[232:233]
	flat_load_dwordx2 v[188:189], v[232:233] offset:32
	flat_load_dwordx2 v[190:191], v[232:233] offset:256
	flat_load_dwordx2 v[192:193], v[232:233] offset:288
	v_lshl_add_u64 v[234:235], v[132:133], 0, s[40:41]
	flat_load_dwordx2 v[194:195], v[234:235]
	flat_load_dwordx2 v[196:197], v[234:235] offset:32
	flat_load_dwordx2 v[198:199], v[234:235] offset:256
	flat_load_dwordx2 v[200:201], v[234:235] offset:288
	v_lshl_add_u64 v[236:237], v[132:133], 0, s[42:43]
	flat_load_dwordx2 v[202:203], v[236:237]
	flat_load_dwordx2 v[204:205], v[236:237] offset:32
	flat_load_dwordx2 v[206:207], v[236:237] offset:256
	flat_load_dwordx2 v[208:209], v[236:237] offset:288
	v_lshl_add_u64 v[238:239], v[132:133], 0, s[44:45]
	flat_load_dwordx2 v[210:211], v[238:239]
	flat_load_dwordx2 v[212:213], v[238:239] offset:32
	flat_load_dwordx2 v[214:215], v[238:239] offset:256
	flat_load_dwordx2 v[216:217], v[238:239] offset:288
	v_lshl_add_u64 v[240:241], v[132:133], 0, s[46:47]
	flat_load_dwordx2 v[218:219], v[240:241]
	flat_load_dwordx2 v[220:221], v[240:241] offset:32
	flat_load_dwordx2 v[222:223], v[240:241] offset:256
	flat_load_dwordx2 v[224:225], v[240:241] offset:288
	s_cmpk_gt_u32 s48, 0xff
	s_waitcnt vmcnt(0) lgkmcnt(0)
; __device__ __forceinline__ unsigned cvt_pk_bf16(float lo, float hi) { unsigned r; asm volatile("v_cvt_pk_bf16_f32 %0, %1, %2" : "=v"(r) : "v"(lo), "v"(hi)); return r; }
; __device__ __forceinline__ float sigmoidf_(float z) { return 1.0f / (1.0f + __expf(-z)); }
;     __device__ __forceinline__ void operator()(const f32x4 (&acc)[2][2][4][2], const Unit& u, int wr, int wc, int fr, int fq) const {
;     ...
;                     for (int n = 0; n < 2; ++n) { const u32x2 gw = *(const u32x2*)(G + ro + bj * HALF + n * 16); f32x4 v = acc[ai][bj][m][n];
;                         const float g0 = __uint_as_float(gw.x << 16), g1 = __uint_as_float(gw.x & 0xffff0000u), g2 = __uint_as_float(gw.y << 16), g3 = __uint_as_float(gw.y & 0xffff0000u);
;                         v[0] *= g0 * sigmoidf_(g0); v[1] *= g1 * sigmoidf_(g1); v[2] *= g2 * sigmoidf_(g2); v[3] *= g3 * sigmoidf_(g3);
;                         u32x2 w; w.x = cvt_pk_bf16(v[0], v[1]); w.y = cvt_pk_bf16(v[2], v[3]); *(u32x2*)(YC + ro + bj * HALF + n * 16) = w; } }
	v_lshlrev_b32_e32 v127, 16, v130
	v_and_b32_e32 v130, 0xffff0000, v130
	v_mul_f32_e32 v137, 0xbfb8aa3b, v127
	v_lshlrev_b32_e32 v136, 16, v131
	v_mul_f32_e32 v138, 0xbfb8aa3b, v130
	v_exp_f32_e32 v137, v137
	v_and_b32_e32 v131, 0xffff0000, v131
	v_mul_f32_e32 v139, 0xbfb8aa3b, v136
	v_exp_f32_e32 v138, v138
	v_mul_f32_e32 v140, 0xbfb8aa3b, v131
	v_exp_f32_e32 v139, v139
	v_exp_f32_e32 v140, v140
	v_add_f32_e32 v137, 1.0, v137
	v_add_f32_e32 v138, 1.0, v138
	v_div_scale_f32 v141, s[0:1], v137, v137, 1.0
	v_add_f32_e32 v139, 1.0, v139
	v_div_scale_f32 v143, s[0:1], v138, v138, 1.0
	v_rcp_f32_e32 v149, v141
	v_add_f32_e32 v140, 1.0, v140
	v_div_scale_f32 v145, s[0:1], v139, v139, 1.0
	v_rcp_f32_e32 v150, v143
	v_div_scale_f32 v147, s[0:1], v140, v140, 1.0
	v_rcp_f32_e32 v151, v145
	v_rcp_f32_e32 v152, v147
	v_fma_f32 v153, -v141, v149, 1.0
	v_div_scale_f32 v142, vcc, 1.0, v137, 1.0
	v_fma_f32 v154, -v143, v150, 1.0
	v_fmac_f32_e32 v149, v153, v149
	v_div_scale_f32 v144, s[2:3], 1.0, v138, 1.0
	v_fma_f32 v155, -v145, v151, 1.0
	v_fmac_f32_e32 v150, v154, v150
	v_mul_f32_e32 v153, v142, v149
	v_div_scale_f32 v146, s[4:5], 1.0, v139, 1.0
	v_fma_f32 v156, -v147, v152, 1.0
	v_fmac_f32_e32 v151, v155, v151
	v_mul_f32_e32 v154, v144, v150
	v_fma_f32 v157, -v141, v153, v142
	v_div_scale_f32 v148, s[6:7], 1.0, v140, 1.0
	v_fmac_f32_e32 v152, v156, v152
	v_mul_f32_e32 v155, v146, v151
	v_fma_f32 v158, -v143, v154, v144
	v_fmac_f32_e32 v153, v157, v149
	v_mul_f32_e32 v156, v148, v152
	v_fma_f32 v159, -v145, v155, v146
	v_fmac_f32_e32 v154, v158, v150
	v_fma_f32 v141, -v141, v153, v142
	v_fma_f32 v160, -v147, v156, v148
	v_fmac_f32_e32 v155, v159, v151
	v_fma_f32 v142, -v143, v154, v144
	v_div_fmas_f32 v141, v141, v149, v153
	s_mov_b64 vcc, s[2:3]
	v_fmac_f32_e32 v156, v160, v152
	v_fma_f32 v143, -v145, v155, v146
	v_div_fixup_f32 v137, v141, v137, 1.0
	v_div_fmas_f32 v141, v142, v150, v154
	s_mov_b64 vcc, s[4:5]
	v_fma_f32 v144, -v147, v156, v148
	v_mul_f32_e32 v127, v137, v127
	v_div_fixup_f32 v137, v141, v138, 1.0
	v_div_fmas_f32 v138, v143, v151, v155
	s_mov_b64 vcc, s[6:7]
	v_mul_f32_e32 v130, v137, v130
	v_div_fixup_f32 v137, v138, v139, 1.0
	v_div_fmas_f32 v138, v144, v152, v156
	v_mul_f32_e32 v136, v137, v136
	v_div_fixup_f32 v137, v138, v140, 1.0
	v_mul_f32_e32 v127, v248, v127
	v_mul_f32_e32 v138, v250, v136
	v_mul_f32_e32 v131, v137, v131
	v_mul_f32_e32 v130, v249, v130
	v_cvt_pk_bf16_f32 v136, v127, v130
	v_mul_f32_e32 v127, v251, v131
	v_cvt_pk_bf16_f32 v137, v138, v127
	v_mov_b64_e32 v[138:139], v[164:165]
	v_lshl_add_u64 v[130:131], s[12:13], 0, v[124:125]
	flat_store_dwordx2 v[130:131], v[136:137]
	v_lshlrev_b32_e32 v127, 16, v138
	v_and_b32_e32 v136, 0xffff0000, v138
	v_lshlrev_b32_e32 v137, 16, v139
	v_and_b32_e32 v138, 0xffff0000, v139
	v_mul_f32_e32 v139, 0xbfb8aa3b, v127
	v_mul_f32_e32 v140, 0xbfb8aa3b, v136
	v_exp_f32_e32 v139, v139
	v_mul_f32_e32 v141, 0xbfb8aa3b, v137
	v_exp_f32_e32 v140, v140
	v_mul_f32_e32 v142, 0xbfb8aa3b, v138
	v_exp_f32_e32 v141, v141
	v_exp_f32_e32 v142, v142
	v_add_f32_e32 v139, 1.0, v139
	v_add_f32_e32 v140, 1.0, v140
	v_div_scale_f32 v143, s[0:1], v139, v139, 1.0
	v_add_f32_e32 v141, 1.0, v141
	v_div_scale_f32 v145, s[0:1], v140, v140, 1.0
	v_rcp_f32_e32 v151, v143
	v_add_f32_e32 v142, 1.0, v142
	v_div_scale_f32 v147, s[0:1], v141, v141, 1.0
	v_rcp_f32_e32 v152, v145
	v_div_scale_f32 v149, s[0:1], v142, v142, 1.0
	v_rcp_f32_e32 v153, v147
	v_rcp_f32_e32 v154, v149
	v_fma_f32 v155, -v143, v151, 1.0
	v_div_scale_f32 v144, vcc, 1.0, v139, 1.0
	v_fma_f32 v156, -v145, v152, 1.0
	v_fmac_f32_e32 v151, v155, v151
	v_div_scale_f32 v146, s[2:3], 1.0, v140, 1.0
	v_fma_f32 v157, -v147, v153, 1.0
	v_fmac_f32_e32 v152, v156, v152
	v_mul_f32_e32 v155, v144, v151
	v_div_scale_f32 v148, s[4:5], 1.0, v141, 1.0
	v_fma_f32 v158, -v149, v154, 1.0
	v_fmac_f32_e32 v153, v157, v153
	v_mul_f32_e32 v156, v146, v152
	v_fma_f32 v159, -v143, v155, v144
	v_div_scale_f32 v150, s[6:7], 1.0, v142, 1.0
	v_fmac_f32_e32 v154, v158, v154
	v_mul_f32_e32 v157, v148, v153
	v_fma_f32 v160, -v145, v156, v146
	v_fmac_f32_e32 v155, v159, v151
	v_mul_f32_e32 v158, v150, v154
	v_fma_f32 v161, -v147, v157, v148
	v_fmac_f32_e32 v156, v160, v152
	v_fma_f32 v143, -v143, v155, v144
	v_fma_f32 v162, -v149, v158, v150
	v_fmac_f32_e32 v157, v161, v153
	v_fma_f32 v144, -v145, v156, v146
	v_div_fmas_f32 v143, v143, v151, v155
	s_mov_b64 vcc, s[2:3]
	v_fmac_f32_e32 v158, v162, v154
	v_fma_f32 v145, -v147, v157, v148
	v_div_fixup_f32 v139, v143, v139, 1.0
	v_div_fmas_f32 v143, v144, v152, v156
	s_mov_b64 vcc, s[4:5]
	v_fma_f32 v146, -v149, v158, v150
	v_mul_f32_e32 v127, v139, v127
	v_div_fixup_f32 v139, v143, v140, 1.0
	v_div_fmas_f32 v140, v145, v153, v157
	s_mov_b64 vcc, s[6:7]
	v_mul_f32_e32 v120, v120, v127
	v_mul_f32_e32 v127, v139, v136
	v_div_fixup_f32 v136, v140, v141, 1.0
	v_div_fmas_f32 v139, v146, v154, v158
	v_mul_f32_e32 v121, v121, v127
	v_mul_f32_e32 v127, v136, v137
	v_div_fixup_f32 v136, v139, v142, 1.0
	v_mul_f32_e32 v122, v122, v127
	v_mul_f32_e32 v127, v136, v138
	v_cvt_pk_bf16_f32 v120, v120, v121
	v_mul_f32_e32 v121, v123, v127
	v_cvt_pk_bf16_f32 v121, v122, v121
	v_mov_b64_e32 v[122:123], v[166:167]
	s_nop 0
	flat_store_dwordx2 v[130:131], v[120:121] offset:32
	v_lshlrev_b32_e32 v120, 16, v122
	v_and_b32_e32 v121, 0xffff0000, v122
	v_mul_f32_e32 v127, 0xbfb8aa3b, v120
	v_lshlrev_b32_e32 v122, 16, v123
	v_mul_f32_e32 v136, 0xbfb8aa3b, v121
	v_exp_f32_e32 v127, v127
	v_and_b32_e32 v123, 0xffff0000, v123
	v_mul_f32_e32 v137, 0xbfb8aa3b, v122
	v_exp_f32_e32 v136, v136
	v_mul_f32_e32 v138, 0xbfb8aa3b, v123
	v_exp_f32_e32 v137, v137
; __device__ __forceinline__ unsigned cvt_pk_bf16(float lo, float hi) { unsigned r; asm volatile("v_cvt_pk_bf16_f32 %0, %1, %2" : "=v"(r) : "v"(lo), "v"(hi)); return r; }
; __device__ __forceinline__ float sigmoidf_(float z) { return 1.0f / (1.0f + __expf(-z)); }
;     __device__ __forceinline__ void operator()(const f32x4 (&acc)[2][2][4][2], const Unit& u, int wr, int wc, int fr, int fq) const {
;     ...
;             for (int m = 0; m < 4; ++m) { const size_t ro = (size_t)(row0 + ai * HALF + m * 16) * 4096 + col0;
; #pragma unroll
;                 for (int bj = 0; bj < 2; ++bj)
; #pragma unroll
;                     for (int n = 0; n < 2; ++n) { const u32x2 gw = *(const u32x2*)(G + ro + bj * HALF + n * 16); f32x4 v = acc[ai][bj][m][n];
;                         const float g0 = __uint_as_float(gw.x << 16), g1 = __uint_as_float(gw.x & 0xffff0000u), g2 = __uint_as_float(gw.y << 16), g3 = __uint_as_float(gw.y & 0xffff0000u);
;                         v[0] *= g0 * sigmoidf_(g0); v[1] *= g1 * sigmoidf_(g1); v[2] *= g2 * sigmoidf_(g2); v[3] *= g3 * sigmoidf_(g3);
;                         u32x2 w; w.x = cvt_pk_bf16(v[0], v[1]); w.y = cvt_pk_bf16(v[2], v[3]); *(u32x2*)(YC + ro + bj * HALF + n * 16) = w; } }
	v_exp_f32_e32 v138, v138
	v_add_f32_e32 v127, 1.0, v127
	v_add_f32_e32 v136, 1.0, v136
	v_div_scale_f32 v139, s[0:1], v127, v127, 1.0
	v_add_f32_e32 v137, 1.0, v137
	v_div_scale_f32 v141, s[0:1], v136, v136, 1.0
	v_rcp_f32_e32 v147, v139
	v_add_f32_e32 v138, 1.0, v138
	v_div_scale_f32 v143, s[0:1], v137, v137, 1.0
	v_rcp_f32_e32 v148, v141
	v_div_scale_f32 v145, s[0:1], v138, v138, 1.0
	v_rcp_f32_e32 v149, v143
	v_rcp_f32_e32 v150, v145
	v_fma_f32 v151, -v139, v147, 1.0
	v_div_scale_f32 v140, vcc, 1.0, v127, 1.0
	v_fma_f32 v152, -v141, v148, 1.0
	v_fmac_f32_e32 v147, v151, v147
	v_div_scale_f32 v142, s[2:3], 1.0, v136, 1.0
	v_fma_f32 v153, -v143, v149, 1.0
	v_fmac_f32_e32 v148, v152, v148
	v_mul_f32_e32 v151, v140, v147
	v_div_scale_f32 v144, s[4:5], 1.0, v137, 1.0
	v_fma_f32 v154, -v145, v150, 1.0
	v_fmac_f32_e32 v149, v153, v149
	v_mul_f32_e32 v152, v142, v148
	v_fma_f32 v155, -v139, v151, v140
	v_div_scale_f32 v146, s[6:7], 1.0, v138, 1.0
	v_fmac_f32_e32 v150, v154, v150
	v_mul_f32_e32 v153, v144, v149
	v_fma_f32 v156, -v141, v152, v142
	v_fmac_f32_e32 v151, v155, v147
	v_mul_f32_e32 v154, v146, v150
	v_fma_f32 v157, -v143, v153, v144
	v_fmac_f32_e32 v152, v156, v148
	v_fma_f32 v139, -v139, v151, v140
	v_fma_f32 v158, -v145, v154, v146
	v_fmac_f32_e32 v153, v157, v149
	v_fma_f32 v140, -v141, v152, v142
	v_div_fmas_f32 v139, v139, v147, v151
	s_mov_b64 vcc, s[2:3]
	v_fmac_f32_e32 v154, v158, v150
	v_fma_f32 v141, -v143, v153, v144
	v_div_fixup_f32 v127, v139, v127, 1.0
	v_div_fmas_f32 v139, v140, v148, v152
	s_mov_b64 vcc, s[4:5]
	v_fma_f32 v142, -v145, v154, v146
	v_mul_f32_e32 v120, v127, v120
	v_div_fixup_f32 v127, v139, v136, 1.0
	v_div_fmas_f32 v136, v141, v149, v153
	s_mov_b64 vcc, s[6:7]
	v_mul_f32_e32 v116, v116, v120
	v_mul_f32_e32 v120, v127, v121
	v_div_fixup_f32 v121, v136, v137, 1.0
	v_div_fmas_f32 v127, v142, v150, v154
	v_mul_f32_e32 v117, v117, v120
	v_mul_f32_e32 v120, v121, v122
	v_div_fixup_f32 v121, v127, v138, 1.0
	v_mul_f32_e32 v120, v118, v120
	v_mul_f32_e32 v121, v121, v123
	v_cvt_pk_bf16_f32 v118, v116, v117
	v_mul_f32_e32 v116, v119, v121
	v_cvt_pk_bf16_f32 v119, v120, v116
	v_mov_b64_e32 v[120:121], v[168:169]
	v_or_b32_e32 v116, 16, v126
	flat_store_dwordx2 v[130:131], v[118:119] offset:256
	v_ashrrev_i32_e32 v117, 31, v116
	v_lshlrev_b64 v[116:117], 12, v[116:117]
	v_lshl_add_u64 v[116:117], v[116:117], 0, v[128:129]
	v_lshlrev_b64 v[122:123], 1, v[116:117]
	v_lshl_add_u64 v[116:117], s[8:9], 0, v[122:123]
	v_lshlrev_b32_e32 v118, 16, v120
	v_and_b32_e32 v119, 0xffff0000, v120
	v_mul_f32_e32 v127, 0xbfb8aa3b, v118
	v_lshlrev_b32_e32 v120, 16, v121
	v_mul_f32_e32 v132, 0xbfb8aa3b, v119
	v_exp_f32_e32 v127, v127
	v_and_b32_e32 v121, 0xffff0000, v121
	v_mul_f32_e32 v133, 0xbfb8aa3b, v120
	v_exp_f32_e32 v132, v132
	v_mul_f32_e32 v136, 0xbfb8aa3b, v121
	v_exp_f32_e32 v133, v133
	v_exp_f32_e32 v136, v136
	v_add_f32_e32 v127, 1.0, v127
	v_add_f32_e32 v132, 1.0, v132
	v_div_scale_f32 v137, s[0:1], v127, v127, 1.0
	v_add_f32_e32 v133, 1.0, v133
	v_div_scale_f32 v139, s[0:1], v132, v132, 1.0
	v_rcp_f32_e32 v145, v137
	v_add_f32_e32 v136, 1.0, v136
	v_div_scale_f32 v141, s[0:1], v133, v133, 1.0
	v_rcp_f32_e32 v146, v139
	v_div_scale_f32 v143, s[0:1], v136, v136, 1.0
	v_rcp_f32_e32 v147, v141
	v_rcp_f32_e32 v148, v143
	v_fma_f32 v149, -v137, v145, 1.0
	v_div_scale_f32 v138, vcc, 1.0, v127, 1.0
	v_fma_f32 v150, -v139, v146, 1.0
	v_fmac_f32_e32 v145, v149, v145
	v_div_scale_f32 v140, s[2:3], 1.0, v132, 1.0
	v_fma_f32 v151, -v141, v147, 1.0
	v_fmac_f32_e32 v146, v150, v146
	v_mul_f32_e32 v149, v138, v145
	v_div_scale_f32 v142, s[4:5], 1.0, v133, 1.0
	v_fma_f32 v152, -v143, v148, 1.0
	v_fmac_f32_e32 v147, v151, v147
	v_mul_f32_e32 v150, v140, v146
	v_fma_f32 v153, -v137, v149, v138
	v_div_scale_f32 v144, s[6:7], 1.0, v136, 1.0
	v_fmac_f32_e32 v148, v152, v148
	v_mul_f32_e32 v151, v142, v147
	v_fma_f32 v154, -v139, v150, v140
	v_fmac_f32_e32 v149, v153, v145
	v_mul_f32_e32 v152, v144, v148
	v_fma_f32 v155, -v141, v151, v142
	v_fmac_f32_e32 v150, v154, v146
	v_fma_f32 v137, -v137, v149, v138
	v_fma_f32 v156, -v143, v152, v144
	v_fmac_f32_e32 v151, v155, v147
	v_fma_f32 v138, -v139, v150, v140
	v_div_fmas_f32 v137, v137, v145, v149
	s_mov_b64 vcc, s[2:3]
	v_fmac_f32_e32 v152, v156, v148
	v_fma_f32 v139, -v141, v151, v142
	v_div_fixup_f32 v127, v137, v127, 1.0
	v_div_fmas_f32 v137, v138, v146, v150
	s_mov_b64 vcc, s[4:5]
	v_fma_f32 v140, -v143, v152, v144
	v_mul_f32_e32 v118, v127, v118
	v_div_fixup_f32 v127, v137, v132, 1.0
	v_div_fmas_f32 v132, v139, v147, v151
	s_mov_b64 vcc, s[6:7]
	v_mul_f32_e32 v112, v112, v118
	v_mul_f32_e32 v118, v127, v119
	v_div_fixup_f32 v119, v132, v133, 1.0
	v_div_fmas_f32 v127, v140, v148, v152
	v_mul_f32_e32 v113, v113, v118
	v_mul_f32_e32 v118, v119, v120
	v_div_fixup_f32 v119, v127, v136, 1.0
	v_mul_f32_e32 v114, v114, v118
	v_mul_f32_e32 v118, v119, v121
	v_cvt_pk_bf16_f32 v112, v112, v113
	v_mul_f32_e32 v113, v115, v118
	v_cvt_pk_bf16_f32 v113, v114, v113
	flat_store_dwordx2 v[130:131], v[112:113] offset:288
	v_mov_b64_e32 v[112:113], v[170:171]
	v_lshlrev_b32_e32 v114, 16, v112
	v_and_b32_e32 v112, 0xffff0000, v112
	v_mul_f32_e32 v118, 0xbfb8aa3b, v114
	v_lshlrev_b32_e32 v115, 16, v113
	v_mul_f32_e32 v119, 0xbfb8aa3b, v112
	v_exp_f32_e32 v118, v118
	v_and_b32_e32 v113, 0xffff0000, v113
	v_mul_f32_e32 v120, 0xbfb8aa3b, v115
	v_exp_f32_e32 v119, v119
	v_mul_f32_e32 v121, 0xbfb8aa3b, v113
	v_exp_f32_e32 v120, v120
	v_exp_f32_e32 v121, v121
	v_add_f32_e32 v118, 1.0, v118
	v_add_f32_e32 v119, 1.0, v119
	v_div_scale_f32 v127, s[0:1], v118, v118, 1.0
	v_add_f32_e32 v120, 1.0, v120
; __device__ __forceinline__ unsigned cvt_pk_bf16(float lo, float hi) { unsigned r; asm volatile("v_cvt_pk_bf16_f32 %0, %1, %2" : "=v"(r) : "v"(lo), "v"(hi)); return r; }
; __device__ __forceinline__ float sigmoidf_(float z) { return 1.0f / (1.0f + __expf(-z)); }
;     __device__ __forceinline__ void operator()(const f32x4 (&acc)[2][2][4][2], const Unit& u, int wr, int wc, int fr, int fq) const {
;     ...
;                     for (int n = 0; n < 2; ++n) { const u32x2 gw = *(const u32x2*)(G + ro + bj * HALF + n * 16); f32x4 v = acc[ai][bj][m][n];
;                         const float g0 = __uint_as_float(gw.x << 16), g1 = __uint_as_float(gw.x & 0xffff0000u), g2 = __uint_as_float(gw.y << 16), g3 = __uint_as_float(gw.y & 0xffff0000u);
;                         v[0] *= g0 * sigmoidf_(g0); v[1] *= g1 * sigmoidf_(g1); v[2] *= g2 * sigmoidf_(g2); v[3] *= g3 * sigmoidf_(g3);
;                         u32x2 w; w.x = cvt_pk_bf16(v[0], v[1]); w.y = cvt_pk_bf16(v[2], v[3]); *(u32x2*)(YC + ro + bj * HALF + n * 16) = w; } }
	v_div_scale_f32 v131, s[0:1], v119, v119, 1.0
	v_rcp_f32_e32 v139, v127
	v_add_f32_e32 v121, 1.0, v121
	v_div_scale_f32 v133, s[0:1], v120, v120, 1.0
	v_rcp_f32_e32 v140, v131
	v_div_scale_f32 v137, s[0:1], v121, v121, 1.0
	v_rcp_f32_e32 v141, v133
	v_rcp_f32_e32 v142, v137
	v_fma_f32 v143, -v127, v139, 1.0
	v_div_scale_f32 v130, vcc, 1.0, v118, 1.0
	v_fma_f32 v144, -v131, v140, 1.0
	v_fmac_f32_e32 v139, v143, v139
	v_div_scale_f32 v132, s[2:3], 1.0, v119, 1.0
	v_fma_f32 v145, -v133, v141, 1.0
	v_fmac_f32_e32 v140, v144, v140
	v_mul_f32_e32 v143, v130, v139
	v_div_scale_f32 v136, s[4:5], 1.0, v120, 1.0
	v_fma_f32 v146, -v137, v142, 1.0
	v_fmac_f32_e32 v141, v145, v141
	v_mul_f32_e32 v144, v132, v140
	v_fma_f32 v147, -v127, v143, v130
	v_div_scale_f32 v138, s[6:7], 1.0, v121, 1.0
	v_fmac_f32_e32 v142, v146, v142
	v_mul_f32_e32 v145, v136, v141
	v_fma_f32 v148, -v131, v144, v132
	v_fmac_f32_e32 v143, v147, v139
	v_mul_f32_e32 v146, v138, v142
	v_fma_f32 v149, -v133, v145, v136
	v_fmac_f32_e32 v144, v148, v140
	v_fma_f32 v127, -v127, v143, v130
	v_fma_f32 v150, -v137, v146, v138
	v_fmac_f32_e32 v145, v149, v141
	v_fma_f32 v130, -v131, v144, v132
	v_div_fmas_f32 v127, v127, v139, v143
	s_mov_b64 vcc, s[2:3]
	v_fmac_f32_e32 v146, v150, v142
	v_fma_f32 v131, -v133, v145, v136
	v_div_fixup_f32 v118, v127, v118, 1.0
	v_div_fmas_f32 v127, v130, v140, v144
	s_mov_b64 vcc, s[4:5]
	v_fma_f32 v132, -v137, v146, v138
	v_mul_f32_e32 v114, v118, v114
	v_div_fixup_f32 v118, v127, v119, 1.0
	v_div_fmas_f32 v119, v131, v141, v145
	s_mov_b64 vcc, s[6:7]
	v_mul_f32_e32 v108, v108, v114
	v_mul_f32_e32 v112, v118, v112
	v_div_fixup_f32 v114, v119, v120, 1.0
	v_div_fmas_f32 v118, v132, v142, v146
	v_mul_f32_e32 v109, v109, v112
	v_mul_f32_e32 v112, v114, v115
	v_div_fixup_f32 v114, v118, v121, 1.0
	v_mul_f32_e32 v112, v110, v112
	v_mul_f32_e32 v113, v114, v113
	v_cvt_pk_bf16_f32 v110, v108, v109
	v_mul_f32_e32 v108, v111, v113
	v_cvt_pk_bf16_f32 v111, v112, v108
	v_mov_b64_e32 v[112:113], v[172:173]
	v_lshl_add_u64 v[108:109], s[12:13], 0, v[122:123]
	flat_store_dwordx2 v[108:109], v[110:111]
	v_lshlrev_b32_e32 v110, 16, v112
	v_and_b32_e32 v111, 0xffff0000, v112
	v_mul_f32_e32 v114, 0xbfb8aa3b, v110
	v_lshlrev_b32_e32 v112, 16, v113
	v_mul_f32_e32 v115, 0xbfb8aa3b, v111
	v_exp_f32_e32 v114, v114
	v_and_b32_e32 v113, 0xffff0000, v113
	v_mul_f32_e32 v118, 0xbfb8aa3b, v112
	v_exp_f32_e32 v115, v115
	v_mul_f32_e32 v119, 0xbfb8aa3b, v113
	v_exp_f32_e32 v118, v118
	v_exp_f32_e32 v119, v119
	v_add_f32_e32 v114, 1.0, v114
	v_add_f32_e32 v115, 1.0, v115
	v_div_scale_f32 v120, s[0:1], v114, v114, 1.0
	v_add_f32_e32 v118, 1.0, v118
	v_div_scale_f32 v122, s[0:1], v115, v115, 1.0
	v_rcp_f32_e32 v133, v120
	v_add_f32_e32 v119, 1.0, v119
	v_div_scale_f32 v127, s[0:1], v118, v118, 1.0
	v_rcp_f32_e32 v136, v122
	v_div_scale_f32 v131, s[0:1], v119, v119, 1.0
	v_rcp_f32_e32 v137, v127
	v_rcp_f32_e32 v138, v131
	v_fma_f32 v139, -v120, v133, 1.0
	v_div_scale_f32 v121, vcc, 1.0, v114, 1.0
	v_fma_f32 v140, -v122, v136, 1.0
	v_fmac_f32_e32 v133, v139, v133
	v_div_scale_f32 v123, s[2:3], 1.0, v115, 1.0
	v_fma_f32 v141, -v127, v137, 1.0
	v_fmac_f32_e32 v136, v140, v136
	v_mul_f32_e32 v139, v121, v133
	v_div_scale_f32 v130, s[4:5], 1.0, v118, 1.0
	v_fma_f32 v142, -v131, v138, 1.0
	v_fmac_f32_e32 v137, v141, v137
	v_mul_f32_e32 v140, v123, v136
	v_fma_f32 v143, -v120, v139, v121
	v_div_scale_f32 v132, s[6:7], 1.0, v119, 1.0
	v_fmac_f32_e32 v138, v142, v138
	v_mul_f32_e32 v141, v130, v137
	v_fma_f32 v144, -v122, v140, v123
	v_fmac_f32_e32 v139, v143, v133
	v_mul_f32_e32 v142, v132, v138
	v_fma_f32 v145, -v127, v141, v130
	v_fmac_f32_e32 v140, v144, v136
	v_fma_f32 v120, -v120, v139, v121
	v_fma_f32 v146, -v131, v142, v132
	v_fmac_f32_e32 v141, v145, v137
	v_fma_f32 v121, -v122, v140, v123
	v_div_fmas_f32 v120, v120, v133, v139
	s_mov_b64 vcc, s[2:3]
	v_fmac_f32_e32 v142, v146, v138
	v_fma_f32 v122, -v127, v141, v130
	v_div_fixup_f32 v114, v120, v114, 1.0
	v_div_fmas_f32 v120, v121, v136, v140
	s_mov_b64 vcc, s[4:5]
	v_fma_f32 v123, -v131, v142, v132
	v_mul_f32_e32 v110, v114, v110
	v_div_fixup_f32 v114, v120, v115, 1.0
	v_div_fmas_f32 v115, v122, v137, v141
	s_mov_b64 vcc, s[6:7]
	v_mul_f32_e32 v104, v104, v110
	v_mul_f32_e32 v110, v114, v111
	v_div_fixup_f32 v111, v115, v118, 1.0
	v_div_fmas_f32 v114, v123, v138, v142
	v_mul_f32_e32 v105, v105, v110
	v_mul_f32_e32 v110, v111, v112
	v_div_fixup_f32 v111, v114, v119, 1.0
	v_mul_f32_e32 v106, v106, v110
	v_mul_f32_e32 v110, v111, v113
	v_cvt_pk_bf16_f32 v104, v104, v105
	v_mul_f32_e32 v105, v107, v110
	v_cvt_pk_bf16_f32 v105, v106, v105
	v_mov_b64_e32 v[106:107], v[174:175]
	s_nop 0
	flat_store_dwordx2 v[108:109], v[104:105] offset:32
	v_lshlrev_b32_e32 v104, 16, v106
	v_and_b32_e32 v105, 0xffff0000, v106
	v_mul_f32_e32 v110, 0xbfb8aa3b, v104
	v_lshlrev_b32_e32 v106, 16, v107
	v_mul_f32_e32 v111, 0xbfb8aa3b, v105
	v_exp_f32_e32 v110, v110
	v_and_b32_e32 v107, 0xffff0000, v107
	v_mul_f32_e32 v112, 0xbfb8aa3b, v106
	v_exp_f32_e32 v111, v111
	v_mul_f32_e32 v113, 0xbfb8aa3b, v107
	v_exp_f32_e32 v112, v112
	v_exp_f32_e32 v113, v113
	v_add_f32_e32 v110, 1.0, v110
	v_add_f32_e32 v111, 1.0, v111
	v_div_scale_f32 v114, s[0:1], v110, v110, 1.0
	v_add_f32_e32 v112, 1.0, v112
	v_div_scale_f32 v118, s[0:1], v111, v111, 1.0
	v_rcp_f32_e32 v127, v114
	v_add_f32_e32 v113, 1.0, v113
	v_div_scale_f32 v120, s[0:1], v112, v112, 1.0
	v_rcp_f32_e32 v130, v118
	v_div_scale_f32 v122, s[0:1], v113, v113, 1.0
	v_rcp_f32_e32 v131, v120
	v_rcp_f32_e32 v132, v122
	v_fma_f32 v133, -v114, v127, 1.0
	v_div_scale_f32 v115, vcc, 1.0, v110, 1.0
	v_fma_f32 v136, -v118, v130, 1.0
; __device__ __forceinline__ unsigned cvt_pk_bf16(float lo, float hi) { unsigned r; asm volatile("v_cvt_pk_bf16_f32 %0, %1, %2" : "=v"(r) : "v"(lo), "v"(hi)); return r; }
; __device__ __forceinline__ float sigmoidf_(float z) { return 1.0f / (1.0f + __expf(-z)); }
;     __device__ __forceinline__ void operator()(const f32x4 (&acc)[2][2][4][2], const Unit& u, int wr, int wc, int fr, int fq) const {
;     ...
;             for (int m = 0; m < 4; ++m) { const size_t ro = (size_t)(row0 + ai * HALF + m * 16) * 4096 + col0;
; #pragma unroll
;                 for (int bj = 0; bj < 2; ++bj)
; #pragma unroll
;                     for (int n = 0; n < 2; ++n) { const u32x2 gw = *(const u32x2*)(G + ro + bj * HALF + n * 16); f32x4 v = acc[ai][bj][m][n];
;                         const float g0 = __uint_as_float(gw.x << 16), g1 = __uint_as_float(gw.x & 0xffff0000u), g2 = __uint_as_float(gw.y << 16), g3 = __uint_as_float(gw.y & 0xffff0000u);
;                         v[0] *= g0 * sigmoidf_(g0); v[1] *= g1 * sigmoidf_(g1); v[2] *= g2 * sigmoidf_(g2); v[3] *= g3 * sigmoidf_(g3);
;                         u32x2 w; w.x = cvt_pk_bf16(v[0], v[1]); w.y = cvt_pk_bf16(v[2], v[3]); *(u32x2*)(YC + ro + bj * HALF + n * 16) = w; } }
	v_fmac_f32_e32 v127, v133, v127
	v_div_scale_f32 v119, s[2:3], 1.0, v111, 1.0
	v_fma_f32 v137, -v120, v131, 1.0
	v_fmac_f32_e32 v130, v136, v130
	v_mul_f32_e32 v133, v115, v127
	v_div_scale_f32 v121, s[4:5], 1.0, v112, 1.0
	v_fma_f32 v138, -v122, v132, 1.0
	v_fmac_f32_e32 v131, v137, v131
	v_mul_f32_e32 v136, v119, v130
	v_fma_f32 v139, -v114, v133, v115
	v_div_scale_f32 v123, s[6:7], 1.0, v113, 1.0
	v_fmac_f32_e32 v132, v138, v132
	v_mul_f32_e32 v137, v121, v131
	v_fma_f32 v140, -v118, v136, v119
	v_fmac_f32_e32 v133, v139, v127
	v_mul_f32_e32 v138, v123, v132
	v_fma_f32 v141, -v120, v137, v121
	v_fmac_f32_e32 v136, v140, v130
	v_fma_f32 v114, -v114, v133, v115
	v_fma_f32 v142, -v122, v138, v123
	v_fmac_f32_e32 v137, v141, v131
	v_fma_f32 v115, -v118, v136, v119
	v_div_fmas_f32 v114, v114, v127, v133
	s_mov_b64 vcc, s[2:3]
	v_fmac_f32_e32 v138, v142, v132
	v_fma_f32 v118, -v120, v137, v121
	v_div_fixup_f32 v110, v114, v110, 1.0
	v_div_fmas_f32 v114, v115, v130, v136
	s_mov_b64 vcc, s[4:5]
	v_fma_f32 v119, -v122, v138, v123
	v_mul_f32_e32 v104, v110, v104
	v_div_fixup_f32 v110, v114, v111, 1.0
	v_div_fmas_f32 v111, v118, v131, v137
	s_mov_b64 vcc, s[6:7]
	v_mul_f32_e32 v100, v100, v104
	v_mul_f32_e32 v104, v110, v105
	v_div_fixup_f32 v105, v111, v112, 1.0
	v_div_fmas_f32 v110, v119, v132, v138
	v_mul_f32_e32 v101, v101, v104
	v_mul_f32_e32 v104, v105, v106
	v_div_fixup_f32 v105, v110, v113, 1.0
	v_mul_f32_e32 v104, v102, v104
	v_mul_f32_e32 v105, v105, v107
	v_cvt_pk_bf16_f32 v102, v100, v101
	v_mul_f32_e32 v100, v103, v105
	v_cvt_pk_bf16_f32 v103, v104, v100
	v_mov_b64_e32 v[104:105], v[176:177]
	v_or_b32_e32 v100, 32, v126
	flat_store_dwordx2 v[108:109], v[102:103] offset:256
	v_ashrrev_i32_e32 v101, 31, v100
	v_lshlrev_b64 v[100:101], 12, v[100:101]
	v_lshl_add_u64 v[100:101], v[100:101], 0, v[128:129]
	v_lshlrev_b64 v[106:107], 1, v[100:101]
	v_lshl_add_u64 v[100:101], s[8:9], 0, v[106:107]
	v_lshlrev_b32_e32 v102, 16, v104
	v_and_b32_e32 v103, 0xffff0000, v104
	v_mul_f32_e32 v110, 0xbfb8aa3b, v102
	v_lshlrev_b32_e32 v104, 16, v105
	v_mul_f32_e32 v111, 0xbfb8aa3b, v103
	v_exp_f32_e32 v110, v110
	v_and_b32_e32 v105, 0xffff0000, v105
	v_mul_f32_e32 v112, 0xbfb8aa3b, v104
	v_exp_f32_e32 v111, v111
	v_mul_f32_e32 v113, 0xbfb8aa3b, v105
	v_exp_f32_e32 v112, v112
	v_exp_f32_e32 v113, v113
	v_add_f32_e32 v110, 1.0, v110
	v_add_f32_e32 v111, 1.0, v111
	v_div_scale_f32 v114, s[0:1], v110, v110, 1.0
	v_add_f32_e32 v112, 1.0, v112
	v_div_scale_f32 v116, s[0:1], v111, v111, 1.0
	v_rcp_f32_e32 v122, v114
	v_add_f32_e32 v113, 1.0, v113
	v_div_scale_f32 v118, s[0:1], v112, v112, 1.0
	v_rcp_f32_e32 v123, v116
	v_div_scale_f32 v120, s[0:1], v113, v113, 1.0
	v_rcp_f32_e32 v127, v118
	v_rcp_f32_e32 v130, v120
	v_fma_f32 v131, -v114, v122, 1.0
	v_div_scale_f32 v115, vcc, 1.0, v110, 1.0
	v_fma_f32 v132, -v116, v123, 1.0
	v_fmac_f32_e32 v122, v131, v122
	v_div_scale_f32 v117, s[2:3], 1.0, v111, 1.0
	v_fma_f32 v133, -v118, v127, 1.0
	v_fmac_f32_e32 v123, v132, v123
	v_mul_f32_e32 v131, v115, v122
	v_div_scale_f32 v119, s[4:5], 1.0, v112, 1.0
	v_fma_f32 v136, -v120, v130, 1.0
	v_fmac_f32_e32 v127, v133, v127
	v_mul_f32_e32 v132, v117, v123
	v_fma_f32 v137, -v114, v131, v115
	v_div_scale_f32 v121, s[6:7], 1.0, v113, 1.0
	v_fmac_f32_e32 v130, v136, v130
	v_mul_f32_e32 v133, v119, v127
	v_fma_f32 v138, -v116, v132, v117
	v_fmac_f32_e32 v131, v137, v122
	v_mul_f32_e32 v136, v121, v130
	v_fma_f32 v139, -v118, v133, v119
	v_fmac_f32_e32 v132, v138, v123
	v_fma_f32 v114, -v114, v131, v115
	v_fma_f32 v140, -v120, v136, v121
	v_fmac_f32_e32 v133, v139, v127
	v_fma_f32 v115, -v116, v132, v117
	v_div_fmas_f32 v114, v114, v122, v131
	s_mov_b64 vcc, s[2:3]
	v_fmac_f32_e32 v136, v140, v130
	v_fma_f32 v116, -v118, v133, v119
	v_div_fixup_f32 v110, v114, v110, 1.0
	v_div_fmas_f32 v114, v115, v123, v132
	s_mov_b64 vcc, s[4:5]
	v_fma_f32 v117, -v120, v136, v121
	v_mul_f32_e32 v102, v110, v102
	v_div_fixup_f32 v110, v114, v111, 1.0
	v_div_fmas_f32 v111, v116, v127, v133
	s_mov_b64 vcc, s[6:7]
	v_mul_f32_e32 v96, v96, v102
	v_mul_f32_e32 v102, v110, v103
	v_div_fixup_f32 v103, v111, v112, 1.0
	v_div_fmas_f32 v110, v117, v130, v136
	v_mul_f32_e32 v97, v97, v102
	v_mul_f32_e32 v102, v103, v104
	v_div_fixup_f32 v103, v110, v113, 1.0
	v_mul_f32_e32 v98, v98, v102
	v_mul_f32_e32 v102, v103, v105
	v_cvt_pk_bf16_f32 v96, v96, v97
	v_mul_f32_e32 v97, v99, v102
	v_cvt_pk_bf16_f32 v97, v98, v97
	flat_store_dwordx2 v[108:109], v[96:97] offset:288
	v_mov_b64_e32 v[96:97], v[178:179]
	v_lshlrev_b32_e32 v98, 16, v96
	v_and_b32_e32 v96, 0xffff0000, v96
	v_mul_f32_e32 v102, 0xbfb8aa3b, v98
	v_lshlrev_b32_e32 v99, 16, v97
	v_mul_f32_e32 v103, 0xbfb8aa3b, v96
	v_exp_f32_e32 v102, v102
	v_and_b32_e32 v97, 0xffff0000, v97
	v_mul_f32_e32 v104, 0xbfb8aa3b, v99
	v_exp_f32_e32 v103, v103
	v_mul_f32_e32 v105, 0xbfb8aa3b, v97
	v_exp_f32_e32 v104, v104
	v_exp_f32_e32 v105, v105
	v_add_f32_e32 v102, 1.0, v102
	v_add_f32_e32 v103, 1.0, v103
	v_div_scale_f32 v108, s[0:1], v102, v102, 1.0
	v_add_f32_e32 v104, 1.0, v104
	v_div_scale_f32 v110, s[0:1], v103, v103, 1.0
	v_rcp_f32_e32 v116, v108
	v_add_f32_e32 v105, 1.0, v105
	v_div_scale_f32 v112, s[0:1], v104, v104, 1.0
	v_rcp_f32_e32 v117, v110
	v_div_scale_f32 v114, s[0:1], v105, v105, 1.0
	v_rcp_f32_e32 v118, v112
	v_rcp_f32_e32 v119, v114
	v_fma_f32 v120, -v108, v116, 1.0
	v_div_scale_f32 v109, vcc, 1.0, v102, 1.0
	v_fma_f32 v121, -v110, v117, 1.0
	v_fmac_f32_e32 v116, v120, v116
	v_div_scale_f32 v111, s[2:3], 1.0, v103, 1.0
	v_fma_f32 v122, -v112, v118, 1.0
	v_fmac_f32_e32 v117, v121, v117
	v_mul_f32_e32 v120, v109, v116
	v_div_scale_f32 v113, s[4:5], 1.0, v104, 1.0
; __device__ __forceinline__ unsigned cvt_pk_bf16(float lo, float hi) { unsigned r; asm volatile("v_cvt_pk_bf16_f32 %0, %1, %2" : "=v"(r) : "v"(lo), "v"(hi)); return r; }
; __device__ __forceinline__ float sigmoidf_(float z) { return 1.0f / (1.0f + __expf(-z)); }
;     __device__ __forceinline__ void operator()(const f32x4 (&acc)[2][2][4][2], const Unit& u, int wr, int wc, int fr, int fq) const {
;     ...
;                     for (int n = 0; n < 2; ++n) { const u32x2 gw = *(const u32x2*)(G + ro + bj * HALF + n * 16); f32x4 v = acc[ai][bj][m][n];
;                         const float g0 = __uint_as_float(gw.x << 16), g1 = __uint_as_float(gw.x & 0xffff0000u), g2 = __uint_as_float(gw.y << 16), g3 = __uint_as_float(gw.y & 0xffff0000u);
;                         v[0] *= g0 * sigmoidf_(g0); v[1] *= g1 * sigmoidf_(g1); v[2] *= g2 * sigmoidf_(g2); v[3] *= g3 * sigmoidf_(g3);
;                         u32x2 w; w.x = cvt_pk_bf16(v[0], v[1]); w.y = cvt_pk_bf16(v[2], v[3]); *(u32x2*)(YC + ro + bj * HALF + n * 16) = w; } }
	v_fma_f32 v123, -v114, v119, 1.0
	v_fmac_f32_e32 v118, v122, v118
	v_mul_f32_e32 v121, v111, v117
	v_fma_f32 v127, -v108, v120, v109
	v_div_scale_f32 v115, s[6:7], 1.0, v105, 1.0
	v_fmac_f32_e32 v119, v123, v119
	v_mul_f32_e32 v122, v113, v118
	v_fma_f32 v130, -v110, v121, v111
	v_fmac_f32_e32 v120, v127, v116
	v_mul_f32_e32 v123, v115, v119
	v_fma_f32 v131, -v112, v122, v113
	v_fmac_f32_e32 v121, v130, v117
	v_fma_f32 v108, -v108, v120, v109
	v_fma_f32 v132, -v114, v123, v115
	v_fmac_f32_e32 v122, v131, v118
	v_fma_f32 v109, -v110, v121, v111
	v_div_fmas_f32 v108, v108, v116, v120
	s_mov_b64 vcc, s[2:3]
	v_fmac_f32_e32 v123, v132, v119
	v_fma_f32 v110, -v112, v122, v113
	v_div_fixup_f32 v102, v108, v102, 1.0
	v_div_fmas_f32 v108, v109, v117, v121
	s_mov_b64 vcc, s[4:5]
	v_fma_f32 v111, -v114, v123, v115
	v_mul_f32_e32 v98, v102, v98
	v_div_fixup_f32 v102, v108, v103, 1.0
	v_div_fmas_f32 v103, v110, v118, v122
	s_mov_b64 vcc, s[6:7]
	v_mul_f32_e32 v92, v92, v98
	v_mul_f32_e32 v96, v102, v96
	v_div_fixup_f32 v98, v103, v104, 1.0
	v_div_fmas_f32 v102, v111, v119, v123
	v_mul_f32_e32 v93, v93, v96
	v_mul_f32_e32 v96, v98, v99
	v_div_fixup_f32 v98, v102, v105, 1.0
	v_mul_f32_e32 v96, v94, v96
	v_mul_f32_e32 v97, v98, v97
	v_cvt_pk_bf16_f32 v94, v92, v93
	v_mul_f32_e32 v92, v95, v97
	v_cvt_pk_bf16_f32 v95, v96, v92
	v_mov_b64_e32 v[96:97], v[180:181]
	v_lshl_add_u64 v[92:93], s[12:13], 0, v[106:107]
	flat_store_dwordx2 v[92:93], v[94:95]
	v_lshlrev_b32_e32 v94, 16, v96
	v_and_b32_e32 v95, 0xffff0000, v96
	v_mul_f32_e32 v98, 0xbfb8aa3b, v94
	v_lshlrev_b32_e32 v96, 16, v97
	v_mul_f32_e32 v99, 0xbfb8aa3b, v95
	v_exp_f32_e32 v98, v98
	v_and_b32_e32 v97, 0xffff0000, v97
	v_mul_f32_e32 v102, 0xbfb8aa3b, v96
	v_exp_f32_e32 v99, v99
	v_mul_f32_e32 v103, 0xbfb8aa3b, v97
	v_exp_f32_e32 v102, v102
	v_exp_f32_e32 v103, v103
	v_add_f32_e32 v98, 1.0, v98
	v_add_f32_e32 v99, 1.0, v99
	v_div_scale_f32 v104, s[0:1], v98, v98, 1.0
	v_add_f32_e32 v102, 1.0, v102
	v_div_scale_f32 v106, s[0:1], v99, v99, 1.0
	v_rcp_f32_e32 v112, v104
	v_add_f32_e32 v103, 1.0, v103
	v_div_scale_f32 v108, s[0:1], v102, v102, 1.0
	v_rcp_f32_e32 v113, v106
	v_div_scale_f32 v110, s[0:1], v103, v103, 1.0
	v_rcp_f32_e32 v114, v108
	v_rcp_f32_e32 v115, v110
	v_fma_f32 v116, -v104, v112, 1.0
	v_div_scale_f32 v105, vcc, 1.0, v98, 1.0
	v_fma_f32 v117, -v106, v113, 1.0
	v_fmac_f32_e32 v112, v116, v112
	v_div_scale_f32 v107, s[2:3], 1.0, v99, 1.0
	v_fma_f32 v118, -v108, v114, 1.0
	v_fmac_f32_e32 v113, v117, v113
	v_mul_f32_e32 v116, v105, v112
	v_div_scale_f32 v109, s[4:5], 1.0, v102, 1.0
	v_fma_f32 v119, -v110, v115, 1.0
	v_fmac_f32_e32 v114, v118, v114
	v_mul_f32_e32 v117, v107, v113
	v_fma_f32 v120, -v104, v116, v105
	v_div_scale_f32 v111, s[6:7], 1.0, v103, 1.0
	v_fmac_f32_e32 v115, v119, v115
	v_mul_f32_e32 v118, v109, v114
	v_fma_f32 v121, -v106, v117, v107
	v_fmac_f32_e32 v116, v120, v112
	v_mul_f32_e32 v119, v111, v115
	v_fma_f32 v122, -v108, v118, v109
	v_fmac_f32_e32 v117, v121, v113
	v_fma_f32 v104, -v104, v116, v105
	v_fma_f32 v123, -v110, v119, v111
	v_fmac_f32_e32 v118, v122, v114
	v_fma_f32 v105, -v106, v117, v107
	v_div_fmas_f32 v104, v104, v112, v116
	s_mov_b64 vcc, s[2:3]
	v_fmac_f32_e32 v119, v123, v115
	v_fma_f32 v106, -v108, v118, v109
	v_div_fixup_f32 v98, v104, v98, 1.0
	v_div_fmas_f32 v104, v105, v113, v117
	s_mov_b64 vcc, s[4:5]
	v_fma_f32 v107, -v110, v119, v111
	v_mul_f32_e32 v94, v98, v94
	v_div_fixup_f32 v98, v104, v99, 1.0
	v_div_fmas_f32 v99, v106, v114, v118
	s_mov_b64 vcc, s[6:7]
	v_mul_f32_e32 v88, v88, v94
	v_mul_f32_e32 v94, v98, v95
	v_div_fixup_f32 v95, v99, v102, 1.0
	v_div_fmas_f32 v98, v107, v115, v119
	v_mul_f32_e32 v89, v89, v94
	v_mul_f32_e32 v94, v95, v96
	v_div_fixup_f32 v95, v98, v103, 1.0
	v_mul_f32_e32 v90, v90, v94
	v_mul_f32_e32 v94, v95, v97
	v_cvt_pk_bf16_f32 v88, v88, v89
	v_mul_f32_e32 v89, v91, v94
	v_cvt_pk_bf16_f32 v89, v90, v89
	v_mov_b64_e32 v[90:91], v[182:183]
	s_nop 0
	flat_store_dwordx2 v[92:93], v[88:89] offset:32
	v_lshlrev_b32_e32 v88, 16, v90
	v_and_b32_e32 v89, 0xffff0000, v90
	v_mul_f32_e32 v94, 0xbfb8aa3b, v88
	v_lshlrev_b32_e32 v90, 16, v91
	v_mul_f32_e32 v95, 0xbfb8aa3b, v89
	v_exp_f32_e32 v94, v94
	v_and_b32_e32 v91, 0xffff0000, v91
	v_mul_f32_e32 v96, 0xbfb8aa3b, v90
	v_exp_f32_e32 v95, v95
	v_mul_f32_e32 v97, 0xbfb8aa3b, v91
	v_exp_f32_e32 v96, v96
	v_exp_f32_e32 v97, v97
	v_add_f32_e32 v94, 1.0, v94
	v_add_f32_e32 v95, 1.0, v95
	v_div_scale_f32 v98, s[0:1], v94, v94, 1.0
	v_add_f32_e32 v96, 1.0, v96
	v_div_scale_f32 v102, s[0:1], v95, v95, 1.0
	v_rcp_f32_e32 v108, v98
	v_add_f32_e32 v97, 1.0, v97
	v_div_scale_f32 v104, s[0:1], v96, v96, 1.0
	v_rcp_f32_e32 v109, v102
	v_div_scale_f32 v106, s[0:1], v97, v97, 1.0
	v_rcp_f32_e32 v110, v104
	v_rcp_f32_e32 v111, v106
	v_fma_f32 v112, -v98, v108, 1.0
	v_div_scale_f32 v99, vcc, 1.0, v94, 1.0
	v_fma_f32 v113, -v102, v109, 1.0
	v_fmac_f32_e32 v108, v112, v108
	v_div_scale_f32 v103, s[2:3], 1.0, v95, 1.0
	v_fma_f32 v114, -v104, v110, 1.0
	v_fmac_f32_e32 v109, v113, v109
	v_mul_f32_e32 v112, v99, v108
	v_div_scale_f32 v105, s[4:5], 1.0, v96, 1.0
	v_fma_f32 v115, -v106, v111, 1.0
	v_fmac_f32_e32 v110, v114, v110
	v_mul_f32_e32 v113, v103, v109
	v_fma_f32 v116, -v98, v112, v99
	v_div_scale_f32 v107, s[6:7], 1.0, v97, 1.0
	v_fmac_f32_e32 v111, v115, v111
	v_mul_f32_e32 v114, v105, v110
	v_fma_f32 v117, -v102, v113, v103
	v_fmac_f32_e32 v112, v116, v108
	v_mul_f32_e32 v115, v107, v111
	v_fma_f32 v118, -v104, v114, v105
	v_fmac_f32_e32 v113, v117, v109
	v_fma_f32 v98, -v98, v112, v99
	v_fma_f32 v119, -v106, v115, v107
	v_fmac_f32_e32 v114, v118, v110
	v_fma_f32 v99, -v102, v113, v103
; __device__ __forceinline__ unsigned cvt_pk_bf16(float lo, float hi) { unsigned r; asm volatile("v_cvt_pk_bf16_f32 %0, %1, %2" : "=v"(r) : "v"(lo), "v"(hi)); return r; }
; __device__ __forceinline__ float sigmoidf_(float z) { return 1.0f / (1.0f + __expf(-z)); }
;     __device__ __forceinline__ void operator()(const f32x4 (&acc)[2][2][4][2], const Unit& u, int wr, int wc, int fr, int fq) const {
;     ...
;             for (int m = 0; m < 4; ++m) { const size_t ro = (size_t)(row0 + ai * HALF + m * 16) * 4096 + col0;
; #pragma unroll
;                 for (int bj = 0; bj < 2; ++bj)
; #pragma unroll
;                     for (int n = 0; n < 2; ++n) { const u32x2 gw = *(const u32x2*)(G + ro + bj * HALF + n * 16); f32x4 v = acc[ai][bj][m][n];
;                         const float g0 = __uint_as_float(gw.x << 16), g1 = __uint_as_float(gw.x & 0xffff0000u), g2 = __uint_as_float(gw.y << 16), g3 = __uint_as_float(gw.y & 0xffff0000u);
;                         v[0] *= g0 * sigmoidf_(g0); v[1] *= g1 * sigmoidf_(g1); v[2] *= g2 * sigmoidf_(g2); v[3] *= g3 * sigmoidf_(g3);
;                         u32x2 w; w.x = cvt_pk_bf16(v[0], v[1]); w.y = cvt_pk_bf16(v[2], v[3]); *(u32x2*)(YC + ro + bj * HALF + n * 16) = w; } }
	v_div_fmas_f32 v98, v98, v108, v112
	s_mov_b64 vcc, s[2:3]
	v_fmac_f32_e32 v115, v119, v111
	v_fma_f32 v102, -v104, v114, v105
	v_div_fixup_f32 v94, v98, v94, 1.0
	v_div_fmas_f32 v98, v99, v109, v113
	s_mov_b64 vcc, s[4:5]
	v_fma_f32 v103, -v106, v115, v107
	v_mul_f32_e32 v88, v94, v88
	v_div_fixup_f32 v94, v98, v95, 1.0
	v_div_fmas_f32 v95, v102, v110, v114
	s_mov_b64 vcc, s[6:7]
	v_mul_f32_e32 v84, v84, v88
	v_mul_f32_e32 v88, v94, v89
	v_div_fixup_f32 v89, v95, v96, 1.0
	v_div_fmas_f32 v94, v103, v111, v115
	v_mul_f32_e32 v85, v85, v88
	v_mul_f32_e32 v88, v89, v90
	v_div_fixup_f32 v89, v94, v97, 1.0
	v_mul_f32_e32 v88, v86, v88
	v_mul_f32_e32 v89, v89, v91
	v_cvt_pk_bf16_f32 v86, v84, v85
	v_mul_f32_e32 v84, v87, v89
	v_cvt_pk_bf16_f32 v87, v88, v84
	v_mov_b64_e32 v[88:89], v[184:185]
	v_or_b32_e32 v84, 48, v126
	flat_store_dwordx2 v[92:93], v[86:87] offset:256
	v_ashrrev_i32_e32 v85, 31, v84
	v_lshlrev_b64 v[84:85], 12, v[84:85]
	v_lshl_add_u64 v[84:85], v[84:85], 0, v[128:129]
	v_lshlrev_b64 v[90:91], 1, v[84:85]
	v_lshl_add_u64 v[84:85], s[8:9], 0, v[90:91]
	v_lshlrev_b32_e32 v86, 16, v88
	v_and_b32_e32 v87, 0xffff0000, v88
	v_mul_f32_e32 v94, 0xbfb8aa3b, v86
	v_lshlrev_b32_e32 v88, 16, v89
	v_mul_f32_e32 v95, 0xbfb8aa3b, v87
	v_exp_f32_e32 v94, v94
	v_and_b32_e32 v89, 0xffff0000, v89
	v_mul_f32_e32 v96, 0xbfb8aa3b, v88
	v_exp_f32_e32 v95, v95
	v_mul_f32_e32 v97, 0xbfb8aa3b, v89
	v_exp_f32_e32 v96, v96
	v_exp_f32_e32 v97, v97
	v_add_f32_e32 v94, 1.0, v94
	v_add_f32_e32 v95, 1.0, v95
	v_div_scale_f32 v98, s[0:1], v94, v94, 1.0
	v_add_f32_e32 v96, 1.0, v96
	v_div_scale_f32 v100, s[0:1], v95, v95, 1.0
	v_rcp_f32_e32 v106, v98
	v_add_f32_e32 v97, 1.0, v97
	v_div_scale_f32 v102, s[0:1], v96, v96, 1.0
	v_rcp_f32_e32 v107, v100
	v_div_scale_f32 v104, s[0:1], v97, v97, 1.0
	v_rcp_f32_e32 v108, v102
	v_rcp_f32_e32 v109, v104
	v_fma_f32 v110, -v98, v106, 1.0
	v_div_scale_f32 v99, vcc, 1.0, v94, 1.0
	v_fma_f32 v111, -v100, v107, 1.0
	v_fmac_f32_e32 v106, v110, v106
	v_div_scale_f32 v101, s[2:3], 1.0, v95, 1.0
	v_fma_f32 v112, -v102, v108, 1.0
	v_fmac_f32_e32 v107, v111, v107
	v_mul_f32_e32 v110, v99, v106
	v_div_scale_f32 v103, s[4:5], 1.0, v96, 1.0
	v_fma_f32 v113, -v104, v109, 1.0
	v_fmac_f32_e32 v108, v112, v108
	v_mul_f32_e32 v111, v101, v107
	v_fma_f32 v114, -v98, v110, v99
	v_div_scale_f32 v105, s[6:7], 1.0, v97, 1.0
	v_fmac_f32_e32 v109, v113, v109
	v_mul_f32_e32 v112, v103, v108
	v_fma_f32 v115, -v100, v111, v101
	v_fmac_f32_e32 v110, v114, v106
	v_mul_f32_e32 v113, v105, v109
	v_fma_f32 v116, -v102, v112, v103
	v_fmac_f32_e32 v111, v115, v107
	v_fma_f32 v98, -v98, v110, v99
	v_fma_f32 v117, -v104, v113, v105
	v_fmac_f32_e32 v112, v116, v108
	v_fma_f32 v99, -v100, v111, v101
	v_div_fmas_f32 v98, v98, v106, v110
	s_mov_b64 vcc, s[2:3]
	v_fmac_f32_e32 v113, v117, v109
	v_fma_f32 v100, -v102, v112, v103
	v_div_fixup_f32 v94, v98, v94, 1.0
	v_div_fmas_f32 v98, v99, v107, v111
	s_mov_b64 vcc, s[4:5]
	v_fma_f32 v101, -v104, v113, v105
	v_mul_f32_e32 v86, v94, v86
	v_div_fixup_f32 v94, v98, v95, 1.0
	v_div_fmas_f32 v95, v100, v108, v112
	s_mov_b64 vcc, s[6:7]
	v_mul_f32_e32 v80, v80, v86
	v_mul_f32_e32 v86, v94, v87
	v_div_fixup_f32 v87, v95, v96, 1.0
	v_div_fmas_f32 v94, v101, v109, v113
	v_mul_f32_e32 v81, v81, v86
	v_mul_f32_e32 v86, v87, v88
	v_div_fixup_f32 v87, v94, v97, 1.0
	v_mul_f32_e32 v82, v82, v86
	v_mul_f32_e32 v86, v87, v89
	v_cvt_pk_bf16_f32 v80, v80, v81
	v_mul_f32_e32 v81, v83, v86
	v_cvt_pk_bf16_f32 v81, v82, v81
	flat_store_dwordx2 v[92:93], v[80:81] offset:288
	v_mov_b64_e32 v[80:81], v[186:187]
	v_lshlrev_b32_e32 v82, 16, v80
	v_and_b32_e32 v80, 0xffff0000, v80
	v_mul_f32_e32 v86, 0xbfb8aa3b, v82
	v_lshlrev_b32_e32 v83, 16, v81
	v_mul_f32_e32 v87, 0xbfb8aa3b, v80
	v_exp_f32_e32 v86, v86
	v_and_b32_e32 v81, 0xffff0000, v81
	v_mul_f32_e32 v88, 0xbfb8aa3b, v83
	v_exp_f32_e32 v87, v87
	v_mul_f32_e32 v89, 0xbfb8aa3b, v81
	v_exp_f32_e32 v88, v88
	v_exp_f32_e32 v89, v89
	v_add_f32_e32 v86, 1.0, v86
	v_add_f32_e32 v87, 1.0, v87
	v_div_scale_f32 v92, s[0:1], v86, v86, 1.0
	v_add_f32_e32 v88, 1.0, v88
	v_div_scale_f32 v94, s[0:1], v87, v87, 1.0
	v_rcp_f32_e32 v100, v92
	v_add_f32_e32 v89, 1.0, v89
	v_div_scale_f32 v96, s[0:1], v88, v88, 1.0
	v_rcp_f32_e32 v101, v94
	v_div_scale_f32 v98, s[0:1], v89, v89, 1.0
	v_rcp_f32_e32 v102, v96
	v_rcp_f32_e32 v103, v98
	v_fma_f32 v104, -v92, v100, 1.0
	v_div_scale_f32 v93, vcc, 1.0, v86, 1.0
	v_fma_f32 v105, -v94, v101, 1.0
	v_fmac_f32_e32 v100, v104, v100
	v_div_scale_f32 v95, s[2:3], 1.0, v87, 1.0
	v_fma_f32 v106, -v96, v102, 1.0
	v_fmac_f32_e32 v101, v105, v101
	v_mul_f32_e32 v104, v93, v100
	v_div_scale_f32 v97, s[4:5], 1.0, v88, 1.0
	v_fma_f32 v107, -v98, v103, 1.0
	v_fmac_f32_e32 v102, v106, v102
	v_mul_f32_e32 v105, v95, v101
	v_fma_f32 v108, -v92, v104, v93
	v_div_scale_f32 v99, s[6:7], 1.0, v89, 1.0
	v_fmac_f32_e32 v103, v107, v103
	v_mul_f32_e32 v106, v97, v102
	v_fma_f32 v109, -v94, v105, v95
	v_fmac_f32_e32 v104, v108, v100
	v_mul_f32_e32 v107, v99, v103
	v_fma_f32 v110, -v96, v106, v97
	v_fmac_f32_e32 v105, v109, v101
	v_fma_f32 v92, -v92, v104, v93
	v_fma_f32 v111, -v98, v107, v99
	v_fmac_f32_e32 v106, v110, v102
	v_fma_f32 v93, -v94, v105, v95
	v_div_fmas_f32 v92, v92, v100, v104
	s_mov_b64 vcc, s[2:3]
	v_fmac_f32_e32 v107, v111, v103
	v_fma_f32 v94, -v96, v106, v97
	v_div_fixup_f32 v86, v92, v86, 1.0
	v_div_fmas_f32 v92, v93, v101, v105
	s_mov_b64 vcc, s[4:5]
	v_fma_f32 v95, -v98, v107, v99
	v_mul_f32_e32 v82, v86, v82
	v_div_fixup_f32 v86, v92, v87, 1.0
	v_div_fmas_f32 v87, v94, v102, v106
	s_mov_b64 vcc, s[6:7]
	v_mul_f32_e32 v76, v76, v82
	v_mul_f32_e32 v80, v86, v80
; __device__ __forceinline__ unsigned cvt_pk_bf16(float lo, float hi) { unsigned r; asm volatile("v_cvt_pk_bf16_f32 %0, %1, %2" : "=v"(r) : "v"(lo), "v"(hi)); return r; }
; __device__ __forceinline__ float sigmoidf_(float z) { return 1.0f / (1.0f + __expf(-z)); }
;     __device__ __forceinline__ void operator()(const f32x4 (&acc)[2][2][4][2], const Unit& u, int wr, int wc, int fr, int fq) const {
;     ...
;                     for (int n = 0; n < 2; ++n) { const u32x2 gw = *(const u32x2*)(G + ro + bj * HALF + n * 16); f32x4 v = acc[ai][bj][m][n];
;                         const float g0 = __uint_as_float(gw.x << 16), g1 = __uint_as_float(gw.x & 0xffff0000u), g2 = __uint_as_float(gw.y << 16), g3 = __uint_as_float(gw.y & 0xffff0000u);
;                         v[0] *= g0 * sigmoidf_(g0); v[1] *= g1 * sigmoidf_(g1); v[2] *= g2 * sigmoidf_(g2); v[3] *= g3 * sigmoidf_(g3);
;                         u32x2 w; w.x = cvt_pk_bf16(v[0], v[1]); w.y = cvt_pk_bf16(v[2], v[3]); *(u32x2*)(YC + ro + bj * HALF + n * 16) = w; } }
	v_div_fixup_f32 v82, v87, v88, 1.0
	v_div_fmas_f32 v86, v95, v103, v107
	v_mul_f32_e32 v77, v77, v80
	v_mul_f32_e32 v80, v82, v83
	v_div_fixup_f32 v82, v86, v89, 1.0
	v_mul_f32_e32 v80, v78, v80
	v_mul_f32_e32 v81, v82, v81
	v_cvt_pk_bf16_f32 v78, v76, v77
	v_mul_f32_e32 v76, v79, v81
	v_cvt_pk_bf16_f32 v79, v80, v76
	v_mov_b64_e32 v[80:81], v[188:189]
	v_lshl_add_u64 v[76:77], s[12:13], 0, v[90:91]
	flat_store_dwordx2 v[76:77], v[78:79]
	v_lshlrev_b32_e32 v78, 16, v80
	v_and_b32_e32 v79, 0xffff0000, v80
	v_mul_f32_e32 v82, 0xbfb8aa3b, v78
	v_lshlrev_b32_e32 v80, 16, v81
	v_mul_f32_e32 v83, 0xbfb8aa3b, v79
	v_exp_f32_e32 v82, v82
	v_and_b32_e32 v81, 0xffff0000, v81
	v_mul_f32_e32 v86, 0xbfb8aa3b, v80
	v_exp_f32_e32 v83, v83
	v_mul_f32_e32 v87, 0xbfb8aa3b, v81
	v_exp_f32_e32 v86, v86
	v_exp_f32_e32 v87, v87
	v_add_f32_e32 v82, 1.0, v82
	v_add_f32_e32 v83, 1.0, v83
	v_div_scale_f32 v88, s[0:1], v82, v82, 1.0
	v_add_f32_e32 v86, 1.0, v86
	v_div_scale_f32 v90, s[0:1], v83, v83, 1.0
	v_rcp_f32_e32 v96, v88
	v_add_f32_e32 v87, 1.0, v87
	v_div_scale_f32 v92, s[0:1], v86, v86, 1.0
	v_rcp_f32_e32 v97, v90
	v_div_scale_f32 v94, s[0:1], v87, v87, 1.0
	v_rcp_f32_e32 v98, v92
	v_rcp_f32_e32 v99, v94
	v_fma_f32 v100, -v88, v96, 1.0
	v_div_scale_f32 v89, vcc, 1.0, v82, 1.0
	v_fma_f32 v101, -v90, v97, 1.0
	v_fmac_f32_e32 v96, v100, v96
	v_div_scale_f32 v91, s[2:3], 1.0, v83, 1.0
	v_fma_f32 v102, -v92, v98, 1.0
	v_fmac_f32_e32 v97, v101, v97
	v_mul_f32_e32 v100, v89, v96
	v_div_scale_f32 v93, s[4:5], 1.0, v86, 1.0
	v_fma_f32 v103, -v94, v99, 1.0
	v_fmac_f32_e32 v98, v102, v98
	v_mul_f32_e32 v101, v91, v97
	v_fma_f32 v104, -v88, v100, v89
	v_div_scale_f32 v95, s[6:7], 1.0, v87, 1.0
	v_fmac_f32_e32 v99, v103, v99
	v_mul_f32_e32 v102, v93, v98
	v_fma_f32 v105, -v90, v101, v91
	v_fmac_f32_e32 v100, v104, v96
	v_mul_f32_e32 v103, v95, v99
	v_fma_f32 v106, -v92, v102, v93
	v_fmac_f32_e32 v101, v105, v97
	v_fma_f32 v88, -v88, v100, v89
	v_fma_f32 v107, -v94, v103, v95
	v_fmac_f32_e32 v102, v106, v98
	v_fma_f32 v89, -v90, v101, v91
	v_div_fmas_f32 v88, v88, v96, v100
	s_mov_b64 vcc, s[2:3]
	v_fmac_f32_e32 v103, v107, v99
	v_fma_f32 v90, -v92, v102, v93
	v_div_fixup_f32 v82, v88, v82, 1.0
	v_div_fmas_f32 v88, v89, v97, v101
	s_mov_b64 vcc, s[4:5]
	v_fma_f32 v91, -v94, v103, v95
	v_mul_f32_e32 v78, v82, v78
	v_div_fixup_f32 v82, v88, v83, 1.0
	v_div_fmas_f32 v83, v90, v98, v102
	s_mov_b64 vcc, s[6:7]
	v_mul_f32_e32 v72, v72, v78
	v_mul_f32_e32 v78, v82, v79
	v_div_fixup_f32 v79, v83, v86, 1.0
	v_div_fmas_f32 v82, v91, v99, v103
	v_mul_f32_e32 v73, v73, v78
	v_mul_f32_e32 v78, v79, v80
	v_div_fixup_f32 v79, v82, v87, 1.0
	v_mul_f32_e32 v74, v74, v78
	v_mul_f32_e32 v78, v79, v81
	v_cvt_pk_bf16_f32 v72, v72, v73
	v_mul_f32_e32 v73, v75, v78
	v_cvt_pk_bf16_f32 v73, v74, v73
	v_mov_b64_e32 v[74:75], v[190:191]
	s_nop 0
	flat_store_dwordx2 v[76:77], v[72:73] offset:32
	v_lshlrev_b32_e32 v72, 16, v74
	v_and_b32_e32 v73, 0xffff0000, v74
	v_mul_f32_e32 v78, 0xbfb8aa3b, v72
	v_lshlrev_b32_e32 v74, 16, v75
	v_mul_f32_e32 v79, 0xbfb8aa3b, v73
	v_exp_f32_e32 v78, v78
	v_and_b32_e32 v75, 0xffff0000, v75
	v_mul_f32_e32 v80, 0xbfb8aa3b, v74
	v_exp_f32_e32 v79, v79
	v_mul_f32_e32 v81, 0xbfb8aa3b, v75
	v_exp_f32_e32 v80, v80
	v_exp_f32_e32 v81, v81
	v_add_f32_e32 v78, 1.0, v78
	v_add_f32_e32 v79, 1.0, v79
	v_div_scale_f32 v82, s[0:1], v78, v78, 1.0
	v_add_f32_e32 v80, 1.0, v80
	v_div_scale_f32 v86, s[0:1], v79, v79, 1.0
	v_rcp_f32_e32 v92, v82
	v_add_f32_e32 v81, 1.0, v81
	v_div_scale_f32 v88, s[0:1], v80, v80, 1.0
	v_rcp_f32_e32 v93, v86
	v_div_scale_f32 v90, s[0:1], v81, v81, 1.0
	v_rcp_f32_e32 v94, v88
	v_rcp_f32_e32 v95, v90
	v_fma_f32 v96, -v82, v92, 1.0
	v_div_scale_f32 v83, vcc, 1.0, v78, 1.0
	v_fma_f32 v97, -v86, v93, 1.0
	v_fmac_f32_e32 v92, v96, v92
	v_div_scale_f32 v87, s[2:3], 1.0, v79, 1.0
	v_fma_f32 v98, -v88, v94, 1.0
	v_fmac_f32_e32 v93, v97, v93
	v_mul_f32_e32 v96, v83, v92
	v_div_scale_f32 v89, s[4:5], 1.0, v80, 1.0
	v_fma_f32 v99, -v90, v95, 1.0
	v_fmac_f32_e32 v94, v98, v94
	v_mul_f32_e32 v97, v87, v93
	v_fma_f32 v100, -v82, v96, v83
	v_div_scale_f32 v91, s[6:7], 1.0, v81, 1.0
	v_fmac_f32_e32 v95, v99, v95
	v_mul_f32_e32 v98, v89, v94
	v_fma_f32 v101, -v86, v97, v87
	v_fmac_f32_e32 v96, v100, v92
	v_mul_f32_e32 v99, v91, v95
	v_fma_f32 v102, -v88, v98, v89
	v_fmac_f32_e32 v97, v101, v93
	v_fma_f32 v82, -v82, v96, v83
	v_fma_f32 v103, -v90, v99, v91
	v_fmac_f32_e32 v98, v102, v94
	v_fma_f32 v83, -v86, v97, v87
	v_div_fmas_f32 v82, v82, v92, v96
	s_mov_b64 vcc, s[2:3]
	v_fmac_f32_e32 v99, v103, v95
	v_fma_f32 v86, -v88, v98, v89
	v_div_fixup_f32 v78, v82, v78, 1.0
	v_div_fmas_f32 v82, v83, v93, v97
	s_mov_b64 vcc, s[4:5]
	v_fma_f32 v87, -v90, v99, v91
	v_mul_f32_e32 v72, v78, v72
	v_div_fixup_f32 v78, v82, v79, 1.0
	v_div_fmas_f32 v79, v86, v94, v98
	s_mov_b64 vcc, s[6:7]
	v_mul_f32_e32 v68, v68, v72
	v_mul_f32_e32 v72, v78, v73
	v_div_fixup_f32 v73, v79, v80, 1.0
	v_div_fmas_f32 v78, v87, v95, v99
	v_mul_f32_e32 v69, v69, v72
	v_mul_f32_e32 v72, v73, v74
	v_div_fixup_f32 v73, v78, v81, 1.0
	v_mul_f32_e32 v72, v70, v72
	v_mul_f32_e32 v73, v73, v75
	v_cvt_pk_bf16_f32 v70, v68, v69
	v_mul_f32_e32 v68, v71, v73
	v_cvt_pk_bf16_f32 v71, v72, v68
	v_mov_b64_e32 v[72:73], v[192:193]
	v_lshl_add_u64 v[74:75], v[124:125], 0, s[40:41]
	flat_store_dwordx2 v[76:77], v[70:71] offset:256
	v_lshl_add_u64 v[68:69], s[8:9], 0, v[74:75]
	v_lshlrev_b32_e32 v70, 16, v72
	v_and_b32_e32 v71, 0xffff0000, v72
	v_mul_f32_e32 v78, 0xbfb8aa3b, v70
	v_lshlrev_b32_e32 v72, 16, v73
	v_mul_f32_e32 v79, 0xbfb8aa3b, v71
	v_exp_f32_e32 v78, v78
	v_and_b32_e32 v73, 0xffff0000, v73
; __device__ __forceinline__ unsigned cvt_pk_bf16(float lo, float hi) { unsigned r; asm volatile("v_cvt_pk_bf16_f32 %0, %1, %2" : "=v"(r) : "v"(lo), "v"(hi)); return r; }
; __device__ __forceinline__ float sigmoidf_(float z) { return 1.0f / (1.0f + __expf(-z)); }
;     __device__ __forceinline__ void operator()(const f32x4 (&acc)[2][2][4][2], const Unit& u, int wr, int wc, int fr, int fq) const {
;     ...
;                     for (int n = 0; n < 2; ++n) { const u32x2 gw = *(const u32x2*)(G + ro + bj * HALF + n * 16); f32x4 v = acc[ai][bj][m][n];
;                         const float g0 = __uint_as_float(gw.x << 16), g1 = __uint_as_float(gw.x & 0xffff0000u), g2 = __uint_as_float(gw.y << 16), g3 = __uint_as_float(gw.y & 0xffff0000u);
;                         v[0] *= g0 * sigmoidf_(g0); v[1] *= g1 * sigmoidf_(g1); v[2] *= g2 * sigmoidf_(g2); v[3] *= g3 * sigmoidf_(g3);
;                         u32x2 w; w.x = cvt_pk_bf16(v[0], v[1]); w.y = cvt_pk_bf16(v[2], v[3]); *(u32x2*)(YC + ro + bj * HALF + n * 16) = w; } }
	v_mul_f32_e32 v80, 0xbfb8aa3b, v72
	v_exp_f32_e32 v79, v79
	v_mul_f32_e32 v81, 0xbfb8aa3b, v73
	v_exp_f32_e32 v80, v80
	v_exp_f32_e32 v81, v81
	v_add_f32_e32 v78, 1.0, v78
	v_add_f32_e32 v79, 1.0, v79
	v_div_scale_f32 v82, s[0:1], v78, v78, 1.0
	v_add_f32_e32 v80, 1.0, v80
	v_div_scale_f32 v84, s[0:1], v79, v79, 1.0
	v_rcp_f32_e32 v90, v82
	v_add_f32_e32 v81, 1.0, v81
	v_div_scale_f32 v86, s[0:1], v80, v80, 1.0
	v_rcp_f32_e32 v91, v84
	v_div_scale_f32 v88, s[0:1], v81, v81, 1.0
	v_rcp_f32_e32 v92, v86
	v_rcp_f32_e32 v93, v88
	v_fma_f32 v94, -v82, v90, 1.0
	v_div_scale_f32 v83, vcc, 1.0, v78, 1.0
	v_fma_f32 v95, -v84, v91, 1.0
	v_fmac_f32_e32 v90, v94, v90
	v_div_scale_f32 v85, s[2:3], 1.0, v79, 1.0
	v_fma_f32 v96, -v86, v92, 1.0
	v_fmac_f32_e32 v91, v95, v91
	v_mul_f32_e32 v94, v83, v90
	v_div_scale_f32 v87, s[4:5], 1.0, v80, 1.0
	v_fma_f32 v97, -v88, v93, 1.0
	v_fmac_f32_e32 v92, v96, v92
	v_mul_f32_e32 v95, v85, v91
	v_fma_f32 v98, -v82, v94, v83
	v_div_scale_f32 v89, s[6:7], 1.0, v81, 1.0
	v_fmac_f32_e32 v93, v97, v93
	v_mul_f32_e32 v96, v87, v92
	v_fma_f32 v99, -v84, v95, v85
	v_fmac_f32_e32 v94, v98, v90
	v_mul_f32_e32 v97, v89, v93
	v_fma_f32 v100, -v86, v96, v87
	v_fmac_f32_e32 v95, v99, v91
	v_fma_f32 v82, -v82, v94, v83
	v_fma_f32 v101, -v88, v97, v89
	v_fmac_f32_e32 v96, v100, v92
	v_fma_f32 v83, -v84, v95, v85
	v_div_fmas_f32 v82, v82, v90, v94
	s_mov_b64 vcc, s[2:3]
	v_fmac_f32_e32 v97, v101, v93
	v_fma_f32 v84, -v86, v96, v87
	v_div_fixup_f32 v78, v82, v78, 1.0
	v_div_fmas_f32 v82, v83, v91, v95
	s_mov_b64 vcc, s[4:5]
	v_fma_f32 v85, -v88, v97, v89
	v_mul_f32_e32 v70, v78, v70
	v_div_fixup_f32 v78, v82, v79, 1.0
	v_div_fmas_f32 v79, v84, v92, v96
	s_mov_b64 vcc, s[6:7]
	v_mul_f32_e32 v64, v64, v70
	v_mul_f32_e32 v70, v78, v71
	v_div_fixup_f32 v71, v79, v80, 1.0
	v_div_fmas_f32 v78, v85, v93, v97
	v_mul_f32_e32 v65, v65, v70
	v_mul_f32_e32 v70, v71, v72
	v_div_fixup_f32 v71, v78, v81, 1.0
	v_mul_f32_e32 v66, v66, v70
	v_mul_f32_e32 v70, v71, v73
	v_cvt_pk_bf16_f32 v64, v64, v65
	v_mul_f32_e32 v65, v67, v70
	v_cvt_pk_bf16_f32 v65, v66, v65
	flat_store_dwordx2 v[76:77], v[64:65] offset:288
	v_mov_b64_e32 v[64:65], v[194:195]
	v_lshlrev_b32_e32 v66, 16, v64
	v_and_b32_e32 v64, 0xffff0000, v64
	v_mul_f32_e32 v70, 0xbfb8aa3b, v66
	v_lshlrev_b32_e32 v67, 16, v65
	v_mul_f32_e32 v71, 0xbfb8aa3b, v64
	v_exp_f32_e32 v70, v70
	v_and_b32_e32 v65, 0xffff0000, v65
	v_mul_f32_e32 v72, 0xbfb8aa3b, v67
	v_exp_f32_e32 v71, v71
	v_mul_f32_e32 v73, 0xbfb8aa3b, v65
	v_exp_f32_e32 v72, v72
	v_exp_f32_e32 v73, v73
	v_add_f32_e32 v70, 1.0, v70
	v_add_f32_e32 v71, 1.0, v71
	v_div_scale_f32 v76, s[0:1], v70, v70, 1.0
	v_add_f32_e32 v72, 1.0, v72
	v_div_scale_f32 v78, s[0:1], v71, v71, 1.0
	v_rcp_f32_e32 v84, v76
	v_add_f32_e32 v73, 1.0, v73
	v_div_scale_f32 v80, s[0:1], v72, v72, 1.0
	v_rcp_f32_e32 v85, v78
	v_div_scale_f32 v82, s[0:1], v73, v73, 1.0
	v_rcp_f32_e32 v86, v80
	v_rcp_f32_e32 v87, v82
	v_fma_f32 v88, -v76, v84, 1.0
	v_div_scale_f32 v77, vcc, 1.0, v70, 1.0
	v_fma_f32 v89, -v78, v85, 1.0
	v_fmac_f32_e32 v84, v88, v84
	v_div_scale_f32 v79, s[2:3], 1.0, v71, 1.0
	v_fma_f32 v90, -v80, v86, 1.0
	v_fmac_f32_e32 v85, v89, v85
	v_mul_f32_e32 v88, v77, v84
	v_div_scale_f32 v81, s[4:5], 1.0, v72, 1.0
	v_fma_f32 v91, -v82, v87, 1.0
	v_fmac_f32_e32 v86, v90, v86
	v_mul_f32_e32 v89, v79, v85
	v_fma_f32 v92, -v76, v88, v77
	v_div_scale_f32 v83, s[6:7], 1.0, v73, 1.0
	v_fmac_f32_e32 v87, v91, v87
	v_mul_f32_e32 v90, v81, v86
	v_fma_f32 v93, -v78, v89, v79
	v_fmac_f32_e32 v88, v92, v84
	v_mul_f32_e32 v91, v83, v87
	v_fma_f32 v94, -v80, v90, v81
	v_fmac_f32_e32 v89, v93, v85
	v_fma_f32 v76, -v76, v88, v77
	v_fma_f32 v95, -v82, v91, v83
	v_fmac_f32_e32 v90, v94, v86
	v_fma_f32 v77, -v78, v89, v79
	v_div_fmas_f32 v76, v76, v84, v88
	s_mov_b64 vcc, s[2:3]
	v_fmac_f32_e32 v91, v95, v87
	v_fma_f32 v78, -v80, v90, v81
	v_div_fixup_f32 v70, v76, v70, 1.0
	v_div_fmas_f32 v76, v77, v85, v89
	s_mov_b64 vcc, s[4:5]
	v_fma_f32 v79, -v82, v91, v83
	v_mul_f32_e32 v66, v70, v66
	v_div_fixup_f32 v70, v76, v71, 1.0
	v_div_fmas_f32 v71, v78, v86, v90
	s_mov_b64 vcc, s[6:7]
	v_mul_f32_e32 v60, v60, v66
	v_mul_f32_e32 v64, v70, v64
	v_div_fixup_f32 v66, v71, v72, 1.0
	v_div_fmas_f32 v70, v79, v87, v91
	v_mul_f32_e32 v61, v61, v64
	v_mul_f32_e32 v64, v66, v67
	v_div_fixup_f32 v66, v70, v73, 1.0
	v_mul_f32_e32 v64, v62, v64
	v_mul_f32_e32 v65, v66, v65
	v_cvt_pk_bf16_f32 v62, v60, v61
	v_mul_f32_e32 v60, v63, v65
	v_cvt_pk_bf16_f32 v63, v64, v60
	v_mov_b64_e32 v[64:65], v[196:197]
	v_lshl_add_u64 v[60:61], s[12:13], 0, v[74:75]
	flat_store_dwordx2 v[60:61], v[62:63]
	v_lshlrev_b32_e32 v62, 16, v64
	v_and_b32_e32 v63, 0xffff0000, v64
	v_mul_f32_e32 v66, 0xbfb8aa3b, v62
	v_lshlrev_b32_e32 v64, 16, v65
	v_mul_f32_e32 v67, 0xbfb8aa3b, v63
	v_exp_f32_e32 v66, v66
	v_and_b32_e32 v65, 0xffff0000, v65
	v_mul_f32_e32 v70, 0xbfb8aa3b, v64
	v_exp_f32_e32 v67, v67
	v_mul_f32_e32 v71, 0xbfb8aa3b, v65
	v_exp_f32_e32 v70, v70
	v_exp_f32_e32 v71, v71
	v_add_f32_e32 v66, 1.0, v66
	v_add_f32_e32 v67, 1.0, v67
	v_div_scale_f32 v72, s[0:1], v66, v66, 1.0
	v_add_f32_e32 v70, 1.0, v70
	v_div_scale_f32 v74, s[0:1], v67, v67, 1.0
	v_rcp_f32_e32 v80, v72
	v_add_f32_e32 v71, 1.0, v71
	v_div_scale_f32 v76, s[0:1], v70, v70, 1.0
	v_rcp_f32_e32 v81, v74
	v_div_scale_f32 v78, s[0:1], v71, v71, 1.0
	v_rcp_f32_e32 v82, v76
	v_rcp_f32_e32 v83, v78
	v_fma_f32 v84, -v72, v80, 1.0
	v_div_scale_f32 v73, vcc, 1.0, v66, 1.0
	v_fma_f32 v85, -v74, v81, 1.0
	v_fmac_f32_e32 v80, v84, v80
	v_div_scale_f32 v75, s[2:3], 1.0, v67, 1.0
	v_fma_f32 v86, -v76, v82, 1.0
	v_fmac_f32_e32 v81, v85, v81
	v_mul_f32_e32 v84, v73, v80
; __device__ __forceinline__ unsigned cvt_pk_bf16(float lo, float hi) { unsigned r; asm volatile("v_cvt_pk_bf16_f32 %0, %1, %2" : "=v"(r) : "v"(lo), "v"(hi)); return r; }
; __device__ __forceinline__ float sigmoidf_(float z) { return 1.0f / (1.0f + __expf(-z)); }
;     __device__ __forceinline__ void operator()(const f32x4 (&acc)[2][2][4][2], const Unit& u, int wr, int wc, int fr, int fq) const {
;     ...
;             for (int m = 0; m < 4; ++m) { const size_t ro = (size_t)(row0 + ai * HALF + m * 16) * 4096 + col0;
; #pragma unroll
;                 for (int bj = 0; bj < 2; ++bj)
; #pragma unroll
;                     for (int n = 0; n < 2; ++n) { const u32x2 gw = *(const u32x2*)(G + ro + bj * HALF + n * 16); f32x4 v = acc[ai][bj][m][n];
;                         const float g0 = __uint_as_float(gw.x << 16), g1 = __uint_as_float(gw.x & 0xffff0000u), g2 = __uint_as_float(gw.y << 16), g3 = __uint_as_float(gw.y & 0xffff0000u);
;                         v[0] *= g0 * sigmoidf_(g0); v[1] *= g1 * sigmoidf_(g1); v[2] *= g2 * sigmoidf_(g2); v[3] *= g3 * sigmoidf_(g3);
;                         u32x2 w; w.x = cvt_pk_bf16(v[0], v[1]); w.y = cvt_pk_bf16(v[2], v[3]); *(u32x2*)(YC + ro + bj * HALF + n * 16) = w; } }
	v_div_scale_f32 v77, s[4:5], 1.0, v70, 1.0
	v_fma_f32 v87, -v78, v83, 1.0
	v_fmac_f32_e32 v82, v86, v82
	v_mul_f32_e32 v85, v75, v81
	v_fma_f32 v88, -v72, v84, v73
	v_div_scale_f32 v79, s[6:7], 1.0, v71, 1.0
	v_fmac_f32_e32 v83, v87, v83
	v_mul_f32_e32 v86, v77, v82
	v_fma_f32 v89, -v74, v85, v75
	v_fmac_f32_e32 v84, v88, v80
	v_mul_f32_e32 v87, v79, v83
	v_fma_f32 v90, -v76, v86, v77
	v_fmac_f32_e32 v85, v89, v81
	v_fma_f32 v72, -v72, v84, v73
	v_fma_f32 v91, -v78, v87, v79
	v_fmac_f32_e32 v86, v90, v82
	v_fma_f32 v73, -v74, v85, v75
	v_div_fmas_f32 v72, v72, v80, v84
	s_mov_b64 vcc, s[2:3]
	v_fmac_f32_e32 v87, v91, v83
	v_fma_f32 v74, -v76, v86, v77
	v_div_fixup_f32 v66, v72, v66, 1.0
	v_div_fmas_f32 v72, v73, v81, v85
	s_mov_b64 vcc, s[4:5]
	v_fma_f32 v75, -v78, v87, v79
	v_mul_f32_e32 v62, v66, v62
	v_div_fixup_f32 v66, v72, v67, 1.0
	v_div_fmas_f32 v67, v74, v82, v86
	s_mov_b64 vcc, s[6:7]
	v_mul_f32_e32 v56, v56, v62
	v_mul_f32_e32 v62, v66, v63
	v_div_fixup_f32 v63, v67, v70, 1.0
	v_div_fmas_f32 v66, v75, v83, v87
	v_mul_f32_e32 v57, v57, v62
	v_mul_f32_e32 v62, v63, v64
	v_div_fixup_f32 v63, v66, v71, 1.0
	v_mul_f32_e32 v58, v58, v62
	v_mul_f32_e32 v62, v63, v65
	v_cvt_pk_bf16_f32 v56, v56, v57
	v_mul_f32_e32 v57, v59, v62
	v_cvt_pk_bf16_f32 v57, v58, v57
	v_mov_b64_e32 v[58:59], v[198:199]
	s_nop 0
	flat_store_dwordx2 v[60:61], v[56:57] offset:32
	v_lshlrev_b32_e32 v56, 16, v58
	v_and_b32_e32 v57, 0xffff0000, v58
	v_mul_f32_e32 v62, 0xbfb8aa3b, v56
	v_lshlrev_b32_e32 v58, 16, v59
	v_mul_f32_e32 v63, 0xbfb8aa3b, v57
	v_exp_f32_e32 v62, v62
	v_and_b32_e32 v59, 0xffff0000, v59
	v_mul_f32_e32 v64, 0xbfb8aa3b, v58
	v_exp_f32_e32 v63, v63
	v_mul_f32_e32 v65, 0xbfb8aa3b, v59
	v_exp_f32_e32 v64, v64
	v_exp_f32_e32 v65, v65
	v_add_f32_e32 v62, 1.0, v62
	v_add_f32_e32 v63, 1.0, v63
	v_div_scale_f32 v66, s[0:1], v62, v62, 1.0
	v_add_f32_e32 v64, 1.0, v64
	v_div_scale_f32 v70, s[0:1], v63, v63, 1.0
	v_rcp_f32_e32 v76, v66
	v_add_f32_e32 v65, 1.0, v65
	v_div_scale_f32 v72, s[0:1], v64, v64, 1.0
	v_rcp_f32_e32 v77, v70
	v_div_scale_f32 v74, s[0:1], v65, v65, 1.0
	v_rcp_f32_e32 v78, v72
	v_rcp_f32_e32 v79, v74
	v_fma_f32 v80, -v66, v76, 1.0
	v_div_scale_f32 v67, vcc, 1.0, v62, 1.0
	v_fma_f32 v81, -v70, v77, 1.0
	v_fmac_f32_e32 v76, v80, v76
	v_div_scale_f32 v71, s[2:3], 1.0, v63, 1.0
	v_fma_f32 v82, -v72, v78, 1.0
	v_fmac_f32_e32 v77, v81, v77
	v_mul_f32_e32 v80, v67, v76
	v_div_scale_f32 v73, s[4:5], 1.0, v64, 1.0
	v_fma_f32 v83, -v74, v79, 1.0
	v_fmac_f32_e32 v78, v82, v78
	v_mul_f32_e32 v81, v71, v77
	v_fma_f32 v84, -v66, v80, v67
	v_div_scale_f32 v75, s[6:7], 1.0, v65, 1.0
	v_fmac_f32_e32 v79, v83, v79
	v_mul_f32_e32 v82, v73, v78
	v_fma_f32 v85, -v70, v81, v71
	v_fmac_f32_e32 v80, v84, v76
	v_mul_f32_e32 v83, v75, v79
	v_fma_f32 v86, -v72, v82, v73
	v_fmac_f32_e32 v81, v85, v77
	v_fma_f32 v66, -v66, v80, v67
	v_fma_f32 v87, -v74, v83, v75
	v_fmac_f32_e32 v82, v86, v78
	v_fma_f32 v67, -v70, v81, v71
	v_div_fmas_f32 v66, v66, v76, v80
	s_mov_b64 vcc, s[2:3]
	v_fmac_f32_e32 v83, v87, v79
	v_fma_f32 v70, -v72, v82, v73
	v_div_fixup_f32 v62, v66, v62, 1.0
	v_div_fmas_f32 v66, v67, v77, v81
	s_mov_b64 vcc, s[4:5]
	v_fma_f32 v71, -v74, v83, v75
	v_mul_f32_e32 v56, v62, v56
	v_div_fixup_f32 v62, v66, v63, 1.0
	v_div_fmas_f32 v63, v70, v78, v82
	s_mov_b64 vcc, s[6:7]
	v_mul_f32_e32 v52, v52, v56
	v_mul_f32_e32 v56, v62, v57
	v_div_fixup_f32 v57, v63, v64, 1.0
	v_div_fmas_f32 v62, v71, v79, v83
	v_mul_f32_e32 v53, v53, v56
	v_mul_f32_e32 v56, v57, v58
	v_div_fixup_f32 v57, v62, v65, 1.0
	v_mul_f32_e32 v56, v54, v56
	v_mul_f32_e32 v57, v57, v59
	v_cvt_pk_bf16_f32 v54, v52, v53
	v_mul_f32_e32 v52, v55, v57
	v_cvt_pk_bf16_f32 v55, v56, v52
	v_mov_b64_e32 v[56:57], v[200:201]
	v_lshl_add_u64 v[58:59], v[124:125], 0, s[42:43]
	flat_store_dwordx2 v[60:61], v[54:55] offset:256
	v_lshl_add_u64 v[52:53], s[8:9], 0, v[58:59]
	v_lshlrev_b32_e32 v54, 16, v56
	v_and_b32_e32 v55, 0xffff0000, v56
	v_mul_f32_e32 v62, 0xbfb8aa3b, v54
	v_lshlrev_b32_e32 v56, 16, v57
	v_mul_f32_e32 v63, 0xbfb8aa3b, v55
	v_exp_f32_e32 v62, v62
	v_and_b32_e32 v57, 0xffff0000, v57
	v_mul_f32_e32 v64, 0xbfb8aa3b, v56
	v_exp_f32_e32 v63, v63
	v_mul_f32_e32 v65, 0xbfb8aa3b, v57
	v_exp_f32_e32 v64, v64
	v_exp_f32_e32 v65, v65
	v_add_f32_e32 v62, 1.0, v62
	v_add_f32_e32 v63, 1.0, v63
	v_div_scale_f32 v66, s[0:1], v62, v62, 1.0
	v_add_f32_e32 v64, 1.0, v64
	v_div_scale_f32 v68, s[0:1], v63, v63, 1.0
	v_rcp_f32_e32 v74, v66
	v_add_f32_e32 v65, 1.0, v65
	v_div_scale_f32 v70, s[0:1], v64, v64, 1.0
	v_rcp_f32_e32 v75, v68
	v_div_scale_f32 v72, s[0:1], v65, v65, 1.0
	v_rcp_f32_e32 v76, v70
	v_rcp_f32_e32 v77, v72
	v_fma_f32 v78, -v66, v74, 1.0
	v_div_scale_f32 v67, vcc, 1.0, v62, 1.0
	v_fma_f32 v79, -v68, v75, 1.0
	v_fmac_f32_e32 v74, v78, v74
	v_div_scale_f32 v69, s[2:3], 1.0, v63, 1.0
	v_fma_f32 v80, -v70, v76, 1.0
	v_fmac_f32_e32 v75, v79, v75
	v_mul_f32_e32 v78, v67, v74
	v_div_scale_f32 v71, s[4:5], 1.0, v64, 1.0
	v_fma_f32 v81, -v72, v77, 1.0
	v_fmac_f32_e32 v76, v80, v76
	v_mul_f32_e32 v79, v69, v75
	v_fma_f32 v82, -v66, v78, v67
	v_div_scale_f32 v73, s[6:7], 1.0, v65, 1.0
	v_fmac_f32_e32 v77, v81, v77
	v_mul_f32_e32 v80, v71, v76
	v_fma_f32 v83, -v68, v79, v69
	v_fmac_f32_e32 v78, v82, v74
	v_mul_f32_e32 v81, v73, v77
	v_fma_f32 v84, -v70, v80, v71
	v_fmac_f32_e32 v79, v83, v75
	v_fma_f32 v66, -v66, v78, v67
	v_fma_f32 v85, -v72, v81, v73
	v_fmac_f32_e32 v80, v84, v76
	v_fma_f32 v67, -v68, v79, v69
	v_div_fmas_f32 v66, v66, v74, v78
	s_mov_b64 vcc, s[2:3]
	v_fmac_f32_e32 v81, v85, v77
	v_fma_f32 v68, -v70, v80, v71
	v_div_fixup_f32 v62, v66, v62, 1.0
	v_div_fmas_f32 v66, v67, v75, v79
; __device__ __forceinline__ unsigned cvt_pk_bf16(float lo, float hi) { unsigned r; asm volatile("v_cvt_pk_bf16_f32 %0, %1, %2" : "=v"(r) : "v"(lo), "v"(hi)); return r; }
; __device__ __forceinline__ float sigmoidf_(float z) { return 1.0f / (1.0f + __expf(-z)); }
;     __device__ __forceinline__ void operator()(const f32x4 (&acc)[2][2][4][2], const Unit& u, int wr, int wc, int fr, int fq) const {
;         const int h = u.pm >> 5, mt = u.pm & 31; const int row0 = mt * BM + wr * 64 + fr, col0 = 3072 + h * 256 + wc * 32 + 4 * fq;
; #pragma unroll
;         for (int ai = 0; ai < 2; ++ai)
; #pragma unroll
;             for (int m = 0; m < 4; ++m) { const size_t ro = (size_t)(row0 + ai * HALF + m * 16) * 4096 + col0;
; #pragma unroll
;                 for (int bj = 0; bj < 2; ++bj)
; #pragma unroll
;                     for (int n = 0; n < 2; ++n) { const u32x2 gw = *(const u32x2*)(G + ro + bj * HALF + n * 16); f32x4 v = acc[ai][bj][m][n];
;                         const float g0 = __uint_as_float(gw.x << 16), g1 = __uint_as_float(gw.x & 0xffff0000u), g2 = __uint_as_float(gw.y << 16), g3 = __uint_as_float(gw.y & 0xffff0000u);
;                         v[0] *= g0 * sigmoidf_(g0); v[1] *= g1 * sigmoidf_(g1); v[2] *= g2 * sigmoidf_(g2); v[3] *= g3 * sigmoidf_(g3);
;                         u32x2 w; w.x = cvt_pk_bf16(v[0], v[1]); w.y = cvt_pk_bf16(v[2], v[3]); *(u32x2*)(YC + ro + bj * HALF + n * 16) = w; } }
	s_mov_b64 vcc, s[4:5]
	v_fma_f32 v69, -v72, v81, v73
	v_mul_f32_e32 v54, v62, v54
	v_div_fixup_f32 v62, v66, v63, 1.0
	v_div_fmas_f32 v63, v68, v76, v80
	s_mov_b64 vcc, s[6:7]
	v_mul_f32_e32 v48, v48, v54
	v_mul_f32_e32 v54, v62, v55
	v_div_fixup_f32 v55, v63, v64, 1.0
	v_div_fmas_f32 v62, v69, v77, v81
	v_mul_f32_e32 v49, v49, v54
	v_mul_f32_e32 v54, v55, v56
	v_div_fixup_f32 v55, v62, v65, 1.0
	v_mul_f32_e32 v50, v50, v54
	v_mul_f32_e32 v54, v55, v57
	v_cvt_pk_bf16_f32 v48, v48, v49
	v_mul_f32_e32 v49, v51, v54
	v_cvt_pk_bf16_f32 v49, v50, v49
	flat_store_dwordx2 v[60:61], v[48:49] offset:288
	v_mov_b64_e32 v[48:49], v[202:203]
	v_lshlrev_b32_e32 v50, 16, v48
	v_and_b32_e32 v48, 0xffff0000, v48
	v_mul_f32_e32 v54, 0xbfb8aa3b, v50
	v_lshlrev_b32_e32 v51, 16, v49
	v_mul_f32_e32 v55, 0xbfb8aa3b, v48
	v_exp_f32_e32 v54, v54
	v_and_b32_e32 v49, 0xffff0000, v49
	v_mul_f32_e32 v56, 0xbfb8aa3b, v51
	v_exp_f32_e32 v55, v55
	v_mul_f32_e32 v57, 0xbfb8aa3b, v49
	v_exp_f32_e32 v56, v56
	v_exp_f32_e32 v57, v57
	v_add_f32_e32 v54, 1.0, v54
	v_add_f32_e32 v55, 1.0, v55
	v_div_scale_f32 v60, s[0:1], v54, v54, 1.0
	v_add_f32_e32 v56, 1.0, v56
	v_div_scale_f32 v62, s[0:1], v55, v55, 1.0
	v_rcp_f32_e32 v68, v60
	v_add_f32_e32 v57, 1.0, v57
	v_div_scale_f32 v64, s[0:1], v56, v56, 1.0
	v_rcp_f32_e32 v69, v62
	v_div_scale_f32 v66, s[0:1], v57, v57, 1.0
	v_rcp_f32_e32 v70, v64
	v_rcp_f32_e32 v71, v66
	v_fma_f32 v72, -v60, v68, 1.0
	v_div_scale_f32 v61, vcc, 1.0, v54, 1.0
	v_fma_f32 v73, -v62, v69, 1.0
	v_fmac_f32_e32 v68, v72, v68
	v_div_scale_f32 v63, s[2:3], 1.0, v55, 1.0
	v_fma_f32 v74, -v64, v70, 1.0
	v_fmac_f32_e32 v69, v73, v69
	v_mul_f32_e32 v72, v61, v68
	v_div_scale_f32 v65, s[4:5], 1.0, v56, 1.0
	v_fma_f32 v75, -v66, v71, 1.0
	v_fmac_f32_e32 v70, v74, v70
	v_mul_f32_e32 v73, v63, v69
	v_fma_f32 v76, -v60, v72, v61
	v_div_scale_f32 v67, s[6:7], 1.0, v57, 1.0
	v_fmac_f32_e32 v71, v75, v71
	v_mul_f32_e32 v74, v65, v70
	v_fma_f32 v77, -v62, v73, v63
	v_fmac_f32_e32 v72, v76, v68
	v_mul_f32_e32 v75, v67, v71
	v_fma_f32 v78, -v64, v74, v65
	v_fmac_f32_e32 v73, v77, v69
	v_fma_f32 v60, -v60, v72, v61
	v_fma_f32 v79, -v66, v75, v67
	v_fmac_f32_e32 v74, v78, v70
	v_fma_f32 v61, -v62, v73, v63
	v_div_fmas_f32 v60, v60, v68, v72
	s_mov_b64 vcc, s[2:3]
	v_fmac_f32_e32 v75, v79, v71
	v_fma_f32 v62, -v64, v74, v65
	v_div_fixup_f32 v54, v60, v54, 1.0
	v_div_fmas_f32 v60, v61, v69, v73
	s_mov_b64 vcc, s[4:5]
	v_fma_f32 v63, -v66, v75, v67
	v_mul_f32_e32 v50, v54, v50
	v_div_fixup_f32 v54, v60, v55, 1.0
	v_div_fmas_f32 v55, v62, v70, v74
	s_mov_b64 vcc, s[6:7]
	v_mul_f32_e32 v44, v44, v50
	v_mul_f32_e32 v48, v54, v48
	v_div_fixup_f32 v50, v55, v56, 1.0
	v_div_fmas_f32 v54, v63, v71, v75
	v_mul_f32_e32 v45, v45, v48
	v_mul_f32_e32 v48, v50, v51
	v_div_fixup_f32 v50, v54, v57, 1.0
	v_mul_f32_e32 v48, v46, v48
	v_mul_f32_e32 v49, v50, v49
	v_cvt_pk_bf16_f32 v46, v44, v45
	v_mul_f32_e32 v44, v47, v49
	v_cvt_pk_bf16_f32 v47, v48, v44
	v_mov_b64_e32 v[48:49], v[204:205]
	v_lshl_add_u64 v[44:45], s[12:13], 0, v[58:59]
	flat_store_dwordx2 v[44:45], v[46:47]
	v_lshlrev_b32_e32 v46, 16, v48
	v_and_b32_e32 v47, 0xffff0000, v48
	v_mul_f32_e32 v50, 0xbfb8aa3b, v46
	v_lshlrev_b32_e32 v48, 16, v49
	v_mul_f32_e32 v51, 0xbfb8aa3b, v47
	v_exp_f32_e32 v50, v50
	v_and_b32_e32 v49, 0xffff0000, v49
	v_mul_f32_e32 v54, 0xbfb8aa3b, v48
	v_exp_f32_e32 v51, v51
	v_mul_f32_e32 v55, 0xbfb8aa3b, v49
	v_exp_f32_e32 v54, v54
	v_exp_f32_e32 v55, v55
	v_add_f32_e32 v50, 1.0, v50
	v_add_f32_e32 v51, 1.0, v51
	v_div_scale_f32 v56, s[0:1], v50, v50, 1.0
	v_add_f32_e32 v54, 1.0, v54
	v_div_scale_f32 v58, s[0:1], v51, v51, 1.0
	v_rcp_f32_e32 v64, v56
	v_add_f32_e32 v55, 1.0, v55
	v_div_scale_f32 v60, s[0:1], v54, v54, 1.0
	v_rcp_f32_e32 v65, v58
	v_div_scale_f32 v62, s[0:1], v55, v55, 1.0
	v_rcp_f32_e32 v66, v60
	v_rcp_f32_e32 v67, v62
	v_fma_f32 v68, -v56, v64, 1.0
	v_div_scale_f32 v57, vcc, 1.0, v50, 1.0
	v_fma_f32 v69, -v58, v65, 1.0
	v_fmac_f32_e32 v64, v68, v64
	v_div_scale_f32 v59, s[2:3], 1.0, v51, 1.0
	v_fma_f32 v70, -v60, v66, 1.0
	v_fmac_f32_e32 v65, v69, v65
	v_mul_f32_e32 v68, v57, v64
	v_div_scale_f32 v61, s[4:5], 1.0, v54, 1.0
	v_fma_f32 v71, -v62, v67, 1.0
	v_fmac_f32_e32 v66, v70, v66
	v_mul_f32_e32 v69, v59, v65
	v_fma_f32 v72, -v56, v68, v57
	v_div_scale_f32 v63, s[6:7], 1.0, v55, 1.0
	v_fmac_f32_e32 v67, v71, v67
	v_mul_f32_e32 v70, v61, v66
	v_fma_f32 v73, -v58, v69, v59
	v_fmac_f32_e32 v68, v72, v64
	v_mul_f32_e32 v71, v63, v67
	v_fma_f32 v74, -v60, v70, v61
	v_fmac_f32_e32 v69, v73, v65
	v_fma_f32 v56, -v56, v68, v57
	v_fma_f32 v75, -v62, v71, v63
	v_fmac_f32_e32 v70, v74, v66
	v_fma_f32 v57, -v58, v69, v59
	v_div_fmas_f32 v56, v56, v64, v68
	s_mov_b64 vcc, s[2:3]
	v_fmac_f32_e32 v71, v75, v67
	v_fma_f32 v58, -v60, v70, v61
	v_div_fixup_f32 v50, v56, v50, 1.0
	v_div_fmas_f32 v56, v57, v65, v69
	s_mov_b64 vcc, s[4:5]
	v_fma_f32 v59, -v62, v71, v63
	v_mul_f32_e32 v46, v50, v46
	v_div_fixup_f32 v50, v56, v51, 1.0
	v_div_fmas_f32 v51, v58, v66, v70
	s_mov_b64 vcc, s[6:7]
	v_mul_f32_e32 v40, v40, v46
	v_mul_f32_e32 v46, v50, v47
	v_div_fixup_f32 v47, v51, v54, 1.0
	v_div_fmas_f32 v50, v59, v67, v71
	v_mul_f32_e32 v41, v41, v46
	v_mul_f32_e32 v46, v47, v48
	v_div_fixup_f32 v47, v50, v55, 1.0
	v_mul_f32_e32 v42, v42, v46
	v_mul_f32_e32 v46, v47, v49
	v_cvt_pk_bf16_f32 v40, v40, v41
	v_mul_f32_e32 v41, v43, v46
	v_cvt_pk_bf16_f32 v41, v42, v41
	v_mov_b64_e32 v[42:43], v[206:207]
	s_nop 0
	flat_store_dwordx2 v[44:45], v[40:41] offset:32
	v_lshlrev_b32_e32 v40, 16, v42
	v_and_b32_e32 v41, 0xffff0000, v42
	v_mul_f32_e32 v46, 0xbfb8aa3b, v40
	v_lshlrev_b32_e32 v42, 16, v43
; __device__ __forceinline__ unsigned cvt_pk_bf16(float lo, float hi) { unsigned r; asm volatile("v_cvt_pk_bf16_f32 %0, %1, %2" : "=v"(r) : "v"(lo), "v"(hi)); return r; }
; __device__ __forceinline__ float sigmoidf_(float z) { return 1.0f / (1.0f + __expf(-z)); }
;     __device__ __forceinline__ void operator()(const f32x4 (&acc)[2][2][4][2], const Unit& u, int wr, int wc, int fr, int fq) const {
;     ...
;             for (int m = 0; m < 4; ++m) { const size_t ro = (size_t)(row0 + ai * HALF + m * 16) * 4096 + col0;
; #pragma unroll
;                 for (int bj = 0; bj < 2; ++bj)
; #pragma unroll
;                     for (int n = 0; n < 2; ++n) { const u32x2 gw = *(const u32x2*)(G + ro + bj * HALF + n * 16); f32x4 v = acc[ai][bj][m][n];
;                         const float g0 = __uint_as_float(gw.x << 16), g1 = __uint_as_float(gw.x & 0xffff0000u), g2 = __uint_as_float(gw.y << 16), g3 = __uint_as_float(gw.y & 0xffff0000u);
;                         v[0] *= g0 * sigmoidf_(g0); v[1] *= g1 * sigmoidf_(g1); v[2] *= g2 * sigmoidf_(g2); v[3] *= g3 * sigmoidf_(g3);
;                         u32x2 w; w.x = cvt_pk_bf16(v[0], v[1]); w.y = cvt_pk_bf16(v[2], v[3]); *(u32x2*)(YC + ro + bj * HALF + n * 16) = w; } }
	v_mul_f32_e32 v47, 0xbfb8aa3b, v41
	v_exp_f32_e32 v46, v46
	v_and_b32_e32 v43, 0xffff0000, v43
	v_mul_f32_e32 v48, 0xbfb8aa3b, v42
	v_exp_f32_e32 v47, v47
	v_mul_f32_e32 v49, 0xbfb8aa3b, v43
	v_exp_f32_e32 v48, v48
	v_exp_f32_e32 v49, v49
	v_add_f32_e32 v46, 1.0, v46
	v_add_f32_e32 v47, 1.0, v47
	v_div_scale_f32 v50, s[0:1], v46, v46, 1.0
	v_add_f32_e32 v48, 1.0, v48
	v_div_scale_f32 v54, s[0:1], v47, v47, 1.0
	v_rcp_f32_e32 v60, v50
	v_add_f32_e32 v49, 1.0, v49
	v_div_scale_f32 v56, s[0:1], v48, v48, 1.0
	v_rcp_f32_e32 v61, v54
	v_div_scale_f32 v58, s[0:1], v49, v49, 1.0
	v_rcp_f32_e32 v62, v56
	v_rcp_f32_e32 v63, v58
	v_fma_f32 v64, -v50, v60, 1.0
	v_div_scale_f32 v51, vcc, 1.0, v46, 1.0
	v_fma_f32 v65, -v54, v61, 1.0
	v_fmac_f32_e32 v60, v64, v60
	v_div_scale_f32 v55, s[2:3], 1.0, v47, 1.0
	v_fma_f32 v66, -v56, v62, 1.0
	v_fmac_f32_e32 v61, v65, v61
	v_mul_f32_e32 v64, v51, v60
	v_div_scale_f32 v57, s[4:5], 1.0, v48, 1.0
	v_fma_f32 v67, -v58, v63, 1.0
	v_fmac_f32_e32 v62, v66, v62
	v_mul_f32_e32 v65, v55, v61
	v_fma_f32 v68, -v50, v64, v51
	v_div_scale_f32 v59, s[6:7], 1.0, v49, 1.0
	v_fmac_f32_e32 v63, v67, v63
	v_mul_f32_e32 v66, v57, v62
	v_fma_f32 v69, -v54, v65, v55
	v_fmac_f32_e32 v64, v68, v60
	v_mul_f32_e32 v67, v59, v63
	v_fma_f32 v70, -v56, v66, v57
	v_fmac_f32_e32 v65, v69, v61
	v_fma_f32 v50, -v50, v64, v51
	v_fma_f32 v71, -v58, v67, v59
	v_fmac_f32_e32 v66, v70, v62
	v_fma_f32 v51, -v54, v65, v55
	v_div_fmas_f32 v50, v50, v60, v64
	s_mov_b64 vcc, s[2:3]
	v_fmac_f32_e32 v67, v71, v63
	v_fma_f32 v54, -v56, v66, v57
	v_div_fixup_f32 v46, v50, v46, 1.0
	v_div_fmas_f32 v50, v51, v61, v65
	s_mov_b64 vcc, s[4:5]
	v_fma_f32 v55, -v58, v67, v59
	v_mul_f32_e32 v40, v46, v40
	v_div_fixup_f32 v46, v50, v47, 1.0
	v_div_fmas_f32 v47, v54, v62, v66
	s_mov_b64 vcc, s[6:7]
	v_mul_f32_e32 v36, v36, v40
	v_mul_f32_e32 v40, v46, v41
	v_div_fixup_f32 v41, v47, v48, 1.0
	v_div_fmas_f32 v46, v55, v63, v67
	v_mul_f32_e32 v37, v37, v40
	v_mul_f32_e32 v40, v41, v42
	v_div_fixup_f32 v41, v46, v49, 1.0
	v_mul_f32_e32 v40, v38, v40
	v_mul_f32_e32 v41, v41, v43
	v_cvt_pk_bf16_f32 v38, v36, v37
	v_mul_f32_e32 v36, v39, v41
	v_cvt_pk_bf16_f32 v39, v40, v36
	v_mov_b64_e32 v[40:41], v[208:209]
	v_lshl_add_u64 v[42:43], v[124:125], 0, s[44:45]
	flat_store_dwordx2 v[44:45], v[38:39] offset:256
	v_lshl_add_u64 v[36:37], s[8:9], 0, v[42:43]
	v_lshlrev_b32_e32 v38, 16, v40
	v_and_b32_e32 v39, 0xffff0000, v40
	v_mul_f32_e32 v46, 0xbfb8aa3b, v38
	v_lshlrev_b32_e32 v40, 16, v41
	v_mul_f32_e32 v47, 0xbfb8aa3b, v39
	v_exp_f32_e32 v46, v46
	v_and_b32_e32 v41, 0xffff0000, v41
	v_mul_f32_e32 v48, 0xbfb8aa3b, v40
	v_exp_f32_e32 v47, v47
	v_mul_f32_e32 v49, 0xbfb8aa3b, v41
	v_exp_f32_e32 v48, v48
	v_exp_f32_e32 v49, v49
	v_add_f32_e32 v46, 1.0, v46
	v_add_f32_e32 v47, 1.0, v47
	v_div_scale_f32 v50, s[0:1], v46, v46, 1.0
	v_add_f32_e32 v48, 1.0, v48
	v_div_scale_f32 v52, s[0:1], v47, v47, 1.0
	v_rcp_f32_e32 v58, v50
	v_add_f32_e32 v49, 1.0, v49
	v_div_scale_f32 v54, s[0:1], v48, v48, 1.0
	v_rcp_f32_e32 v59, v52
	v_div_scale_f32 v56, s[0:1], v49, v49, 1.0
	v_rcp_f32_e32 v60, v54
	v_rcp_f32_e32 v61, v56
	v_fma_f32 v62, -v50, v58, 1.0
	v_div_scale_f32 v51, vcc, 1.0, v46, 1.0
	v_fma_f32 v63, -v52, v59, 1.0
	v_fmac_f32_e32 v58, v62, v58
	v_div_scale_f32 v53, s[2:3], 1.0, v47, 1.0
	v_fma_f32 v64, -v54, v60, 1.0
	v_fmac_f32_e32 v59, v63, v59
	v_mul_f32_e32 v62, v51, v58
	v_div_scale_f32 v55, s[4:5], 1.0, v48, 1.0
	v_fma_f32 v65, -v56, v61, 1.0
	v_fmac_f32_e32 v60, v64, v60
	v_mul_f32_e32 v63, v53, v59
	v_fma_f32 v66, -v50, v62, v51
	v_div_scale_f32 v57, s[6:7], 1.0, v49, 1.0
	v_fmac_f32_e32 v61, v65, v61
	v_mul_f32_e32 v64, v55, v60
	v_fma_f32 v67, -v52, v63, v53
	v_fmac_f32_e32 v62, v66, v58
	v_mul_f32_e32 v65, v57, v61
	v_fma_f32 v68, -v54, v64, v55
	v_fmac_f32_e32 v63, v67, v59
	v_fma_f32 v50, -v50, v62, v51
	v_fma_f32 v69, -v56, v65, v57
	v_fmac_f32_e32 v64, v68, v60
	v_fma_f32 v51, -v52, v63, v53
	v_div_fmas_f32 v50, v50, v58, v62
	s_mov_b64 vcc, s[2:3]
	v_fmac_f32_e32 v65, v69, v61
	v_fma_f32 v52, -v54, v64, v55
	v_div_fixup_f32 v46, v50, v46, 1.0
	v_div_fmas_f32 v50, v51, v59, v63
	s_mov_b64 vcc, s[4:5]
	v_fma_f32 v53, -v56, v65, v57
	v_mul_f32_e32 v38, v46, v38
	v_div_fixup_f32 v46, v50, v47, 1.0
	v_div_fmas_f32 v47, v52, v60, v64
	s_mov_b64 vcc, s[6:7]
	v_mul_f32_e32 v32, v32, v38
	v_mul_f32_e32 v38, v46, v39
	v_div_fixup_f32 v39, v47, v48, 1.0
	v_div_fmas_f32 v46, v53, v61, v65
	v_mul_f32_e32 v33, v33, v38
	v_mul_f32_e32 v38, v39, v40
	v_div_fixup_f32 v39, v46, v49, 1.0
	v_mul_f32_e32 v34, v34, v38
	v_mul_f32_e32 v38, v39, v41
	v_cvt_pk_bf16_f32 v32, v32, v33
	v_mul_f32_e32 v33, v35, v38
	v_cvt_pk_bf16_f32 v33, v34, v33
	flat_store_dwordx2 v[44:45], v[32:33] offset:288
	v_mov_b64_e32 v[32:33], v[210:211]
	v_lshlrev_b32_e32 v34, 16, v32
	v_and_b32_e32 v32, 0xffff0000, v32
	v_mul_f32_e32 v38, 0xbfb8aa3b, v34
	v_lshlrev_b32_e32 v35, 16, v33
	v_mul_f32_e32 v39, 0xbfb8aa3b, v32
	v_exp_f32_e32 v38, v38
	v_and_b32_e32 v33, 0xffff0000, v33
	v_mul_f32_e32 v40, 0xbfb8aa3b, v35
	v_exp_f32_e32 v39, v39
	v_mul_f32_e32 v41, 0xbfb8aa3b, v33
	v_exp_f32_e32 v40, v40
	v_exp_f32_e32 v41, v41
	v_add_f32_e32 v38, 1.0, v38
	v_add_f32_e32 v39, 1.0, v39
	v_div_scale_f32 v44, s[0:1], v38, v38, 1.0
	v_add_f32_e32 v40, 1.0, v40
	v_div_scale_f32 v46, s[0:1], v39, v39, 1.0
	v_rcp_f32_e32 v52, v44
	v_add_f32_e32 v41, 1.0, v41
	v_div_scale_f32 v48, s[0:1], v40, v40, 1.0
	v_rcp_f32_e32 v53, v46
	v_div_scale_f32 v50, s[0:1], v41, v41, 1.0
	v_rcp_f32_e32 v54, v48
	v_rcp_f32_e32 v55, v50
	v_fma_f32 v56, -v44, v52, 1.0
	v_div_scale_f32 v45, vcc, 1.0, v38, 1.0
	v_fma_f32 v57, -v46, v53, 1.0
; __device__ __forceinline__ unsigned cvt_pk_bf16(float lo, float hi) { unsigned r; asm volatile("v_cvt_pk_bf16_f32 %0, %1, %2" : "=v"(r) : "v"(lo), "v"(hi)); return r; }
; __device__ __forceinline__ float sigmoidf_(float z) { return 1.0f / (1.0f + __expf(-z)); }
;     __device__ __forceinline__ void operator()(const f32x4 (&acc)[2][2][4][2], const Unit& u, int wr, int wc, int fr, int fq) const {
;     ...
;             for (int m = 0; m < 4; ++m) { const size_t ro = (size_t)(row0 + ai * HALF + m * 16) * 4096 + col0;
; #pragma unroll
;                 for (int bj = 0; bj < 2; ++bj)
; #pragma unroll
;                     for (int n = 0; n < 2; ++n) { const u32x2 gw = *(const u32x2*)(G + ro + bj * HALF + n * 16); f32x4 v = acc[ai][bj][m][n];
;                         const float g0 = __uint_as_float(gw.x << 16), g1 = __uint_as_float(gw.x & 0xffff0000u), g2 = __uint_as_float(gw.y << 16), g3 = __uint_as_float(gw.y & 0xffff0000u);
;                         v[0] *= g0 * sigmoidf_(g0); v[1] *= g1 * sigmoidf_(g1); v[2] *= g2 * sigmoidf_(g2); v[3] *= g3 * sigmoidf_(g3);
;                         u32x2 w; w.x = cvt_pk_bf16(v[0], v[1]); w.y = cvt_pk_bf16(v[2], v[3]); *(u32x2*)(YC + ro + bj * HALF + n * 16) = w; } }
	v_fmac_f32_e32 v52, v56, v52
	v_div_scale_f32 v47, s[2:3], 1.0, v39, 1.0
	v_fma_f32 v58, -v48, v54, 1.0
	v_fmac_f32_e32 v53, v57, v53
	v_mul_f32_e32 v56, v45, v52
	v_div_scale_f32 v49, s[4:5], 1.0, v40, 1.0
	v_fma_f32 v59, -v50, v55, 1.0
	v_fmac_f32_e32 v54, v58, v54
	v_mul_f32_e32 v57, v47, v53
	v_fma_f32 v60, -v44, v56, v45
	v_div_scale_f32 v51, s[6:7], 1.0, v41, 1.0
	v_fmac_f32_e32 v55, v59, v55
	v_mul_f32_e32 v58, v49, v54
	v_fma_f32 v61, -v46, v57, v47
	v_fmac_f32_e32 v56, v60, v52
	v_mul_f32_e32 v59, v51, v55
	v_fma_f32 v62, -v48, v58, v49
	v_fmac_f32_e32 v57, v61, v53
	v_fma_f32 v44, -v44, v56, v45
	v_fma_f32 v63, -v50, v59, v51
	v_fmac_f32_e32 v58, v62, v54
	v_fma_f32 v45, -v46, v57, v47
	v_div_fmas_f32 v44, v44, v52, v56
	s_mov_b64 vcc, s[2:3]
	v_fmac_f32_e32 v59, v63, v55
	v_fma_f32 v46, -v48, v58, v49
	v_div_fixup_f32 v38, v44, v38, 1.0
	v_div_fmas_f32 v44, v45, v53, v57
	s_mov_b64 vcc, s[4:5]
	v_fma_f32 v47, -v50, v59, v51
	v_mul_f32_e32 v34, v38, v34
	v_div_fixup_f32 v38, v44, v39, 1.0
	v_div_fmas_f32 v39, v46, v54, v58
	s_mov_b64 vcc, s[6:7]
	v_mul_f32_e32 v28, v28, v34
	v_mul_f32_e32 v32, v38, v32
	v_div_fixup_f32 v34, v39, v40, 1.0
	v_div_fmas_f32 v38, v47, v55, v59
	v_mul_f32_e32 v29, v29, v32
	v_mul_f32_e32 v32, v34, v35
	v_div_fixup_f32 v34, v38, v41, 1.0
	v_mul_f32_e32 v32, v30, v32
	v_mul_f32_e32 v33, v34, v33
	v_cvt_pk_bf16_f32 v30, v28, v29
	v_mul_f32_e32 v28, v31, v33
	v_cvt_pk_bf16_f32 v31, v32, v28
	v_mov_b64_e32 v[32:33], v[212:213]
	v_lshl_add_u64 v[28:29], s[12:13], 0, v[42:43]
	flat_store_dwordx2 v[28:29], v[30:31]
	v_lshlrev_b32_e32 v30, 16, v32
	v_and_b32_e32 v31, 0xffff0000, v32
	v_mul_f32_e32 v34, 0xbfb8aa3b, v30
	v_lshlrev_b32_e32 v32, 16, v33
	v_mul_f32_e32 v35, 0xbfb8aa3b, v31
	v_exp_f32_e32 v34, v34
	v_and_b32_e32 v33, 0xffff0000, v33
	v_mul_f32_e32 v38, 0xbfb8aa3b, v32
	v_exp_f32_e32 v35, v35
	v_mul_f32_e32 v39, 0xbfb8aa3b, v33
	v_exp_f32_e32 v38, v38
	v_exp_f32_e32 v39, v39
	v_add_f32_e32 v34, 1.0, v34
	v_add_f32_e32 v35, 1.0, v35
	v_div_scale_f32 v40, s[0:1], v34, v34, 1.0
	v_add_f32_e32 v38, 1.0, v38
	v_div_scale_f32 v42, s[0:1], v35, v35, 1.0
	v_rcp_f32_e32 v48, v40
	v_add_f32_e32 v39, 1.0, v39
	v_div_scale_f32 v44, s[0:1], v38, v38, 1.0
	v_rcp_f32_e32 v49, v42
	v_div_scale_f32 v46, s[0:1], v39, v39, 1.0
	v_rcp_f32_e32 v50, v44
	v_rcp_f32_e32 v51, v46
	v_fma_f32 v52, -v40, v48, 1.0
	v_div_scale_f32 v41, vcc, 1.0, v34, 1.0
	v_fma_f32 v53, -v42, v49, 1.0
	v_fmac_f32_e32 v48, v52, v48
	v_div_scale_f32 v43, s[2:3], 1.0, v35, 1.0
	v_fma_f32 v54, -v44, v50, 1.0
	v_fmac_f32_e32 v49, v53, v49
	v_mul_f32_e32 v52, v41, v48
	v_div_scale_f32 v45, s[4:5], 1.0, v38, 1.0
	v_fma_f32 v55, -v46, v51, 1.0
	v_fmac_f32_e32 v50, v54, v50
	v_mul_f32_e32 v53, v43, v49
	v_fma_f32 v56, -v40, v52, v41
	v_div_scale_f32 v47, s[6:7], 1.0, v39, 1.0
	v_fmac_f32_e32 v51, v55, v51
	v_mul_f32_e32 v54, v45, v50
	v_fma_f32 v57, -v42, v53, v43
	v_fmac_f32_e32 v52, v56, v48
	v_mul_f32_e32 v55, v47, v51
	v_fma_f32 v58, -v44, v54, v45
	v_fmac_f32_e32 v53, v57, v49
	v_fma_f32 v40, -v40, v52, v41
	v_fma_f32 v59, -v46, v55, v47
	v_fmac_f32_e32 v54, v58, v50
	v_fma_f32 v41, -v42, v53, v43
	v_div_fmas_f32 v40, v40, v48, v52
	s_mov_b64 vcc, s[2:3]
	v_fmac_f32_e32 v55, v59, v51
	v_fma_f32 v42, -v44, v54, v45
	v_div_fixup_f32 v34, v40, v34, 1.0
	v_div_fmas_f32 v40, v41, v49, v53
	s_mov_b64 vcc, s[4:5]
	v_fma_f32 v43, -v46, v55, v47
	v_mul_f32_e32 v30, v34, v30
	v_div_fixup_f32 v34, v40, v35, 1.0
	v_div_fmas_f32 v35, v42, v50, v54
	s_mov_b64 vcc, s[6:7]
	v_mul_f32_e32 v24, v24, v30
	v_mul_f32_e32 v30, v34, v31
	v_div_fixup_f32 v31, v35, v38, 1.0
	v_div_fmas_f32 v34, v43, v51, v55
	v_mul_f32_e32 v25, v25, v30
	v_mul_f32_e32 v30, v31, v32
	v_div_fixup_f32 v31, v34, v39, 1.0
	v_mul_f32_e32 v26, v26, v30
	v_mul_f32_e32 v30, v31, v33
	v_cvt_pk_bf16_f32 v24, v24, v25
	v_mul_f32_e32 v25, v27, v30
	v_cvt_pk_bf16_f32 v25, v26, v25
	v_mov_b64_e32 v[26:27], v[214:215]
	s_nop 0
	flat_store_dwordx2 v[28:29], v[24:25] offset:32
	v_lshlrev_b32_e32 v24, 16, v26
	v_and_b32_e32 v25, 0xffff0000, v26
	v_mul_f32_e32 v30, 0xbfb8aa3b, v24
	v_lshlrev_b32_e32 v26, 16, v27
	v_mul_f32_e32 v31, 0xbfb8aa3b, v25
	v_exp_f32_e32 v30, v30
	v_and_b32_e32 v27, 0xffff0000, v27
	v_mul_f32_e32 v32, 0xbfb8aa3b, v26
	v_exp_f32_e32 v31, v31
	v_mul_f32_e32 v33, 0xbfb8aa3b, v27
	v_exp_f32_e32 v32, v32
	v_exp_f32_e32 v33, v33
	v_add_f32_e32 v30, 1.0, v30
	v_add_f32_e32 v31, 1.0, v31
	v_div_scale_f32 v34, s[0:1], v30, v30, 1.0
	v_add_f32_e32 v32, 1.0, v32
	v_div_scale_f32 v38, s[0:1], v31, v31, 1.0
	v_rcp_f32_e32 v44, v34
	v_add_f32_e32 v33, 1.0, v33
	v_div_scale_f32 v40, s[0:1], v32, v32, 1.0
	v_rcp_f32_e32 v45, v38
	v_div_scale_f32 v42, s[0:1], v33, v33, 1.0
	v_rcp_f32_e32 v46, v40
	v_rcp_f32_e32 v47, v42
	v_fma_f32 v48, -v34, v44, 1.0
	v_div_scale_f32 v35, vcc, 1.0, v30, 1.0
	v_fma_f32 v49, -v38, v45, 1.0
	v_fmac_f32_e32 v44, v48, v44
	v_div_scale_f32 v39, s[2:3], 1.0, v31, 1.0
	v_fma_f32 v50, -v40, v46, 1.0
	v_fmac_f32_e32 v45, v49, v45
	v_mul_f32_e32 v48, v35, v44
	v_div_scale_f32 v41, s[4:5], 1.0, v32, 1.0
	v_fma_f32 v51, -v42, v47, 1.0
	v_fmac_f32_e32 v46, v50, v46
	v_mul_f32_e32 v49, v39, v45
	v_fma_f32 v52, -v34, v48, v35
	v_div_scale_f32 v43, s[6:7], 1.0, v33, 1.0
	v_fmac_f32_e32 v47, v51, v47
	v_mul_f32_e32 v50, v41, v46
	v_fma_f32 v53, -v38, v49, v39
	v_fmac_f32_e32 v48, v52, v44
	v_mul_f32_e32 v51, v43, v47
	v_fma_f32 v54, -v40, v50, v41
	v_fmac_f32_e32 v49, v53, v45
	v_fma_f32 v34, -v34, v48, v35
	v_fma_f32 v55, -v42, v51, v43
	v_fmac_f32_e32 v50, v54, v46
	v_fma_f32 v35, -v38, v49, v39
	v_div_fmas_f32 v34, v34, v44, v48
	s_mov_b64 vcc, s[2:3]
	v_fmac_f32_e32 v51, v55, v47
; __device__ __forceinline__ unsigned cvt_pk_bf16(float lo, float hi) { unsigned r; asm volatile("v_cvt_pk_bf16_f32 %0, %1, %2" : "=v"(r) : "v"(lo), "v"(hi)); return r; }
; __device__ __forceinline__ float sigmoidf_(float z) { return 1.0f / (1.0f + __expf(-z)); }
;     __device__ __forceinline__ void operator()(const f32x4 (&acc)[2][2][4][2], const Unit& u, int wr, int wc, int fr, int fq) const {
;     ...
;             for (int m = 0; m < 4; ++m) { const size_t ro = (size_t)(row0 + ai * HALF + m * 16) * 4096 + col0;
; #pragma unroll
;                 for (int bj = 0; bj < 2; ++bj)
; #pragma unroll
;                     for (int n = 0; n < 2; ++n) { const u32x2 gw = *(const u32x2*)(G + ro + bj * HALF + n * 16); f32x4 v = acc[ai][bj][m][n];
;                         const float g0 = __uint_as_float(gw.x << 16), g1 = __uint_as_float(gw.x & 0xffff0000u), g2 = __uint_as_float(gw.y << 16), g3 = __uint_as_float(gw.y & 0xffff0000u);
;                         v[0] *= g0 * sigmoidf_(g0); v[1] *= g1 * sigmoidf_(g1); v[2] *= g2 * sigmoidf_(g2); v[3] *= g3 * sigmoidf_(g3);
;                         u32x2 w; w.x = cvt_pk_bf16(v[0], v[1]); w.y = cvt_pk_bf16(v[2], v[3]); *(u32x2*)(YC + ro + bj * HALF + n * 16) = w; } }
	v_fma_f32 v38, -v40, v50, v41
	v_div_fixup_f32 v30, v34, v30, 1.0
	v_div_fmas_f32 v34, v35, v45, v49
	s_mov_b64 vcc, s[4:5]
	v_fma_f32 v39, -v42, v51, v43
	v_mul_f32_e32 v24, v30, v24
	v_div_fixup_f32 v30, v34, v31, 1.0
	v_div_fmas_f32 v31, v38, v46, v50
	s_mov_b64 vcc, s[6:7]
	v_mul_f32_e32 v20, v20, v24
	v_mul_f32_e32 v24, v30, v25
	v_div_fixup_f32 v25, v31, v32, 1.0
	v_div_fmas_f32 v30, v39, v47, v51
	v_mul_f32_e32 v21, v21, v24
	v_mul_f32_e32 v24, v25, v26
	v_div_fixup_f32 v25, v30, v33, 1.0
	v_mul_f32_e32 v24, v22, v24
	v_mul_f32_e32 v25, v25, v27
	v_cvt_pk_bf16_f32 v22, v20, v21
	v_mul_f32_e32 v20, v23, v25
	v_cvt_pk_bf16_f32 v23, v24, v20
	v_mov_b64_e32 v[24:25], v[216:217]
	v_lshl_add_u64 v[26:27], v[124:125], 0, s[46:47]
	flat_store_dwordx2 v[28:29], v[22:23] offset:256
	v_lshl_add_u64 v[20:21], s[8:9], 0, v[26:27]
	v_lshlrev_b32_e32 v22, 16, v24
	v_and_b32_e32 v23, 0xffff0000, v24
	v_mul_f32_e32 v30, 0xbfb8aa3b, v22
	v_lshlrev_b32_e32 v24, 16, v25
	v_mul_f32_e32 v31, 0xbfb8aa3b, v23
	v_exp_f32_e32 v30, v30
	v_and_b32_e32 v25, 0xffff0000, v25
	v_mul_f32_e32 v32, 0xbfb8aa3b, v24
	v_exp_f32_e32 v31, v31
	v_mul_f32_e32 v33, 0xbfb8aa3b, v25
	v_exp_f32_e32 v32, v32
	v_exp_f32_e32 v33, v33
	v_add_f32_e32 v30, 1.0, v30
	v_add_f32_e32 v31, 1.0, v31
	v_div_scale_f32 v34, s[0:1], v30, v30, 1.0
	v_add_f32_e32 v32, 1.0, v32
	v_div_scale_f32 v36, s[0:1], v31, v31, 1.0
	v_rcp_f32_e32 v42, v34
	v_add_f32_e32 v33, 1.0, v33
	v_div_scale_f32 v38, s[0:1], v32, v32, 1.0
	v_rcp_f32_e32 v43, v36
	v_div_scale_f32 v40, s[0:1], v33, v33, 1.0
	v_rcp_f32_e32 v44, v38
	v_rcp_f32_e32 v45, v40
	v_fma_f32 v46, -v34, v42, 1.0
	v_div_scale_f32 v35, vcc, 1.0, v30, 1.0
	v_fma_f32 v47, -v36, v43, 1.0
	v_fmac_f32_e32 v42, v46, v42
	v_div_scale_f32 v37, s[2:3], 1.0, v31, 1.0
	v_fma_f32 v48, -v38, v44, 1.0
	v_fmac_f32_e32 v43, v47, v43
	v_mul_f32_e32 v46, v35, v42
	v_div_scale_f32 v39, s[4:5], 1.0, v32, 1.0
	v_fma_f32 v49, -v40, v45, 1.0
	v_fmac_f32_e32 v44, v48, v44
	v_mul_f32_e32 v47, v37, v43
	v_fma_f32 v50, -v34, v46, v35
	v_div_scale_f32 v41, s[6:7], 1.0, v33, 1.0
	v_fmac_f32_e32 v45, v49, v45
	v_mul_f32_e32 v48, v39, v44
	v_fma_f32 v51, -v36, v47, v37
	v_fmac_f32_e32 v46, v50, v42
	v_mul_f32_e32 v49, v41, v45
	v_fma_f32 v52, -v38, v48, v39
	v_fmac_f32_e32 v47, v51, v43
	v_fma_f32 v34, -v34, v46, v35
	v_fma_f32 v53, -v40, v49, v41
	v_fmac_f32_e32 v48, v52, v44
	v_fma_f32 v35, -v36, v47, v37
	v_div_fmas_f32 v34, v34, v42, v46
	s_mov_b64 vcc, s[2:3]
	v_fmac_f32_e32 v49, v53, v45
	v_fma_f32 v36, -v38, v48, v39
	v_div_fixup_f32 v30, v34, v30, 1.0
	v_div_fmas_f32 v34, v35, v43, v47
	s_mov_b64 vcc, s[4:5]
	v_fma_f32 v37, -v40, v49, v41
	v_mul_f32_e32 v22, v30, v22
	v_div_fixup_f32 v30, v34, v31, 1.0
	v_div_fmas_f32 v31, v36, v44, v48
	s_mov_b64 vcc, s[6:7]
	v_mul_f32_e32 v16, v16, v22
	v_mul_f32_e32 v22, v30, v23
	v_div_fixup_f32 v23, v31, v32, 1.0
	v_div_fmas_f32 v30, v37, v45, v49
	v_mul_f32_e32 v17, v17, v22
	v_mul_f32_e32 v22, v23, v24
	v_div_fixup_f32 v23, v30, v33, 1.0
	v_mul_f32_e32 v18, v18, v22
	v_mul_f32_e32 v22, v23, v25
	v_cvt_pk_bf16_f32 v16, v16, v17
	v_mul_f32_e32 v17, v19, v22
	v_cvt_pk_bf16_f32 v17, v18, v17
	flat_store_dwordx2 v[28:29], v[16:17] offset:288
	v_mov_b64_e32 v[16:17], v[218:219]
	v_lshlrev_b32_e32 v18, 16, v16
	v_and_b32_e32 v16, 0xffff0000, v16
	v_mul_f32_e32 v22, 0xbfb8aa3b, v18
	v_lshlrev_b32_e32 v19, 16, v17
	v_mul_f32_e32 v23, 0xbfb8aa3b, v16
	v_exp_f32_e32 v22, v22
	v_and_b32_e32 v17, 0xffff0000, v17
	v_mul_f32_e32 v24, 0xbfb8aa3b, v19
	v_exp_f32_e32 v23, v23
	v_mul_f32_e32 v25, 0xbfb8aa3b, v17
	v_exp_f32_e32 v24, v24
	v_exp_f32_e32 v25, v25
	v_add_f32_e32 v22, 1.0, v22
	v_add_f32_e32 v23, 1.0, v23
	v_div_scale_f32 v28, s[0:1], v22, v22, 1.0
	v_add_f32_e32 v24, 1.0, v24
	v_div_scale_f32 v30, s[0:1], v23, v23, 1.0
	v_rcp_f32_e32 v36, v28
	v_add_f32_e32 v25, 1.0, v25
	v_div_scale_f32 v32, s[0:1], v24, v24, 1.0
	v_rcp_f32_e32 v37, v30
	v_div_scale_f32 v34, s[0:1], v25, v25, 1.0
	v_rcp_f32_e32 v38, v32
	v_rcp_f32_e32 v39, v34
	v_fma_f32 v40, -v28, v36, 1.0
	v_div_scale_f32 v29, vcc, 1.0, v22, 1.0
	v_fma_f32 v41, -v30, v37, 1.0
	v_fmac_f32_e32 v36, v40, v36
	v_div_scale_f32 v31, s[2:3], 1.0, v23, 1.0
	v_fma_f32 v42, -v32, v38, 1.0
	v_fmac_f32_e32 v37, v41, v37
	v_mul_f32_e32 v40, v29, v36
	v_div_scale_f32 v33, s[4:5], 1.0, v24, 1.0
	v_fma_f32 v43, -v34, v39, 1.0
	v_fmac_f32_e32 v38, v42, v38
	v_mul_f32_e32 v41, v31, v37
	v_fma_f32 v44, -v28, v40, v29
	v_div_scale_f32 v35, s[6:7], 1.0, v25, 1.0
	v_fmac_f32_e32 v39, v43, v39
	v_mul_f32_e32 v42, v33, v38
	v_fma_f32 v45, -v30, v41, v31
	v_fmac_f32_e32 v40, v44, v36
	v_mul_f32_e32 v43, v35, v39
	v_fma_f32 v46, -v32, v42, v33
	v_fmac_f32_e32 v41, v45, v37
	v_fma_f32 v28, -v28, v40, v29
	v_fma_f32 v47, -v34, v43, v35
	v_fmac_f32_e32 v42, v46, v38
	v_fma_f32 v29, -v30, v41, v31
	v_div_fmas_f32 v28, v28, v36, v40
	s_mov_b64 vcc, s[2:3]
	v_fmac_f32_e32 v43, v47, v39
	v_fma_f32 v30, -v32, v42, v33
	v_div_fixup_f32 v22, v28, v22, 1.0
	v_div_fmas_f32 v28, v29, v37, v41
	s_mov_b64 vcc, s[4:5]
	v_fma_f32 v31, -v34, v43, v35
	v_mul_f32_e32 v18, v22, v18
	v_div_fixup_f32 v22, v28, v23, 1.0
	v_div_fmas_f32 v23, v30, v38, v42
	s_mov_b64 vcc, s[6:7]
	v_mul_f32_e32 v12, v12, v18
	v_mul_f32_e32 v16, v22, v16
	v_div_fixup_f32 v18, v23, v24, 1.0
	v_div_fmas_f32 v22, v31, v39, v43
	v_mul_f32_e32 v13, v13, v16
	v_mul_f32_e32 v16, v18, v19
	v_div_fixup_f32 v18, v22, v25, 1.0
	v_mul_f32_e32 v16, v14, v16
	v_mul_f32_e32 v17, v18, v17
	v_cvt_pk_bf16_f32 v14, v12, v13
	v_mul_f32_e32 v12, v15, v17
	v_cvt_pk_bf16_f32 v15, v16, v12
	v_mov_b64_e32 v[16:17], v[220:221]
	v_lshl_add_u64 v[12:13], s[12:13], 0, v[26:27]
; __device__ __forceinline__ unsigned cvt_pk_bf16(float lo, float hi) { unsigned r; asm volatile("v_cvt_pk_bf16_f32 %0, %1, %2" : "=v"(r) : "v"(lo), "v"(hi)); return r; }
; __device__ __forceinline__ float sigmoidf_(float z) { return 1.0f / (1.0f + __expf(-z)); }
;     __device__ __forceinline__ void operator()(const f32x4 (&acc)[2][2][4][2], const Unit& u, int wr, int wc, int fr, int fq) const {
;     ...
;             for (int m = 0; m < 4; ++m) { const size_t ro = (size_t)(row0 + ai * HALF + m * 16) * 4096 + col0;
; #pragma unroll
;                 for (int bj = 0; bj < 2; ++bj)
; #pragma unroll
;                     for (int n = 0; n < 2; ++n) { const u32x2 gw = *(const u32x2*)(G + ro + bj * HALF + n * 16); f32x4 v = acc[ai][bj][m][n];
;                         const float g0 = __uint_as_float(gw.x << 16), g1 = __uint_as_float(gw.x & 0xffff0000u), g2 = __uint_as_float(gw.y << 16), g3 = __uint_as_float(gw.y & 0xffff0000u);
;                         v[0] *= g0 * sigmoidf_(g0); v[1] *= g1 * sigmoidf_(g1); v[2] *= g2 * sigmoidf_(g2); v[3] *= g3 * sigmoidf_(g3);
;                         u32x2 w; w.x = cvt_pk_bf16(v[0], v[1]); w.y = cvt_pk_bf16(v[2], v[3]); *(u32x2*)(YC + ro + bj * HALF + n * 16) = w; } }
	flat_store_dwordx2 v[12:13], v[14:15]
	v_lshlrev_b32_e32 v14, 16, v16
	v_and_b32_e32 v15, 0xffff0000, v16
	v_mul_f32_e32 v18, 0xbfb8aa3b, v14
	v_lshlrev_b32_e32 v16, 16, v17
	v_mul_f32_e32 v19, 0xbfb8aa3b, v15
	v_exp_f32_e32 v18, v18
	v_and_b32_e32 v17, 0xffff0000, v17
	v_mul_f32_e32 v22, 0xbfb8aa3b, v16
	v_exp_f32_e32 v19, v19
	v_mul_f32_e32 v23, 0xbfb8aa3b, v17
	v_exp_f32_e32 v22, v22
	v_exp_f32_e32 v23, v23
	v_add_f32_e32 v18, 1.0, v18
	v_add_f32_e32 v19, 1.0, v19
	v_div_scale_f32 v24, s[0:1], v18, v18, 1.0
	v_add_f32_e32 v22, 1.0, v22
	v_div_scale_f32 v26, s[0:1], v19, v19, 1.0
	v_rcp_f32_e32 v32, v24
	v_add_f32_e32 v23, 1.0, v23
	v_div_scale_f32 v28, s[0:1], v22, v22, 1.0
	v_rcp_f32_e32 v33, v26
	v_div_scale_f32 v30, s[0:1], v23, v23, 1.0
	v_rcp_f32_e32 v34, v28
	v_rcp_f32_e32 v35, v30
	v_fma_f32 v36, -v24, v32, 1.0
	v_div_scale_f32 v25, vcc, 1.0, v18, 1.0
	v_fma_f32 v37, -v26, v33, 1.0
	v_fmac_f32_e32 v32, v36, v32
	v_div_scale_f32 v27, s[2:3], 1.0, v19, 1.0
	v_fma_f32 v38, -v28, v34, 1.0
	v_fmac_f32_e32 v33, v37, v33
	v_mul_f32_e32 v36, v25, v32
	v_div_scale_f32 v29, s[4:5], 1.0, v22, 1.0
	v_fma_f32 v39, -v30, v35, 1.0
	v_fmac_f32_e32 v34, v38, v34
	v_mul_f32_e32 v37, v27, v33
	v_fma_f32 v40, -v24, v36, v25
	v_div_scale_f32 v31, s[6:7], 1.0, v23, 1.0
	v_fmac_f32_e32 v35, v39, v35
	v_mul_f32_e32 v38, v29, v34
	v_fma_f32 v41, -v26, v37, v27
	v_fmac_f32_e32 v36, v40, v32
	v_mul_f32_e32 v39, v31, v35
	v_fma_f32 v42, -v28, v38, v29
	v_fmac_f32_e32 v37, v41, v33
	v_fma_f32 v24, -v24, v36, v25
	v_fma_f32 v43, -v30, v39, v31
	v_fmac_f32_e32 v38, v42, v34
	v_fma_f32 v25, -v26, v37, v27
	v_div_fmas_f32 v24, v24, v32, v36
	s_mov_b64 vcc, s[2:3]
	v_fmac_f32_e32 v39, v43, v35
	v_fma_f32 v26, -v28, v38, v29
	v_div_fixup_f32 v18, v24, v18, 1.0
	v_div_fmas_f32 v24, v25, v33, v37
	s_mov_b64 vcc, s[4:5]
	v_fma_f32 v27, -v30, v39, v31
	v_mul_f32_e32 v14, v18, v14
	v_div_fixup_f32 v18, v24, v19, 1.0
	v_div_fmas_f32 v19, v26, v34, v38
	s_mov_b64 vcc, s[6:7]
	v_mul_f32_e32 v8, v8, v14
	v_mul_f32_e32 v14, v18, v15
	v_div_fixup_f32 v15, v19, v22, 1.0
	v_div_fmas_f32 v18, v27, v35, v39
	v_mul_f32_e32 v9, v9, v14
	v_mul_f32_e32 v14, v15, v16
	v_div_fixup_f32 v15, v18, v23, 1.0
	v_mul_f32_e32 v10, v10, v14
	v_mul_f32_e32 v14, v15, v17
	v_cvt_pk_bf16_f32 v8, v8, v9
	v_mul_f32_e32 v9, v11, v14
	v_cvt_pk_bf16_f32 v9, v10, v9
	v_mov_b64_e32 v[10:11], v[222:223]
	s_nop 0
	flat_store_dwordx2 v[12:13], v[8:9] offset:32
	v_lshlrev_b32_e32 v8, 16, v10
	v_and_b32_e32 v9, 0xffff0000, v10
	v_mul_f32_e32 v14, 0xbfb8aa3b, v8
	v_lshlrev_b32_e32 v10, 16, v11
	v_mul_f32_e32 v15, 0xbfb8aa3b, v9
	v_exp_f32_e32 v14, v14
	v_and_b32_e32 v11, 0xffff0000, v11
	v_mul_f32_e32 v16, 0xbfb8aa3b, v10
	v_exp_f32_e32 v15, v15
	v_mul_f32_e32 v17, 0xbfb8aa3b, v11
	v_exp_f32_e32 v16, v16
	v_exp_f32_e32 v17, v17
	v_add_f32_e32 v14, 1.0, v14
	v_add_f32_e32 v15, 1.0, v15
	v_div_scale_f32 v18, s[0:1], v14, v14, 1.0
	v_add_f32_e32 v16, 1.0, v16
	v_div_scale_f32 v22, s[0:1], v15, v15, 1.0
	v_rcp_f32_e32 v28, v18
	v_add_f32_e32 v17, 1.0, v17
	v_div_scale_f32 v24, s[0:1], v16, v16, 1.0
	v_rcp_f32_e32 v29, v22
	v_div_scale_f32 v26, s[0:1], v17, v17, 1.0
	v_rcp_f32_e32 v30, v24
	v_rcp_f32_e32 v31, v26
	v_fma_f32 v32, -v18, v28, 1.0
	v_div_scale_f32 v19, vcc, 1.0, v14, 1.0
	v_fma_f32 v33, -v22, v29, 1.0
	v_fmac_f32_e32 v28, v32, v28
	v_div_scale_f32 v23, s[2:3], 1.0, v15, 1.0
	v_fma_f32 v34, -v24, v30, 1.0
	v_fmac_f32_e32 v29, v33, v29
	v_mul_f32_e32 v32, v19, v28
	v_div_scale_f32 v25, s[4:5], 1.0, v16, 1.0
	v_fma_f32 v35, -v26, v31, 1.0
	v_fmac_f32_e32 v30, v34, v30
	v_mul_f32_e32 v33, v23, v29
; __device__ __forceinline__ unsigned cvt_pk_bf16(float lo, float hi) { unsigned r; asm volatile("v_cvt_pk_bf16_f32 %0, %1, %2" : "=v"(r) : "v"(lo), "v"(hi)); return r; }
; __device__ __forceinline__ float sigmoidf_(float z) { return 1.0f / (1.0f + __expf(-z)); }
; #define PG8_WAIT_V(n) asm volatile("s_waitcnt vmcnt(" #n ")" ::: "memory")
; #define PG8_BAR __builtin_amdgcn_s_barrier()
;     __device__ __forceinline__ void operator()(const f32x4 (&acc)[2][2][4][2], const Unit& u, int wr, int wc, int fr, int fq) const {
;     ...
;             for (int m = 0; m < 4; ++m) { const size_t ro = (size_t)(row0 + ai * HALF + m * 16) * 4096 + col0;
; #pragma unroll
;                 for (int bj = 0; bj < 2; ++bj)
; #pragma unroll
;                     for (int n = 0; n < 2; ++n) { const u32x2 gw = *(const u32x2*)(G + ro + bj * HALF + n * 16); f32x4 v = acc[ai][bj][m][n];
;                         const float g0 = __uint_as_float(gw.x << 16), g1 = __uint_as_float(gw.x & 0xffff0000u), g2 = __uint_as_float(gw.y << 16), g3 = __uint_as_float(gw.y & 0xffff0000u);
;                         v[0] *= g0 * sigmoidf_(g0); v[1] *= g1 * sigmoidf_(g1); v[2] *= g2 * sigmoidf_(g2); v[3] *= g3 * sigmoidf_(g3);
;                         u32x2 w; w.x = cvt_pk_bf16(v[0], v[1]); w.y = cvt_pk_bf16(v[2], v[3]); *(u32x2*)(YC + ro + bj * HALF + n * 16) = w; } }
; template <class Epi, class Sched, bool ALIGN_EPI = false, bool SP2 = false>
; __device__ __forceinline__ void gemm_phase(PG8_LAS unsigned char* lds, const Gemm g, const Sched& S, const Epi& E, int tid_in) {
;     ...
;     PG8_WAIT_V(0);
;     if constexpr (!ALIGN_EPI) { if (wr == 0) PG8_BAR; }
;     PG8_BAR;
	v_fma_f32 v36, -v18, v32, v19
	v_div_scale_f32 v27, s[6:7], 1.0, v17, 1.0
	v_fmac_f32_e32 v31, v35, v31
	v_mul_f32_e32 v34, v25, v30
	v_fma_f32 v37, -v22, v33, v23
	v_fmac_f32_e32 v32, v36, v28
	v_mul_f32_e32 v35, v27, v31
	v_fma_f32 v38, -v24, v34, v25
	v_fmac_f32_e32 v33, v37, v29
	v_fma_f32 v18, -v18, v32, v19
	v_fma_f32 v39, -v26, v35, v27
	v_fmac_f32_e32 v34, v38, v30
	v_fma_f32 v19, -v22, v33, v23
	v_div_fmas_f32 v18, v18, v28, v32
	s_mov_b64 vcc, s[2:3]
	v_fmac_f32_e32 v35, v39, v31
	v_fma_f32 v22, -v24, v34, v25
	v_div_fixup_f32 v14, v18, v14, 1.0
	v_div_fmas_f32 v18, v19, v29, v33
	s_mov_b64 vcc, s[4:5]
	v_fma_f32 v23, -v26, v35, v27
	v_mul_f32_e32 v8, v14, v8
	v_div_fixup_f32 v14, v18, v15, 1.0
	v_div_fmas_f32 v15, v22, v30, v34
	s_mov_b64 vcc, s[6:7]
	v_mul_f32_e32 v4, v4, v8
	v_mul_f32_e32 v8, v14, v9
	v_div_fixup_f32 v9, v15, v16, 1.0
	v_div_fmas_f32 v14, v23, v31, v35
	v_mul_f32_e32 v5, v5, v8
	v_mul_f32_e32 v8, v9, v10
	v_div_fixup_f32 v9, v14, v17, 1.0
	v_mul_f32_e32 v6, v6, v8
	v_mul_f32_e32 v8, v9, v11
	v_cvt_pk_bf16_f32 v4, v4, v5
	v_mul_f32_e32 v5, v7, v8
	v_cvt_pk_bf16_f32 v5, v6, v5
	v_mov_b64_e32 v[6:7], v[224:225]
	s_nop 0
	flat_store_dwordx2 v[12:13], v[4:5] offset:256
	v_lshlrev_b32_e32 v4, 16, v6
	v_and_b32_e32 v5, 0xffff0000, v6
	v_mul_f32_e32 v8, 0xbfb8aa3b, v4
	v_lshlrev_b32_e32 v6, 16, v7
	v_mul_f32_e32 v9, 0xbfb8aa3b, v5
	v_exp_f32_e32 v8, v8
	v_and_b32_e32 v7, 0xffff0000, v7
	v_mul_f32_e32 v10, 0xbfb8aa3b, v6
	v_exp_f32_e32 v9, v9
	v_mul_f32_e32 v11, 0xbfb8aa3b, v7
	v_exp_f32_e32 v10, v10
	v_exp_f32_e32 v11, v11
	v_add_f32_e32 v8, 1.0, v8
	v_add_f32_e32 v9, 1.0, v9
	v_div_scale_f32 v14, s[0:1], v8, v8, 1.0
	v_add_f32_e32 v10, 1.0, v10
	v_div_scale_f32 v16, s[0:1], v9, v9, 1.0
	v_rcp_f32_e32 v22, v14
	v_add_f32_e32 v11, 1.0, v11
	v_div_scale_f32 v18, s[0:1], v10, v10, 1.0
	v_rcp_f32_e32 v23, v16
	v_div_scale_f32 v20, s[0:1], v11, v11, 1.0
	v_rcp_f32_e32 v24, v18
	v_rcp_f32_e32 v25, v20
	v_fma_f32 v26, -v14, v22, 1.0
	v_div_scale_f32 v15, vcc, 1.0, v8, 1.0
	v_fma_f32 v27, -v16, v23, 1.0
	v_fmac_f32_e32 v22, v26, v22
	v_div_scale_f32 v17, s[2:3], 1.0, v9, 1.0
	v_fma_f32 v28, -v18, v24, 1.0
	v_fmac_f32_e32 v23, v27, v23
	v_mul_f32_e32 v26, v15, v22
	v_div_scale_f32 v19, s[4:5], 1.0, v10, 1.0
	v_fma_f32 v29, -v20, v25, 1.0
	v_fmac_f32_e32 v24, v28, v24
	v_mul_f32_e32 v27, v17, v23
	v_fma_f32 v30, -v14, v26, v15
	v_div_scale_f32 v21, s[6:7], 1.0, v11, 1.0
	v_fmac_f32_e32 v25, v29, v25
	v_mul_f32_e32 v28, v19, v24
	v_fma_f32 v31, -v16, v27, v17
	v_fmac_f32_e32 v26, v30, v22
	v_mul_f32_e32 v29, v21, v25
	v_fma_f32 v32, -v18, v28, v19
	v_fmac_f32_e32 v27, v31, v23
	v_fma_f32 v14, -v14, v26, v15
	v_fma_f32 v33, -v20, v29, v21
	v_fmac_f32_e32 v28, v32, v24
	v_fma_f32 v15, -v16, v27, v17
	v_div_fmas_f32 v14, v14, v22, v26
	s_mov_b64 vcc, s[2:3]
	v_fmac_f32_e32 v29, v33, v25
	v_fma_f32 v16, -v18, v28, v19
	v_div_fixup_f32 v8, v14, v8, 1.0
	v_div_fmas_f32 v14, v15, v23, v27
	s_mov_b64 vcc, s[4:5]
	v_fma_f32 v17, -v20, v29, v21
	v_mul_f32_e32 v4, v8, v4
	v_div_fixup_f32 v8, v14, v9, 1.0
	v_div_fmas_f32 v9, v16, v24, v28
	s_mov_b64 vcc, s[6:7]
	v_mul_f32_e32 v0, v0, v4
	v_mul_f32_e32 v4, v8, v5
	v_div_fixup_f32 v5, v9, v10, 1.0
	v_div_fmas_f32 v8, v17, v25, v29
	v_mul_f32_e32 v1, v1, v4
	v_mul_f32_e32 v4, v5, v6
	v_div_fixup_f32 v5, v8, v11, 1.0
	v_mul_f32_e32 v2, v2, v4
	v_mul_f32_e32 v4, v5, v7
	v_cvt_pk_bf16_f32 v0, v0, v1
	v_mul_f32_e32 v1, v3, v4
	v_cvt_pk_bf16_f32 v1, v2, v1
	flat_store_dwordx2 v[12:13], v[0:1] offset:288
	s_waitcnt vmcnt(0)
	s_cbranch_scc1 .LBB0_655
	s_barrier
	s_branch .LBB0_655
